# g2 forward substitution rewritten: multipliers via broadcast ds_read_b128 from LDS + pk_fma in 4-row blocks (replaces v_readlane per multiplier); plus barrier invalidate hoist
# speedup vs baseline: 1.0139x; 1.0002x over previous
.LBB0_955:
	v_ashrrev_i32_e32 v0, 10, v164
	v_bfe_u32 v1, v164, 5, 5
	v_lshlrev_b32_e32 v3, 11, v0
	v_mov_b32_e32 v176, v165
	v_bfe_u32 v4, v164, 1, 4
	v_lshl_or_b32 v5, v1, 6, v3
	v_lshlrev_b32_e32 v0, 9, v0
	v_lshlrev_b32_e32 v1, 4, v1
	v_or3_b32 v146, v1, v0, v4
	v_add_u32_e32 v0, v5, v176
	v_ashrrev_i32_e32 v1, 31, v0
	v_and_b32_e32 v2, 31, v164
	v_lshlrev_b64 v[0:1], 7, v[0:1]
	v_lshl_or_b32 v0, v2, 2, v0
	v_lshl_add_u64 v[2:3], s[80:81], 0, v[0:1]
	global_load_dword v6, v[2:3], off
	v_lshl_add_u64 v[2:3], s[62:63], 0, v[0:1]
	global_load_dword v153, v[2:3], off
	v_cmp_lt_i32_e32 vcc, v168, v169
	v_and_b32_e32 v177, 15, v176
	v_lshl_add_u64 v[0:1], s[64:65], 0, v[0:1]
	v_cndmask_b32_e32 v2, v168, v167, vcc
	v_lshlrev_b32_e32 v2, 2, v2
	v_cmp_gt_i32_e32 vcc, 1, v176
	v_ashrrev_i32_e32 v130, 4, v176
	v_lshlrev_b32_e32 v144, 8, v4
	v_or_b32_e32 v4, v169, v177
	v_lshlrev_b32_e32 v4, 2, v4
	v_lshl_add_u32 v16, v177, 2, v166
	v_or_b32_e32 v178, 16, v177
	v_or_b32_e32 v179, 32, v177
	v_writelane_b32 v247, s0, 21
	v_or_b32_e32 v180, 48, v177
	v_lshl_add_u32 v67, v130, 10, v16
	v_writelane_b32 v247, s1, 22
	s_mov_b64 s[42:43], s[80:81]
	s_mov_b64 s[40:41], s[82:83]
	s_mov_b64 s[38:39], s[84:85]
	s_mov_b64 s[36:37], s[86:87]
	v_lshlrev_b32_e32 v148, 3, v130
	v_ashrrev_i32_e32 v149, 31, v148
	v_lshlrev_b64 v[150:151], 1, v[148:149]
	v_lshl_add_u32 v131, v176, 2, v166
	v_lshlrev_b32_e32 v175, 8, v177
	v_add_u32_e32 v149, 35, v148
	v_ashrrev_i32_e32 v147, 31, v146
	s_waitcnt vmcnt(1)
	ds_bpermute_b32 v2, v2, v6
	s_waitcnt lgkmcnt(0)
	v_add_f32_e32 v2, v6, v2
	v_cndmask_b32_e32 v2, v2, v6, vcc
	v_cmp_lt_i32_e32 vcc, v170, v169
	s_nop 1
	v_cndmask_b32_e32 v3, v170, v167, vcc
	v_lshlrev_b32_e32 v3, 2, v3
	ds_bpermute_b32 v3, v3, v2
	v_cmp_gt_i32_e32 vcc, 2, v176
	s_waitcnt lgkmcnt(0)
	v_add_f32_e32 v3, v2, v3
	v_cndmask_b32_e32 v2, v3, v2, vcc
	v_cmp_lt_i32_e32 vcc, v171, v169
	s_nop 1
	v_cndmask_b32_e32 v3, v171, v167, vcc
	v_lshlrev_b32_e32 v3, 2, v3
	ds_bpermute_b32 v3, v3, v2
	v_cmp_gt_i32_e32 vcc, 4, v176
	s_waitcnt lgkmcnt(0)
	v_add_f32_e32 v3, v2, v3
	v_cndmask_b32_e32 v2, v3, v2, vcc
	v_cmp_lt_i32_e32 vcc, v172, v169
	s_nop 1
	v_cndmask_b32_e32 v3, v172, v167, vcc
	v_lshlrev_b32_e32 v3, 2, v3
	ds_bpermute_b32 v3, v3, v2
	v_cmp_gt_i32_e32 vcc, 8, v176
	s_waitcnt lgkmcnt(0)
	v_add_f32_e32 v3, v2, v3
	v_cndmask_b32_e32 v2, v3, v2, vcc
	v_cmp_lt_i32_e32 vcc, v173, v169
	s_nop 1
	v_cndmask_b32_e32 v3, v173, v167, vcc
	v_lshlrev_b32_e32 v3, 2, v3
	ds_bpermute_b32 v3, v3, v2
	v_cmp_gt_i32_e32 vcc, 16, v176
	s_waitcnt lgkmcnt(0)
	v_add_f32_e32 v3, v2, v3
	v_cndmask_b32_e32 v2, v3, v2, vcc
	v_cmp_lt_i32_e32 vcc, v174, v169
	s_nop 1
	v_cndmask_b32_e32 v3, v174, v167, vcc
	v_lshlrev_b32_e32 v3, 2, v3
	ds_bpermute_b32 v3, v3, v2
	v_cmp_gt_i32_e32 vcc, 32, v176
	s_waitcnt lgkmcnt(0)
	v_add_f32_e32 v3, v2, v3
	v_cndmask_b32_e32 v157, v3, v2, vcc
	global_store_dword v[0:1], v157, off
	v_or_b32_e32 v0, v5, v177
	v_ashrrev_i32_e32 v1, 31, v0
	v_lshlrev_b64 v[2:3], 12, v[0:1]
	v_lshl_add_u64 v[0:1], s[84:85], 0, v[2:3]
	v_lshl_add_u64 v[2:3], s[82:83], 0, v[2:3]
	v_lshl_add_u64 v[64:65], v[2:3], 0, v[144:145]
	v_lshlrev_b32_e32 v2, 2, v130
	v_and_or_b32 v3, v2, 60, v169
	v_lshlrev_b32_e32 v3, 2, v3
	ds_bpermute_b32 v11, v4, v157
	ds_bpermute_b32 v4, v3, v157
	s_waitcnt vmcnt(1)
	ds_bpermute_b32 v66, v3, v153
	v_or_b32_e32 v12, 3, v2
	v_cmp_gt_i32_e64 s[56:57], v2, v178
	v_cmp_lt_i32_e64 s[58:59], v2, v178
	s_waitcnt lgkmcnt(1)
	v_sub_f32_e32 v3, v4, v11
	v_mul_f32_e32 v3, 0x3fb8aa3b, v3
	v_exp_f32_e32 v68, v3
	v_or_b32_e32 v3, 1, v2
	v_and_or_b32 v5, v3, 61, v169
	v_lshlrev_b32_e32 v6, 2, v5
	ds_bpermute_b32 v5, v6, v157
	ds_bpermute_b32 v69, v6, v153
	v_lshl_add_u32 v70, v3, 8, v16
	v_or_b32_e32 v3, 2, v2
	s_waitcnt lgkmcnt(2)
	v_mul_f32_e32 v13, 0, v66
	s_waitcnt lgkmcnt(1)
	v_sub_f32_e32 v6, v5, v11
	v_mul_f32_e32 v6, 0x3fb8aa3b, v6
	v_exp_f32_e32 v71, v6
	v_and_or_b32 v6, v3, 62, v169
	v_lshlrev_b32_e32 v7, 2, v6
	ds_bpermute_b32 v6, v7, v157
	ds_bpermute_b32 v72, v7, v153
	s_waitcnt lgkmcnt(2)
	v_mul_f32_e32 v14, 0, v69
	v_cmp_gt_i32_e64 s[60:61], v3, v178
	v_cmp_gt_i32_e64 s[62:63], v12, v178
	s_waitcnt lgkmcnt(1)
	v_sub_f32_e32 v7, v6, v11
	v_mul_f32_e32 v7, 0x3fb8aa3b, v7
	v_exp_f32_e32 v74, v7
	v_and_or_b32 v7, v12, 63, v169
	v_lshlrev_b32_e32 v8, 2, v7
	ds_bpermute_b32 v7, v8, v157
	ds_bpermute_b32 v75, v8, v153
	s_waitcnt lgkmcnt(2)
	v_mul_f32_e32 v15, 0, v72
	v_cmp_gt_i32_e64 s[0:1], v2, v179
	v_cmp_gt_i32_e64 s[72:73], v3, v177
	s_waitcnt lgkmcnt(1)
	v_sub_f32_e32 v8, v7, v11
	v_mul_f32_e32 v8, 0x3fb8aa3b, v8
	v_exp_f32_e32 v77, v8
	v_or_b32_e32 v8, v169, v178
	v_lshlrev_b32_e32 v8, 2, v8
	ds_bpermute_b32 v10, v8, v157
	s_waitcnt lgkmcnt(1)
	v_mul_f32_e32 v17, 0, v75
	v_writelane_b32 v247, s0, 23
	v_lshl_add_u32 v73, v3, 8, v16
	v_lshl_add_u32 v76, v12, 8, v16
	s_waitcnt lgkmcnt(0)
	v_sub_f32_e32 v8, v4, v10
	v_mul_f32_e32 v8, 0x3fb8aa3b, v8
	v_exp_f32_e32 v8, v8
	v_writelane_b32 v247, s1, 24
	v_cmp_gt_i32_e64 s[74:75], v12, v177
	v_lshl_add_u64 v[0:1], v[0:1], 0, v[144:145]
	v_mul_f32_e64 v8, v13, -v8
	v_cndmask_b32_e64 v78, 0, v8, s[56:57]
	v_sub_f32_e32 v8, v5, v10
	v_mul_f32_e32 v8, 0x3fb8aa3b, v8
	v_exp_f32_e32 v8, v8
	v_lshlrev_b32_e32 v144, 7, v177
	v_cmp_gt_i32_e64 s[44:45], v2, v177
	v_cmp_lt_i32_e64 s[70:71], v2, v177
	v_mul_f32_e64 v8, v14, -v8
	v_cndmask_b32_e64 v79, v8, 0, s[58:59]
	v_sub_f32_e32 v8, v6, v10
	v_mul_f32_e32 v8, 0x3fb8aa3b, v8
	v_exp_f32_e32 v8, v8
	v_lshl_add_u64 v[0:1], v[0:1], 0, v[150:151]
	v_mul_f32_e64 v8, v15, -v8
	v_cndmask_b32_e64 v82, 0, v8, s[60:61]
	v_sub_f32_e32 v8, v7, v10
	v_mul_f32_e32 v8, 0x3fb8aa3b, v8
	v_exp_f32_e32 v8, v8
	s_nop 0
	v_mul_f32_e64 v8, v17, -v8
	v_cndmask_b32_e64 v83, 0, v8, s[62:63]
	v_or_b32_e32 v8, v169, v179
	v_lshlrev_b32_e32 v8, 2, v8
	ds_bpermute_b32 v9, v8, v157
	s_waitcnt lgkmcnt(0)
	v_sub_f32_e32 v8, v4, v9
	v_mul_f32_e32 v8, 0x3fb8aa3b, v8
	v_exp_f32_e32 v8, v8
	s_nop 0
	v_mul_f32_e64 v8, v13, -v8
	v_cndmask_b32_e64 v18, 0, v8, s[0:1]
	v_sub_f32_e32 v8, v5, v9
	v_mul_f32_e32 v8, 0x3fb8aa3b, v8
	v_exp_f32_e32 v8, v8
	v_cmp_lt_i32_e64 s[0:1], v2, v179
	v_mul_f32_e64 v8, v14, -v8
	s_nop 0
	v_writelane_b32 v247, s0, 25
	s_nop 1
	v_cndmask_b32_e64 v19, v8, 0, s[0:1]
	v_sub_f32_e32 v8, v6, v9
	v_mul_f32_e32 v8, 0x3fb8aa3b, v8
	v_exp_f32_e32 v8, v8
	v_writelane_b32 v247, s1, 26
	v_cmp_gt_i32_e64 s[0:1], v3, v179
	v_mul_f32_e64 v8, v15, -v8
	s_nop 0
	v_writelane_b32 v247, s0, 27
	s_nop 1
	v_cndmask_b32_e64 v20, 0, v8, s[0:1]
	v_sub_f32_e32 v8, v7, v9
	v_mul_f32_e32 v8, 0x3fb8aa3b, v8
	v_exp_f32_e32 v8, v8
	v_writelane_b32 v247, s1, 28
	v_cmp_gt_i32_e64 s[0:1], v12, v179
	v_mul_f32_e64 v8, v17, -v8
	s_nop 0
	v_writelane_b32 v247, s0, 29
	s_nop 1
	v_cndmask_b32_e64 v21, 0, v8, s[0:1]
	v_or_b32_e32 v8, v169, v180
	v_lshlrev_b32_e32 v8, 2, v8
	ds_bpermute_b32 v8, v8, v157
	v_writelane_b32 v247, s1, 30
	v_cmp_gt_i32_e64 s[0:1], v2, v180
	s_waitcnt lgkmcnt(0)
	v_sub_f32_e32 v22, v4, v8
	v_mul_f32_e32 v22, 0x3fb8aa3b, v22
	v_exp_f32_e32 v22, v22
	v_writelane_b32 v247, s0, 31
	v_mul_f32_e64 v13, v13, -v22
	s_nop 0
	v_cndmask_b32_e64 v13, 0, v13, s[0:1]
	ds_write2_b32 v67, v18, v13 offset0:32 offset1:48
	v_sub_f32_e32 v13, v5, v8
	v_mul_f32_e32 v13, 0x3fb8aa3b, v13
	v_exp_f32_e32 v13, v13
	v_writelane_b32 v247, s1, 32
	v_cmp_lt_i32_e64 s[0:1], v2, v180
	v_add_u32_e32 v18, 18, v2
	v_mul_f32_e64 v13, v14, -v13
	v_writelane_b32 v247, s0, 33
	v_lshl_add_u32 v139, v18, 8, v16
	v_cmp_gt_i32_e64 s[80:81], v18, v177
	v_writelane_b32 v247, s1, 34
	v_cndmask_b32_e64 v13, v13, 0, s[0:1]
	v_cmp_gt_i32_e64 s[0:1], v3, v180
	v_sub_f32_e32 v3, v6, v8
	v_mul_f32_e32 v3, 0x3fb8aa3b, v3
	v_exp_f32_e32 v3, v3
	v_writelane_b32 v247, s0, 35
	ds_write2_b32 v70, v19, v13 offset0:32 offset1:48
	v_add_u32_e32 v19, 19, v2
	v_mul_f32_e64 v3, v15, -v3
	v_cndmask_b32_e64 v3, 0, v3, s[0:1]
	ds_write2_b32 v73, v20, v3 offset0:32 offset1:48
	v_sub_f32_e32 v3, v7, v8
	v_mul_f32_e32 v3, 0x3fb8aa3b, v3
	v_exp_f32_e32 v3, v3
	v_writelane_b32 v247, s1, 36
	v_cmp_gt_i32_e64 s[0:1], v12, v180
	v_cmp_gt_i32_e64 s[48:49], v19, v179
	v_mul_f32_e64 v3, v17, -v3
	v_writelane_b32 v247, s0, 37
	v_add_u32_e32 v17, 17, v2
	v_lshl_add_u32 v137, v17, 8, v16
	v_cndmask_b32_e64 v3, 0, v3, s[0:1]
	ds_write2_b32 v76, v21, v3 offset0:32 offset1:48
	v_add_u32_e32 v3, 16, v2
	v_and_or_b32 v12, v3, 60, v169
	v_lshlrev_b32_e32 v13, 2, v12
	ds_bpermute_b32 v12, v13, v157
	ds_bpermute_b32 v96, v13, v153
	v_writelane_b32 v247, s1, 38
	v_cmp_gt_i32_e64 s[0:1], v3, v179
	v_cmp_gt_i32_e64 s[76:77], v3, v177
	s_waitcnt lgkmcnt(1)
	v_sub_f32_e32 v13, v12, v11
	v_mul_f32_e32 v13, 0x3fb8aa3b, v13
	v_exp_f32_e32 v154, v13
	v_and_or_b32 v13, v17, 61, v169
	v_lshlrev_b32_e32 v14, 2, v13
	ds_bpermute_b32 v13, v14, v157
	ds_bpermute_b32 v136, v14, v153
	v_sub_f32_e32 v21, v12, v9
	v_mul_f32_e32 v21, 0x3fb8aa3b, v21
	v_exp_f32_e32 v21, v21
	s_waitcnt lgkmcnt(1)
	v_sub_f32_e32 v14, v13, v11
	v_mul_f32_e32 v14, 0x3fb8aa3b, v14
	v_exp_f32_e32 v156, v14
	v_and_or_b32 v14, v18, 62, v169
	v_lshlrev_b32_e32 v15, 2, v14
	ds_bpermute_b32 v14, v15, v157
	ds_bpermute_b32 v138, v15, v153
	v_sub_f32_e32 v23, v13, v9
	v_mul_f32_e32 v23, 0x3fb8aa3b, v23
	v_exp_f32_e32 v23, v23
	s_waitcnt lgkmcnt(1)
	v_sub_f32_e32 v15, v14, v11
	v_mul_f32_e32 v15, 0x3fb8aa3b, v15
	v_exp_f32_e32 v158, v15
	v_and_or_b32 v15, v19, 63, v169
	v_lshlrev_b32_e32 v20, 2, v15
	ds_bpermute_b32 v15, v20, v157
	ds_bpermute_b32 v152, v20, v153
	v_sub_f32_e32 v25, v14, v9
	v_mul_f32_e32 v25, 0x3fb8aa3b, v25
	v_writelane_b32 v247, s0, 39
	s_waitcnt lgkmcnt(1)
	v_sub_f32_e32 v20, v15, v11
	v_mul_f32_e32 v20, 0x3fb8aa3b, v20
	v_exp_f32_e32 v163, v20
	v_sub_f32_e32 v20, v12, v10
	v_mul_f32_e32 v20, 0x3fb8aa3b, v20
	v_exp_f32_e32 v159, v20
	v_sub_f32_e32 v20, v13, v10
	v_mul_f32_e32 v20, 0x3fb8aa3b, v20
	v_exp_f32_e32 v160, v20
	v_sub_f32_e32 v20, v14, v10
	v_mul_f32_e32 v20, 0x3fb8aa3b, v20
	v_exp_f32_e32 v161, v20
	v_sub_f32_e32 v20, v15, v10
	v_mul_f32_e32 v20, 0x3fb8aa3b, v20
	v_exp_f32_e32 v162, v20
	v_mul_f32_e32 v20, 0, v96
	v_mul_f32_e64 v21, v20, -v21
	v_exp_f32_e32 v25, v25
	v_writelane_b32 v247, s1, 40
	v_cndmask_b32_e64 v21, 0, v21, s[0:1]
	v_cmp_gt_i32_e64 s[0:1], v17, v179
	v_mul_f32_e32 v22, 0, v136
	v_mul_f32_e64 v23, v22, -v23
	v_writelane_b32 v247, s0, 41
	v_mul_f32_e32 v24, 0, v138
	v_mul_f32_e64 v25, v24, -v25
	v_writelane_b32 v247, s1, 42
	v_cndmask_b32_e64 v23, 0, v23, s[0:1]
	v_cmp_gt_i32_e64 s[0:1], v18, v179
	v_lshl_add_u32 v97, v3, 8, v16
	v_sub_f32_e32 v27, v15, v9
	v_writelane_b32 v247, s0, 43
	v_mul_f32_e32 v27, 0x3fb8aa3b, v27
	v_exp_f32_e32 v27, v27
	v_writelane_b32 v247, s1, 44
	v_cndmask_b32_e64 v25, 0, v25, s[0:1]
	v_cmp_gt_i32_e64 s[0:1], v3, v180
	v_sub_f32_e32 v3, v12, v8
	v_mul_f32_e32 v3, 0x3fb8aa3b, v3
	v_exp_f32_e32 v3, v3
	v_writelane_b32 v247, s0, 45
	s_waitcnt lgkmcnt(0)
	v_mul_f32_e32 v26, 0, v152
	v_mul_f32_e64 v27, v26, -v27
	v_mul_f32_e64 v3, v20, -v3
	v_cndmask_b32_e64 v3, 0, v3, s[0:1]
	ds_write2_b32 v97, v21, v3 offset0:32 offset1:48
	v_sub_f32_e32 v3, v13, v8
	v_mul_f32_e32 v3, 0x3fb8aa3b, v3
	v_exp_f32_e32 v3, v3
	v_writelane_b32 v247, s1, 46
	v_cmp_gt_i32_e64 s[0:1], v17, v180
	v_lshl_add_u32 v155, v19, 8, v16
	v_mul_f32_e64 v3, v22, -v3
	v_writelane_b32 v247, s0, 47
	v_cndmask_b32_e64 v27, 0, v27, s[48:49]
	v_cmp_gt_i32_e64 s[78:79], v17, v177
	v_cndmask_b32_e64 v3, 0, v3, s[0:1]
	ds_write2_b32 v137, v23, v3 offset0:32 offset1:48
	v_sub_f32_e32 v3, v14, v8
	v_mul_f32_e32 v3, 0x3fb8aa3b, v3
	v_exp_f32_e32 v3, v3
	v_writelane_b32 v247, s1, 48
	v_cmp_gt_i32_e64 s[0:1], v18, v180
	v_cmp_gt_i32_e64 s[64:65], v17, v178
	v_mul_f32_e64 v3, v24, -v3
	v_writelane_b32 v247, s0, 49
	v_cmp_gt_i32_e64 s[66:67], v18, v178
	v_cmp_gt_i32_e64 s[82:83], v19, v177
	v_cndmask_b32_e64 v3, 0, v3, s[0:1]
	ds_write2_b32 v139, v25, v3 offset0:32 offset1:48
	v_sub_f32_e32 v3, v15, v8
	v_mul_f32_e32 v3, 0x3fb8aa3b, v3
	v_exp_f32_e32 v3, v3
	v_writelane_b32 v247, s1, 50
	v_cmp_gt_i32_e64 s[0:1], v19, v180
	v_cmp_gt_i32_e64 s[68:69], v19, v178
	v_mul_f32_e64 v3, v26, -v3
	v_writelane_b32 v247, s0, 51
	s_nop 1
	v_cndmask_b32_e64 v3, 0, v3, s[0:1]
	ds_write2_b32 v155, v27, v3 offset0:32 offset1:48
	v_add_u32_e32 v3, 32, v2
	v_and_or_b32 v17, v3, 60, v169
	v_lshlrev_b32_e32 v17, 2, v17
	ds_bpermute_b32 v18, v17, v157
	ds_bpermute_b32 v181, v17, v153
	v_writelane_b32 v247, s1, 52
	v_cmp_gt_i32_e64 s[84:85], v3, v177
	v_lshl_add_u32 v182, v3, 8, v16
	s_waitcnt lgkmcnt(1)
	v_sub_f32_e32 v17, v18, v11
	v_mul_f32_e32 v17, 0x3fb8aa3b, v17
	v_exp_f32_e32 v190, v17
	v_add_u32_e32 v17, 33, v2
	v_and_or_b32 v19, v17, 61, v169
	v_lshlrev_b32_e32 v19, 2, v19
	ds_bpermute_b32 v20, v19, v157
	ds_bpermute_b32 v183, v19, v153
	v_cmp_gt_i32_e64 s[90:91], v3, v178
	v_cmp_gt_i32_e64 s[0:1], v3, v180
	s_waitcnt lgkmcnt(2)
	v_mul_f32_e32 v3, 0, v181
	s_waitcnt lgkmcnt(1)
	v_sub_f32_e32 v19, v20, v11
	v_mul_f32_e32 v19, 0x3fb8aa3b, v19
	v_exp_f32_e32 v194, v19
	v_add_u32_e32 v19, 34, v2
	v_and_or_b32 v21, v19, 62, v169
	v_lshlrev_b32_e32 v21, 2, v21
	ds_bpermute_b32 v22, v21, v157
	ds_bpermute_b32 v185, v21, v153
	v_writelane_b32 v247, s0, 53
	v_cmp_gt_i32_e64 s[86:87], v17, v177
	v_lshl_add_u32 v184, v17, 8, v16
	s_waitcnt lgkmcnt(1)
	v_sub_f32_e32 v21, v22, v11
	v_mul_f32_e32 v21, 0x3fb8aa3b, v21
	v_exp_f32_e32 v197, v21
	v_add_u32_e32 v21, 35, v2
	v_and_or_b32 v23, v21, 63, v169
	v_lshlrev_b32_e32 v23, 2, v23
	ds_bpermute_b32 v24, v23, v157
	ds_bpermute_b32 v187, v23, v153
	v_cmp_gt_i32_e64 s[92:93], v17, v178
	v_cmp_gt_i32_e64 s[50:51], v17, v179
	v_writelane_b32 v247, s1, 54
	s_waitcnt lgkmcnt(1)
	v_sub_f32_e32 v23, v24, v11
	v_mul_f32_e32 v23, 0x3fb8aa3b, v23
	v_exp_f32_e32 v210, v23
	v_sub_f32_e32 v23, v18, v10
	v_mul_f32_e32 v23, 0x3fb8aa3b, v23
	v_exp_f32_e32 v205, v23
	v_sub_f32_e32 v23, v20, v10
	v_mul_f32_e32 v23, 0x3fb8aa3b, v23
	v_exp_f32_e32 v206, v23
	v_sub_f32_e32 v23, v22, v10
	v_mul_f32_e32 v23, 0x3fb8aa3b, v23
	v_exp_f32_e32 v207, v23
	v_sub_f32_e32 v23, v24, v10
	v_mul_f32_e32 v23, 0x3fb8aa3b, v23
	v_exp_f32_e32 v208, v23
	v_sub_f32_e32 v23, v18, v9
	v_mul_f32_e32 v23, 0x3fb8aa3b, v23
	v_exp_f32_e32 v198, v23
	v_sub_f32_e32 v23, v20, v9
	v_mul_f32_e32 v23, 0x3fb8aa3b, v23
	v_exp_f32_e32 v199, v23
	v_sub_f32_e32 v23, v22, v9
	v_mul_f32_e32 v23, 0x3fb8aa3b, v23
	v_exp_f32_e32 v200, v23
	v_sub_f32_e32 v23, v24, v9
	v_mul_f32_e32 v23, 0x3fb8aa3b, v23
	v_exp_f32_e32 v201, v23
	v_sub_f32_e32 v23, v18, v8
	v_mul_f32_e32 v23, 0x3fb8aa3b, v23
	v_exp_f32_e32 v23, v23
	v_cmp_gt_i32_e64 s[88:89], v19, v177
	v_lshl_add_u32 v186, v19, 8, v16
	v_cmp_gt_i32_e64 s[94:95], v19, v178
	v_mul_f32_e64 v3, v3, -v23
	v_cndmask_b32_e64 v211, 0, v3, s[0:1]
	v_cmp_gt_i32_e64 s[0:1], v17, v180
	v_sub_f32_e32 v17, v20, v8
	v_mul_f32_e32 v17, 0x3fb8aa3b, v17
	v_exp_f32_e32 v17, v17
	v_mul_f32_e32 v3, 0, v183
	v_writelane_b32 v247, s0, 55
	v_cmp_gt_i32_e64 s[52:53], v19, v179
	v_mul_f32_e64 v3, v3, -v17
	v_sub_f32_e32 v17, v22, v8
	v_mul_f32_e32 v17, 0x3fb8aa3b, v17
	v_exp_f32_e32 v17, v17
	v_cndmask_b32_e64 v212, 0, v3, s[0:1]
	v_mul_f32_e32 v3, 0, v185
	v_writelane_b32 v247, s1, 56
	v_mul_f32_e64 v3, v3, -v17
	v_sub_f32_e32 v17, v24, v8
	v_mul_f32_e32 v17, 0x3fb8aa3b, v17
	v_exp_f32_e32 v17, v17
	v_cmp_gt_i32_e64 s[0:1], v19, v180
	v_cmp_gt_i32_e64 s[34:35], v21, v177
	v_lshl_add_u32 v188, v21, 8, v16
	v_writelane_b32 v247, s0, 57
	v_cmp_gt_i32_e64 s[96:97], v21, v178
	v_cmp_gt_i32_e64 s[54:55], v21, v179
	v_cndmask_b32_e64 v213, 0, v3, s[0:1]
	s_waitcnt lgkmcnt(0)
	v_mul_f32_e32 v3, 0, v187
	v_writelane_b32 v247, s1, 58
	v_cmp_gt_i32_e64 s[0:1], v21, v180
	v_mul_f32_e64 v3, v3, -v17
	global_load_dwordx4 v[48:51], v[0:1], off
	global_load_dwordx4 v[52:55], v[0:1], off offset:64
	global_load_dwordx4 v[56:59], v[0:1], off offset:128
	global_load_dwordx4 v[60:63], v[0:1], off offset:192
	v_writelane_b32 v247, s0, 59
	s_waitcnt vmcnt(3)
	v_mfma_f32_16x16x32_bf16 v[214:217], v[48:51], v[48:51], 0
	v_cndmask_b32_e64 v218, 0, v3, s[0:1]
	v_add_u32_e32 v3, 48, v2
	v_and_or_b32 v17, v3, 60, v169
	v_lshlrev_b32_e32 v17, 2, v17
	ds_bpermute_b32 v19, v17, v157
	ds_bpermute_b32 v189, v17, v153
	v_cmp_gt_i32_e64 s[26:27], v3, v177
	v_lshl_add_u32 v191, v3, 8, v16
	v_cmp_gt_i32_e64 s[6:7], v3, v178
	s_waitcnt lgkmcnt(1)
	v_sub_f32_e32 v17, v19, v11
	v_mul_f32_e32 v17, 0x3fb8aa3b, v17
	v_exp_f32_e32 v219, v17
	v_add_u32_e32 v17, 49, v2
	v_and_or_b32 v21, v17, 61, v169
	v_lshlrev_b32_e32 v21, 2, v21
	ds_bpermute_b32 v23, v21, v157
	ds_bpermute_b32 v192, v21, v153
	v_cmp_gt_i32_e64 s[20:21], v3, v179
	v_sub_f32_e32 v3, v19, v9
	v_mul_f32_e32 v3, 0x3fb8aa3b, v3
	s_waitcnt lgkmcnt(1)
	v_sub_f32_e32 v21, v23, v11
	v_mul_f32_e32 v21, 0x3fb8aa3b, v21
	v_exp_f32_e32 v220, v21
	v_add_u32_e32 v21, 50, v2
	v_and_or_b32 v25, v21, 62, v169
	v_lshlrev_b32_e32 v25, 2, v25
	ds_bpermute_b32 v26, v25, v157
	ds_bpermute_b32 v195, v25, v153
	v_exp_f32_e32 v227, v3
	v_sub_f32_e32 v3, v23, v9
	v_mul_f32_e32 v3, 0x3fb8aa3b, v3
	s_waitcnt lgkmcnt(1)
	v_sub_f32_e32 v25, v26, v11
	v_mul_f32_e32 v25, 0x3fb8aa3b, v25
	v_exp_f32_e32 v221, v25
	v_add_u32_e32 v25, 51, v2
	v_and_or_b32 v27, v25, 63, v169
	v_lshlrev_b32_e32 v27, 2, v27
	ds_bpermute_b32 v28, v27, v157
	v_exp_f32_e32 v228, v3
	v_sub_f32_e32 v3, v26, v9
	v_mul_f32_e32 v3, 0x3fb8aa3b, v3
	v_exp_f32_e32 v229, v3
	s_waitcnt lgkmcnt(0)
	v_sub_f32_e32 v3, v28, v9
	v_mul_f32_e32 v3, 0x3fb8aa3b, v3
	v_exp_f32_e32 v230, v3
	v_sub_f32_e32 v3, v19, v8
	v_mul_f32_e32 v3, 0x3fb8aa3b, v3
	v_exp_f32_e32 v231, v3
	v_sub_f32_e32 v3, v23, v8
	v_mul_f32_e32 v3, 0x3fb8aa3b, v3
	v_exp_f32_e32 v232, v3
	v_sub_f32_e32 v3, v26, v8
	v_mul_f32_e32 v3, 0x3fb8aa3b, v3
	v_exp_f32_e32 v233, v3
	v_sub_f32_e32 v3, v28, v8
	v_mul_f32_e32 v3, 0x3fb8aa3b, v3
	v_writelane_b32 v247, s1, 60
	v_exp_f32_e32 v234, v3
	v_ashrrev_i32_e32 v3, 31, v2
	v_lshl_add_u64 v[2:3], v[2:3], 1, v[144:145]
	v_readlane_b32 s28, v247, 61
	v_lshl_add_u64 v[2:3], v[140:141], 0, v[2:3]
	v_readlane_b32 s30, v247, 63
	v_readlane_b32 s31, v246, 0
	v_cmp_gt_i32_e64 s[24:25], v17, v177
	v_cmp_gt_i32_e64 s[8:9], v17, v178
	v_lshl_add_u64 v[84:85], s[30:31], 0, v[2:3]
	v_sub_f32_e32 v2, v11, v4
	v_mul_f32_e32 v2, 0x3fb8aa3b, v2
	v_exp_f32_e32 v235, v2
	v_sub_f32_e32 v2, v11, v5
	v_mul_f32_e32 v2, 0x3fb8aa3b, v2
	v_exp_f32_e32 v236, v2
	v_sub_f32_e32 v2, v11, v6
	v_mul_f32_e32 v2, 0x3fb8aa3b, v2
	v_exp_f32_e32 v237, v2
	v_sub_f32_e32 v2, v11, v7
	v_mul_f32_e32 v2, 0x3fb8aa3b, v2
	v_exp_f32_e32 v238, v2
	v_sub_f32_e32 v2, v11, v12
	v_sub_f32_e32 v3, v11, v13
	v_mul_f32_e32 v2, 0x3fb8aa3b, v2
	v_mul_f32_e32 v3, 0x3fb8aa3b, v3
	v_exp_f32_e32 v2, v2
	v_exp_f32_e32 v3, v3
	v_cmp_gt_i32_e64 s[18:19], v17, v179
	s_mov_b32 s28, 0x10000
	v_mul_f32_e32 v2, 0, v2
	v_mul_f32_e32 v3, 0, v3
	v_cndmask_b32_e64 v2, v2, 0, s[76:77]
	v_cndmask_b32_e64 v3, v3, 0, s[78:79]
	v_cvt_pk_bf16_f32 v86, v2, v3
	v_sub_f32_e32 v2, v11, v18
	v_sub_f32_e32 v3, v11, v20
	v_mul_f32_e32 v2, 0x3fb8aa3b, v2
	v_mul_f32_e32 v3, 0x3fb8aa3b, v3
	v_exp_f32_e32 v2, v2
	v_exp_f32_e32 v3, v3
	v_lshl_add_u32 v193, v17, 8, v16
	v_lshl_add_u32 v196, v21, 8, v16
	v_mul_f32_e32 v2, 0, v2
	v_mul_f32_e32 v3, 0, v3
	v_cndmask_b32_e64 v2, v2, 0, s[84:85]
	v_cndmask_b32_e64 v3, v3, 0, s[86:87]
	v_cvt_pk_bf16_f32 v88, v2, v3
	v_sub_f32_e32 v2, v11, v19
	v_sub_f32_e32 v3, v11, v23
	v_mul_f32_e32 v2, 0x3fb8aa3b, v2
	v_mul_f32_e32 v3, 0x3fb8aa3b, v3
	v_exp_f32_e32 v2, v2
	v_exp_f32_e32 v3, v3
	v_lshl_add_u32 v209, v25, 8, v16
	v_sub_f32_e32 v16, v19, v10
	v_mul_f32_e32 v2, 0, v2
	v_mul_f32_e32 v3, 0, v3
	v_cndmask_b32_e64 v2, v2, 0, s[26:27]
	v_cndmask_b32_e64 v3, v3, 0, s[24:25]
	v_cvt_pk_bf16_f32 v90, v2, v3
	v_sub_f32_e32 v2, v10, v4
	v_mul_f32_e32 v2, 0x3fb8aa3b, v2
	v_exp_f32_e32 v132, v2
	v_sub_f32_e32 v2, v10, v5
	v_mul_f32_e32 v2, 0x3fb8aa3b, v2
	v_exp_f32_e32 v133, v2
	v_sub_f32_e32 v2, v10, v6
	v_mul_f32_e32 v2, 0x3fb8aa3b, v2
	v_exp_f32_e32 v134, v2
	v_sub_f32_e32 v2, v10, v7
	v_mul_f32_e32 v2, 0x3fb8aa3b, v2
	v_exp_f32_e32 v135, v2
	v_sub_f32_e32 v2, v10, v12
	v_mul_f32_e32 v2, 0x3fb8aa3b, v2
	v_exp_f32_e32 v126, v2
	v_sub_f32_e32 v2, v10, v13
	v_mul_f32_e32 v2, 0x3fb8aa3b, v2
	v_exp_f32_e32 v128, v2
	v_sub_f32_e32 v2, v10, v14
	v_mul_f32_e32 v2, 0x3fb8aa3b, v2
	v_exp_f32_e32 v127, v2
	v_sub_f32_e32 v2, v10, v15
	v_mul_f32_e32 v2, 0x3fb8aa3b, v2
	v_exp_f32_e32 v129, v2
	v_sub_f32_e32 v2, v10, v18
	v_sub_f32_e32 v3, v10, v20
	v_mul_f32_e32 v2, 0x3fb8aa3b, v2
	v_mul_f32_e32 v3, 0x3fb8aa3b, v3
	v_exp_f32_e32 v2, v2
	v_exp_f32_e32 v3, v3
	v_mul_f32_e32 v16, 0x3fb8aa3b, v16
	v_exp_f32_e32 v223, v16
	v_mul_f32_e32 v2, 0, v2
	v_mul_f32_e32 v3, 0, v3
	v_cndmask_b32_e64 v2, v2, 0, s[90:91]
	v_cndmask_b32_e64 v3, v3, 0, s[92:93]
	v_cvt_pk_bf16_f32 v92, v2, v3
	v_sub_f32_e32 v2, v10, v19
	v_sub_f32_e32 v3, v10, v23
	v_mul_f32_e32 v2, 0x3fb8aa3b, v2
	v_mul_f32_e32 v3, 0x3fb8aa3b, v3
	v_exp_f32_e32 v2, v2
	v_exp_f32_e32 v3, v3
	v_sub_f32_e32 v16, v23, v10
	v_mul_f32_e32 v16, 0x3fb8aa3b, v16
	v_mul_f32_e32 v2, 0, v2
	v_mul_f32_e32 v3, 0, v3
	v_cndmask_b32_e64 v2, v2, 0, s[6:7]
	v_cndmask_b32_e64 v3, v3, 0, s[8:9]
	v_cvt_pk_bf16_f32 v94, v2, v3
	v_sub_f32_e32 v2, v9, v4
	v_mul_f32_e32 v2, 0x3fb8aa3b, v2
	v_exp_f32_e32 v125, v2
	v_sub_f32_e32 v2, v9, v5
	v_mul_f32_e32 v2, 0x3fb8aa3b, v2
	v_exp_f32_e32 v124, v2
	v_sub_f32_e32 v2, v9, v6
	v_mul_f32_e32 v2, 0x3fb8aa3b, v2
	v_exp_f32_e32 v123, v2
	v_sub_f32_e32 v2, v9, v7
	v_mul_f32_e32 v2, 0x3fb8aa3b, v2
	v_exp_f32_e32 v122, v2
	v_sub_f32_e32 v2, v9, v12
	v_mul_f32_e32 v2, 0x3fb8aa3b, v2
	v_exp_f32_e32 v121, v2
	v_sub_f32_e32 v2, v9, v13
	v_mul_f32_e32 v2, 0x3fb8aa3b, v2
	v_exp_f32_e32 v120, v2
	v_sub_f32_e32 v2, v9, v14
	v_mul_f32_e32 v2, 0x3fb8aa3b, v2
	v_exp_f32_e32 v119, v2
	v_sub_f32_e32 v2, v9, v15
	v_mul_f32_e32 v2, 0x3fb8aa3b, v2
	v_exp_f32_e32 v118, v2
	v_sub_f32_e32 v2, v9, v18
	v_mul_f32_e32 v2, 0x3fb8aa3b, v2
	v_exp_f32_e32 v114, v2
	v_sub_f32_e32 v2, v9, v20
	v_mul_f32_e32 v2, 0x3fb8aa3b, v2
	v_exp_f32_e32 v115, v2
	v_sub_f32_e32 v2, v9, v22
	v_mul_f32_e32 v2, 0x3fb8aa3b, v2
	v_exp_f32_e32 v116, v2
	v_sub_f32_e32 v2, v9, v24
	v_mul_f32_e32 v2, 0x3fb8aa3b, v2
	v_exp_f32_e32 v117, v2
	v_sub_f32_e32 v2, v9, v19
	v_sub_f32_e32 v3, v9, v23
	v_mul_f32_e32 v2, 0x3fb8aa3b, v2
	v_mul_f32_e32 v3, 0x3fb8aa3b, v3
	v_exp_f32_e32 v2, v2
	v_exp_f32_e32 v3, v3
	v_exp_f32_e32 v224, v16
	v_sub_f32_e32 v16, v26, v10
	v_mul_f32_e32 v2, 0, v2
	v_mul_f32_e32 v3, 0, v3
	v_cndmask_b32_e64 v2, v2, 0, s[20:21]
	v_cndmask_b32_e64 v3, v3, 0, s[18:19]
	v_cvt_pk_bf16_f32 v80, v2, v3
	v_sub_f32_e32 v2, v8, v4
	v_mul_f32_e32 v2, 0x3fb8aa3b, v2
	v_exp_f32_e32 v113, v2
	v_sub_f32_e32 v2, v8, v5
	v_mul_f32_e32 v2, 0x3fb8aa3b, v2
	v_exp_f32_e32 v112, v2
	v_sub_f32_e32 v2, v8, v6
	v_mul_f32_e32 v2, 0x3fb8aa3b, v2
	v_exp_f32_e32 v111, v2
	v_sub_f32_e32 v2, v8, v7
	v_mul_f32_e32 v2, 0x3fb8aa3b, v2
	v_exp_f32_e32 v110, v2
	v_sub_f32_e32 v2, v8, v12
	v_mul_f32_e32 v2, 0x3fb8aa3b, v2
	v_exp_f32_e32 v109, v2
	v_sub_f32_e32 v2, v8, v13
	v_mul_f32_e32 v2, 0x3fb8aa3b, v2
	v_exp_f32_e32 v108, v2
	v_sub_f32_e32 v2, v8, v14
	v_mul_f32_e32 v2, 0x3fb8aa3b, v2
	v_exp_f32_e32 v107, v2
	v_sub_f32_e32 v2, v8, v15
	v_mul_f32_e32 v2, 0x3fb8aa3b, v2
	v_exp_f32_e32 v106, v2
	v_sub_f32_e32 v2, v8, v18
	v_mul_f32_e32 v2, 0x3fb8aa3b, v2
	v_exp_f32_e32 v105, v2
	v_sub_f32_e32 v2, v8, v20
	v_mul_f32_e32 v2, 0x3fb8aa3b, v2
	v_exp_f32_e32 v104, v2
	v_sub_f32_e32 v2, v8, v22
	v_mul_f32_e32 v2, 0x3fb8aa3b, v2
	v_exp_f32_e32 v103, v2
	v_sub_f32_e32 v2, v8, v24
	v_mul_f32_e32 v2, 0x3fb8aa3b, v2
	v_exp_f32_e32 v102, v2
	v_sub_f32_e32 v2, v8, v19
	v_mul_f32_e32 v2, 0x3fb8aa3b, v2
	v_exp_f32_e32 v98, v2
	v_sub_f32_e32 v2, v8, v23
	v_mul_f32_e32 v2, 0x3fb8aa3b, v2
	v_exp_f32_e32 v99, v2
	v_sub_f32_e32 v2, v8, v26
	v_mul_f32_e32 v2, 0x3fb8aa3b, v2
	v_exp_f32_e32 v100, v2
	v_sub_f32_e32 v2, v8, v28
	v_mul_f32_e32 v2, 0x3fb8aa3b, v2
	v_exp_f32_e32 v101, v2
	v_add_co_u32_e32 v2, vcc, s28, v0
	v_mul_f32_e32 v16, 0x3fb8aa3b, v16
	s_nop 0
	v_addc_co_u32_e32 v3, vcc, 0, v1, vcc
	global_load_dwordx4 v[32:35], v[2:3], off
	global_load_dwordx4 v[36:39], v[2:3], off offset:64
	global_load_dwordx4 v[40:43], v[2:3], off offset:128
	global_load_dwordx4 v[44:47], v[2:3], off offset:192
	v_exp_f32_e32 v225, v16
	v_sub_f32_e32 v16, v28, v10
	v_mul_f32_e32 v16, 0x3fb8aa3b, v16
	v_exp_f32_e32 v226, v16
	v_cmp_gt_i32_e64 s[10:11], v17, v180
	v_sub_f32_e32 v16, v11, v14
	v_sub_f32_e32 v17, v11, v15
	v_mul_f32_e32 v16, 0x3fb8aa3b, v16
	v_mul_f32_e32 v17, 0x3fb8aa3b, v17
	v_exp_f32_e32 v16, v16
	v_exp_f32_e32 v17, v17
	ds_bpermute_b32 v204, v27, v153
	v_sub_f32_e32 v27, v28, v11
	v_mul_f32_e32 v16, 0, v16
	v_mul_f32_e32 v17, 0, v17
	v_cndmask_b32_e64 v16, v16, 0, s[80:81]
	v_cndmask_b32_e64 v17, v17, 0, s[82:83]
	v_cvt_pk_bf16_f32 v87, v16, v17
	v_sub_f32_e32 v16, v11, v22
	v_sub_f32_e32 v17, v11, v24
	v_mul_f32_e32 v16, 0x3fb8aa3b, v16
	v_mul_f32_e32 v17, 0x3fb8aa3b, v17
	v_exp_f32_e32 v16, v16
	v_exp_f32_e32 v17, v17
	v_cmp_gt_i32_e64 s[22:23], v21, v177
	v_cmp_gt_i32_e64 s[0:1], v25, v177
	v_mul_f32_e32 v16, 0, v16
	v_mul_f32_e32 v17, 0, v17
	v_cndmask_b32_e64 v16, v16, 0, s[88:89]
	v_cndmask_b32_e64 v17, v17, 0, s[34:35]
	v_cvt_pk_bf16_f32 v89, v16, v17
	v_sub_f32_e32 v16, v11, v26
	v_sub_f32_e32 v11, v11, v28
	v_mul_f32_e32 v16, 0x3fb8aa3b, v16
	v_mul_f32_e32 v11, 0x3fb8aa3b, v11
	v_exp_f32_e32 v16, v16
	v_exp_f32_e32 v11, v11
	v_readlane_b32 s29, v247, 62
	s_mov_b32 s29, 0x20000
	v_mul_f32_e32 v16, 0, v16
	v_mul_f32_e32 v11, 0, v11
	v_cndmask_b32_e64 v16, v16, 0, s[22:23]
	v_cndmask_b32_e64 v11, v11, 0, s[0:1]
	v_cvt_pk_bf16_f32 v91, v16, v11
	v_sub_f32_e32 v11, v10, v22
	v_sub_f32_e32 v16, v10, v24
	v_mul_f32_e32 v11, 0x3fb8aa3b, v11
	v_mul_f32_e32 v16, 0x3fb8aa3b, v16
	v_exp_f32_e32 v11, v11
	v_exp_f32_e32 v16, v16
	v_cmp_gt_i32_e64 s[2:3], v21, v178
	v_cmp_gt_i32_e64 s[4:5], v25, v178
	v_mul_f32_e32 v11, 0, v11
	v_mul_f32_e32 v16, 0, v16
	v_cndmask_b32_e64 v11, v11, 0, s[94:95]
	v_cndmask_b32_e64 v16, v16, 0, s[96:97]
	v_cvt_pk_bf16_f32 v93, v11, v16
	v_sub_f32_e32 v11, v10, v26
	v_sub_f32_e32 v10, v10, v28
	v_mul_f32_e32 v11, 0x3fb8aa3b, v11
	v_mul_f32_e32 v10, 0x3fb8aa3b, v10
	v_exp_f32_e32 v11, v11
	v_exp_f32_e32 v10, v10
	v_add_co_u32_e32 v2, vcc, s29, v0
	v_mul_f32_e32 v11, 0, v11
	v_mul_f32_e32 v10, 0, v10
	v_mul_f32_e32 v27, 0x3fb8aa3b, v27
	v_cndmask_b32_e64 v11, v11, 0, s[2:3]
	v_cndmask_b32_e64 v10, v10, 0, s[4:5]
	v_addc_co_u32_e32 v3, vcc, 0, v1, vcc
	v_exp_f32_e32 v222, v27
	v_cmp_gt_i32_e64 s[16:17], v21, v179
	v_cmp_gt_i32_e64 s[14:15], v25, v179
	v_cmp_gt_i32_e64 s[12:13], v21, v180
	v_cmp_gt_i32_e64 s[46:47], v25, v180
	v_cvt_pk_bf16_f32 v95, v11, v10
	v_sub_f32_e32 v10, v9, v26
	v_sub_f32_e32 v9, v9, v28
	global_load_dwordx4 v[16:19], v[2:3], off
	global_load_dwordx4 v[20:23], v[2:3], off offset:64
	global_load_dwordx4 v[24:27], v[2:3], off offset:128
	global_load_dwordx4 v[28:31], v[2:3], off offset:192
	s_waitcnt vmcnt(10)
	v_mfma_f32_16x16x32_bf16 v[214:217], v[52:55], v[52:55], v[214:217]
	v_mul_f32_e32 v10, 0x3fb8aa3b, v10
	v_mul_f32_e32 v9, 0x3fb8aa3b, v9
	v_exp_f32_e32 v10, v10
	s_waitcnt vmcnt(9)
	v_mfma_f32_16x16x32_bf16 v[214:217], v[56:59], v[56:59], v[214:217]
	v_exp_f32_e32 v9, v9
	s_mov_b32 s30, 0x30000
	v_mul_f32_e32 v10, 0, v10
	s_waitcnt vmcnt(8)
	v_mfma_f32_16x16x32_bf16 v[214:217], v[60:63], v[60:63], v[214:217]
	v_mul_f32_e32 v9, 0, v9
	v_add_co_u32_e32 v12, vcc, s30, v0
	v_cndmask_b32_e64 v10, v10, 0, s[16:17]
	v_cndmask_b32_e64 v9, v9, 0, s[14:15]
	s_nop 3
	v_mul_f32_e32 v66, v214, v66
	v_mul_f32_e64 v66, v66, -v68
	v_addc_co_u32_e32 v13, vcc, 0, v1, vcc
	v_cndmask_b32_e64 v66, 0, v66, s[44:45]
	v_cvt_pk_bf16_f32 v81, v10, v9
	global_load_dwordx4 v[0:3], v[12:13], off
	global_load_dwordx4 v[4:7], v[12:13], off offset:64
	global_load_dwordx4 v[8:11], v[12:13], off offset:128
	s_nop 0
	global_load_dwordx4 v[12:15], v[12:13], off offset:192
	ds_write2_b32 v67, v66, v78 offset1:16
	v_mul_f32_e32 v66, v215, v69
	v_mul_f32_e64 v66, v66, -v71
	v_cndmask_b32_e64 v66, v66, 0, s[70:71]
	ds_write2_b32 v70, v66, v79 offset1:16
	v_mul_f32_e32 v66, v216, v72
	v_mul_f32_e64 v66, v66, -v74
	v_cndmask_b32_e64 v66, 0, v66, s[72:73]
	ds_write2_b32 v73, v66, v82 offset1:16
	v_mul_f32_e32 v66, v217, v75
	v_mul_f32_e64 v66, v66, -v77
	v_cndmask_b32_e64 v66, 0, v66, s[74:75]
	ds_write2_b32 v76, v66, v83 offset1:16
	s_waitcnt vmcnt(11)
	v_mfma_f32_16x16x32_bf16 v[66:69], v[32:35], v[48:51], 0
	v_lshl_add_u64 v[82:83], v[64:65], 0, v[150:151]
	v_add_co_u32_e32 v76, vcc, s28, v82
	s_waitcnt vmcnt(10)
	v_mfma_f32_16x16x32_bf16 v[66:69], v[36:39], v[52:55], v[66:69]
	v_addc_co_u32_e32 v77, vcc, 0, v83, vcc
	s_waitcnt vmcnt(9)
	v_mfma_f32_16x16x32_bf16 v[66:69], v[40:43], v[56:59], v[66:69]
	s_waitcnt vmcnt(8)
	v_mfma_f32_16x16x32_bf16 v[66:69], v[44:47], v[60:63], v[66:69]
	s_nop 7
	v_mul_f32_e32 v66, v66, v96
	v_mul_f32_e64 v66, v66, -v154
	v_cndmask_b32_e64 v70, 0, v66, s[76:77]
	v_mul_f32_e32 v66, v67, v136
	v_mul_f32_e64 v66, v66, -v156
	v_cndmask_b32_e64 v71, 0, v66, s[78:79]
	v_mul_f32_e32 v66, v68, v138
	v_mul_f32_e64 v66, v66, -v158
	v_cndmask_b32_e64 v72, 0, v66, s[80:81]
	v_mul_f32_e32 v66, v69, v152
	v_mul_f32_e64 v66, v66, -v163
	v_cndmask_b32_e64 v73, 0, v66, s[82:83]
	v_mfma_f32_16x16x32_bf16 v[66:69], v[32:35], v[32:35], 0
	s_mov_b64 s[82:83], s[40:41]
	s_mov_b64 s[80:81], s[42:43]
	v_mfma_f32_16x16x32_bf16 v[66:69], v[36:39], v[36:39], v[66:69]
	v_mfma_f32_16x16x32_bf16 v[66:69], v[40:43], v[40:43], v[66:69]
	v_mfma_f32_16x16x32_bf16 v[66:69], v[44:47], v[44:47], v[66:69]
	s_nop 7
	v_mul_f32_e32 v66, v66, v96
	v_mul_f32_e64 v66, v66, -v159
	v_cndmask_b32_e64 v66, 0, v66, s[44:45]
	ds_write2_b32 v97, v70, v66 offset1:16
	v_mul_f32_e32 v66, v67, v136
	v_mul_f32_e64 v66, v66, -v160
	v_cndmask_b32_e64 v66, 0, v66, s[64:65]
	ds_write2_b32 v137, v71, v66 offset1:16
	v_mul_f32_e32 v66, v68, v138
	v_mul_f32_e64 v66, v66, -v161
	v_cndmask_b32_e64 v66, 0, v66, s[66:67]
	ds_write2_b32 v139, v72, v66 offset1:16
	v_mul_f32_e32 v66, v69, v152
	v_mul_f32_e64 v66, v66, -v162
	v_cndmask_b32_e64 v66, 0, v66, s[68:69]
	ds_write2_b32 v155, v73, v66 offset1:16
	s_waitcnt vmcnt(7)
	v_mfma_f32_16x16x32_bf16 v[66:69], v[16:19], v[48:51], 0
	s_waitcnt vmcnt(6)
	v_mfma_f32_16x16x32_bf16 v[66:69], v[20:23], v[52:55], v[66:69]
	s_waitcnt vmcnt(5)
	v_mfma_f32_16x16x32_bf16 v[66:69], v[24:27], v[56:59], v[66:69]
	s_waitcnt vmcnt(4)
	v_mfma_f32_16x16x32_bf16 v[66:69], v[28:31], v[60:63], v[66:69]
	s_nop 7
	v_mul_f32_e32 v66, v66, v181
	v_mul_f32_e64 v66, v66, -v190
	v_cndmask_b32_e64 v70, 0, v66, s[84:85]
	v_mul_f32_e32 v66, v67, v183
	v_mul_f32_e64 v66, v66, -v194
	v_cndmask_b32_e64 v71, 0, v66, s[86:87]
	v_mul_f32_e32 v66, v68, v185
	v_mul_f32_e64 v66, v66, -v197
	v_cndmask_b32_e64 v72, 0, v66, s[88:89]
	v_mul_f32_e32 v66, v69, v187
	v_mul_f32_e64 v66, v66, -v210
	v_cndmask_b32_e64 v73, 0, v66, s[34:35]
	v_mfma_f32_16x16x32_bf16 v[66:69], v[16:19], v[32:35], 0
	s_mov_b64 s[86:87], s[36:37]
	s_mov_b64 s[84:85], s[38:39]
	v_mfma_f32_16x16x32_bf16 v[66:69], v[20:23], v[36:39], v[66:69]
	v_mfma_f32_16x16x32_bf16 v[66:69], v[24:27], v[40:43], v[66:69]
	v_mfma_f32_16x16x32_bf16 v[66:69], v[28:31], v[44:47], v[66:69]
	s_nop 7
	v_mul_f32_e32 v66, v66, v181
	v_mul_f32_e64 v66, v66, -v205
	v_cndmask_b32_e64 v66, 0, v66, s[90:91]
	ds_write2_b32 v182, v70, v66 offset1:16
	v_mul_f32_e32 v66, v67, v183
	v_mul_f32_e64 v66, v66, -v206
	v_cndmask_b32_e64 v66, 0, v66, s[92:93]
	ds_write2_b32 v184, v71, v66 offset1:16
	v_mul_f32_e32 v66, v68, v185
	v_mul_f32_e64 v66, v66, -v207
	v_cndmask_b32_e64 v66, 0, v66, s[94:95]
	ds_write2_b32 v186, v72, v66 offset1:16
	v_mul_f32_e32 v66, v69, v187
	v_mul_f32_e64 v66, v66, -v208
	v_cndmask_b32_e64 v66, 0, v66, s[96:97]
	ds_write2_b32 v188, v73, v66 offset1:16
	v_mfma_f32_16x16x32_bf16 v[66:69], v[16:19], v[16:19], 0
	v_mfma_f32_16x16x32_bf16 v[66:69], v[20:23], v[20:23], v[66:69]
	v_mfma_f32_16x16x32_bf16 v[66:69], v[24:27], v[24:27], v[66:69]
	v_mfma_f32_16x16x32_bf16 v[66:69], v[28:31], v[28:31], v[66:69]
	s_nop 7
	v_mul_f32_e32 v66, v66, v181
	v_mul_f32_e64 v66, v66, -v198
	v_cndmask_b32_e64 v66, 0, v66, s[44:45]
	ds_write2_b32 v182, v66, v211 offset0:32 offset1:48
	v_mul_f32_e32 v66, v67, v183
	v_mul_f32_e64 v66, v66, -v199
	v_cndmask_b32_e64 v66, 0, v66, s[50:51]
	ds_write2_b32 v184, v66, v212 offset0:32 offset1:48
	v_mul_f32_e32 v66, v68, v185
	v_mul_f32_e64 v66, v66, -v200
	v_cndmask_b32_e64 v66, 0, v66, s[52:53]
	ds_write2_b32 v186, v66, v213 offset0:32 offset1:48
	v_mul_f32_e32 v66, v69, v187
	v_mul_f32_e64 v66, v66, -v201
	v_cndmask_b32_e64 v66, 0, v66, s[54:55]
	ds_write2_b32 v188, v66, v218 offset0:32 offset1:48
	s_waitcnt vmcnt(3)
	v_mfma_f32_16x16x32_bf16 v[66:69], v[0:3], v[48:51], 0
	s_waitcnt vmcnt(2)
	v_mfma_f32_16x16x32_bf16 v[66:69], v[4:7], v[52:55], v[66:69]
	s_waitcnt vmcnt(1)
	v_mfma_f32_16x16x32_bf16 v[66:69], v[8:11], v[56:59], v[66:69]
	s_waitcnt vmcnt(0)
	v_mfma_f32_16x16x32_bf16 v[66:69], v[12:15], v[60:63], v[66:69]
	s_nop 7
	v_mul_f32_e32 v66, v66, v189
	v_mul_f32_e64 v66, v66, -v219
	v_cndmask_b32_e64 v70, 0, v66, s[26:27]
	v_mul_f32_e32 v66, v67, v192
	v_mul_f32_e64 v66, v66, -v220
	v_cndmask_b32_e64 v71, 0, v66, s[24:25]
	v_mul_f32_e32 v66, v68, v195
	v_mul_f32_e64 v66, v66, -v221
	v_cndmask_b32_e64 v72, 0, v66, s[22:23]
	s_waitcnt lgkmcnt(14)
	v_mul_f32_e32 v66, v69, v204
	v_mul_f32_e64 v66, v66, -v222
	v_cndmask_b32_e64 v73, 0, v66, s[0:1]
	v_mfma_f32_16x16x32_bf16 v[66:69], v[0:3], v[32:35], 0
	s_mov_b32 s0, 0x37e80000
	v_mfma_f32_16x16x32_bf16 v[66:69], v[4:7], v[36:39], v[66:69]
	v_mfma_f32_16x16x32_bf16 v[66:69], v[8:11], v[40:43], v[66:69]
	v_mfma_f32_16x16x32_bf16 v[66:69], v[12:15], v[44:47], v[66:69]
	s_nop 7
	v_mul_f32_e32 v66, v66, v189
	v_mul_f32_e64 v66, v66, -v223
	v_cndmask_b32_e64 v66, 0, v66, s[6:7]
	ds_write2_b32 v191, v70, v66 offset1:16
	v_mul_f32_e32 v66, v67, v192
	v_mul_f32_e64 v66, v66, -v224
	v_cndmask_b32_e64 v66, 0, v66, s[8:9]
	ds_write2_b32 v193, v71, v66 offset1:16
	v_mul_f32_e32 v66, v68, v195
	v_mul_f32_e64 v66, v66, -v225
	v_cndmask_b32_e64 v66, 0, v66, s[2:3]
	ds_write2_b32 v196, v72, v66 offset1:16
	v_mul_f32_e32 v66, v69, v204
	v_mul_f32_e64 v66, v66, -v226
	v_cndmask_b32_e64 v66, 0, v66, s[4:5]
	ds_write2_b32 v209, v73, v66 offset1:16
	v_mfma_f32_16x16x32_bf16 v[66:69], v[0:3], v[16:19], 0
	v_mfma_f32_16x16x32_bf16 v[66:69], v[4:7], v[20:23], v[66:69]
	v_mfma_f32_16x16x32_bf16 v[66:69], v[8:11], v[24:27], v[66:69]
	v_mfma_f32_16x16x32_bf16 v[66:69], v[12:15], v[28:31], v[66:69]
	s_nop 7
	v_mul_f32_e32 v66, v66, v189
	v_mul_f32_e64 v66, v66, -v227
	v_cndmask_b32_e64 v70, 0, v66, s[20:21]
	v_mul_f32_e32 v66, v67, v192
	v_mul_f32_e64 v66, v66, -v228
	v_cndmask_b32_e64 v71, 0, v66, s[18:19]
	v_mul_f32_e32 v66, v68, v195
	v_mul_f32_e64 v66, v66, -v229
	v_cndmask_b32_e64 v72, 0, v66, s[16:17]
	v_mul_f32_e32 v66, v69, v204
	v_mul_f32_e64 v66, v66, -v230
	v_cndmask_b32_e64 v73, 0, v66, s[14:15]
	v_mfma_f32_16x16x32_bf16 v[66:69], v[0:3], v[0:3], 0
	v_mfma_f32_16x16x32_bf16 v[66:69], v[4:7], v[4:7], v[66:69]
	v_mfma_f32_16x16x32_bf16 v[66:69], v[8:11], v[8:11], v[66:69]
	v_mfma_f32_16x16x32_bf16 v[66:69], v[12:15], v[12:15], v[66:69]
	s_nop 7
	v_mul_f32_e32 v66, v66, v189
	v_mul_f32_e64 v66, v66, -v231
	v_cndmask_b32_e64 v66, 0, v66, s[44:45]
	ds_write2_b32 v191, v70, v66 offset0:32 offset1:48
	v_mul_f32_e32 v66, v67, v192
	v_mul_f32_e64 v66, v66, -v232
	v_cndmask_b32_e64 v66, 0, v66, s[10:11]
	ds_write2_b32 v193, v71, v66 offset0:32 offset1:48
	v_mul_f32_e32 v66, v68, v195
	v_mul_f32_e64 v66, v66, -v233
	v_cndmask_b32_e64 v66, 0, v66, s[12:13]
	ds_write2_b32 v196, v72, v66 offset0:32 offset1:48
	v_mul_f32_e32 v66, v69, v204
	v_mul_f32_e64 v66, v66, -v234
	v_cndmask_b32_e64 v66, 0, v66, s[46:47]
	ds_write2_b32 v209, v73, v66 offset0:32 offset1:48
	global_load_dwordx4 v[136:139], v[82:83], off
	global_load_dwordx4 v[158:161], v[82:83], off offset:64
	global_load_dwordx4 v[182:185], v[82:83], off offset:128
	global_load_dwordx4 v[186:189], v[82:83], off offset:192
	global_load_dwordx4 v[64:67], v[76:77], off
	global_load_dwordx4 v[68:71], v[76:77], off offset:64
	global_load_dwordx4 v[72:75], v[76:77], off offset:128
	s_nop 0
	global_load_dwordx4 v[76:79], v[76:77], off offset:192
	s_waitcnt vmcnt(7)
	v_mfma_f32_16x16x32_bf16 v[136:139], v[48:51], v[136:139], 0
	s_waitcnt vmcnt(6)
	v_mfma_f32_16x16x32_bf16 v[136:139], v[52:55], v[158:161], v[136:139]
	s_waitcnt vmcnt(5)
	v_mfma_f32_16x16x32_bf16 v[136:139], v[56:59], v[182:185], v[136:139]
	s_waitcnt vmcnt(4)
	v_mfma_f32_16x16x32_bf16 v[136:139], v[60:63], v[186:189], v[136:139]
	s_nop 7
	v_mul_f32_e32 v96, v235, v136
	v_mul_f32_e32 v97, v236, v137
	v_mul_f32_e32 v136, v237, v138
	v_mul_f32_e32 v137, v238, v139
	v_cndmask_b32_e64 v96, v96, 0, s[44:45]
	v_cndmask_b32_e64 v97, 0, v97, s[70:71]
	v_cndmask_b32_e64 v136, v136, 0, s[72:73]
	v_cndmask_b32_e64 v137, v137, 0, s[74:75]
	v_cvt_pk_bf16_f32 v96, v96, v97
	v_cvt_pk_bf16_f32 v97, v136, v137
	v_add_co_u32_e32 v136, vcc, s0, v84
	s_mov_b32 s0, 0x37e81000
	s_nop 0
	v_addc_co_u32_e32 v137, vcc, 0, v85, vcc
	v_add_co_u32_e32 v84, vcc, s0, v84
	v_readlane_b32 s0, v247, 23
	s_nop 0
	v_addc_co_u32_e32 v85, vcc, 0, v85, vcc
	global_store_dwordx2 v[84:85], v[96:97], off offset:-4096
	global_store_dwordx2 v[136:137], v[86:87], off offset:32
	global_store_dwordx2 v[136:137], v[88:89], off offset:64
	global_store_dwordx2 v[136:137], v[90:91], off offset:96
	s_waitcnt vmcnt(7)
	v_mfma_f32_16x16x32_bf16 v[86:89], v[48:51], v[64:67], 0
	v_readlane_b32 s1, v247, 24
	v_mfma_f32_16x16x32_bf16 v[64:67], v[32:35], v[64:67], 0
	s_waitcnt vmcnt(6)
	v_mfma_f32_16x16x32_bf16 v[86:89], v[52:55], v[68:71], v[86:89]
	v_mfma_f32_16x16x32_bf16 v[64:67], v[36:39], v[68:71], v[64:67]
	s_waitcnt vmcnt(5)
	v_mfma_f32_16x16x32_bf16 v[86:89], v[56:59], v[72:75], v[86:89]
	v_mfma_f32_16x16x32_bf16 v[64:67], v[40:43], v[72:75], v[64:67]
	s_waitcnt vmcnt(4)
	v_mfma_f32_16x16x32_bf16 v[86:89], v[60:63], v[76:79], v[86:89]
	v_mfma_f32_16x16x32_bf16 v[64:67], v[44:47], v[76:79], v[64:67]
	s_nop 6
	v_mul_f32_e32 v86, v132, v86
	v_mul_f32_e32 v87, v133, v87
	v_mul_f32_e32 v88, v134, v88
	v_mul_f32_e32 v89, v135, v89
	v_mul_f32_e32 v64, v126, v64
	v_mul_f32_e32 v65, v128, v65
	v_mul_f32_e32 v66, v127, v66
	v_mul_f32_e32 v67, v129, v67
	v_cndmask_b32_e64 v86, v86, 0, s[56:57]
	v_cndmask_b32_e64 v87, 0, v87, s[58:59]
	v_cndmask_b32_e64 v88, v88, 0, s[60:61]
	v_cndmask_b32_e64 v89, v89, 0, s[62:63]
	v_cndmask_b32_e64 v64, v64, 0, s[44:45]
	v_cndmask_b32_e64 v65, v65, 0, s[64:65]
	v_cndmask_b32_e64 v66, v66, 0, s[66:67]
	v_cndmask_b32_e64 v67, v67, 0, s[68:69]
	v_cvt_pk_bf16_f32 v86, v86, v87
	v_cvt_pk_bf16_f32 v87, v88, v89
	v_cvt_pk_bf16_f32 v64, v64, v65
	v_cvt_pk_bf16_f32 v65, v66, v67
	global_store_dwordx2 v[136:137], v[86:87], off offset:2048
	global_store_dwordx2 v[136:137], v[64:65], off offset:2080
	global_store_dwordx2 v[136:137], v[92:93], off offset:2112
	global_store_dwordx2 v[136:137], v[94:95], off offset:2144
	v_add_co_u32_e32 v64, vcc, s29, v82
	v_readlane_b32 s64, v246, 1
	s_nop 0
	v_addc_co_u32_e32 v65, vcc, 0, v83, vcc
	global_load_dwordx4 v[86:89], v[64:65], off
	global_load_dwordx4 v[90:93], v[64:65], off offset:64
	global_load_dwordx4 v[94:97], v[64:65], off offset:128
	global_load_dwordx4 v[126:129], v[64:65], off offset:192
	v_add_co_u32_e32 v76, vcc, s30, v82
	s_waitcnt vmcnt(3)
	v_mfma_f32_16x16x32_bf16 v[132:135], v[48:51], v[86:89], 0
	v_addc_co_u32_e32 v77, vcc, 0, v83, vcc
	global_load_dwordx4 v[64:67], v[76:77], off
	global_load_dwordx4 v[68:71], v[76:77], off offset:64
	global_load_dwordx4 v[72:75], v[76:77], off offset:128
	s_nop 0
	global_load_dwordx4 v[76:79], v[76:77], off offset:192
	s_waitcnt vmcnt(6)
	v_mfma_f32_16x16x32_bf16 v[132:135], v[52:55], v[90:93], v[132:135]
	v_readlane_b32 s65, v246, 2
	s_waitcnt vmcnt(5)
	v_mfma_f32_16x16x32_bf16 v[132:135], v[56:59], v[94:97], v[132:135]
	s_waitcnt vmcnt(4)
	v_mfma_f32_16x16x32_bf16 v[132:135], v[60:63], v[126:129], v[132:135]
	s_waitcnt vmcnt(3)
	v_mfma_f32_16x16x32_bf16 v[48:51], v[48:51], v[64:67], 0
	s_nop 5
	v_mul_f32_e32 v82, v125, v132
	v_cndmask_b32_e64 v82, v82, 0, s[0:1]
	v_readlane_b32 s0, v247, 25
	v_mul_f32_e32 v83, v124, v133
	v_readlane_b32 s1, v247, 26
	v_mul_f32_e32 v123, v123, v134
	v_mul_f32_e32 v122, v122, v135
	v_cndmask_b32_e64 v83, 0, v83, s[0:1]
	v_readlane_b32 s0, v247, 27
	v_readlane_b32 s1, v247, 28
	v_cvt_pk_bf16_f32 v82, v82, v83
	s_waitcnt vmcnt(2)
	v_mfma_f32_16x16x32_bf16 v[48:51], v[52:55], v[68:71], v[48:51]
	v_cndmask_b32_e64 v123, v123, 0, s[0:1]
	v_readlane_b32 s0, v247, 29
	v_readlane_b32 s1, v247, 30
	s_waitcnt vmcnt(1)
	v_mfma_f32_16x16x32_bf16 v[48:51], v[56:59], v[72:75], v[48:51]
	v_mov_b32_e32 v135, v145
	v_cndmask_b32_e64 v122, v122, 0, s[0:1]
	v_cvt_pk_bf16_f32 v83, v123, v122
	v_mfma_f32_16x16x32_bf16 v[122:125], v[32:35], v[86:89], 0
	v_readlane_b32 s0, v247, 39
	global_store_dwordx2 v[84:85], v[82:83], off
	v_readlane_b32 s1, v247, 40
	v_mfma_f32_16x16x32_bf16 v[122:125], v[36:39], v[90:93], v[122:125]
	v_mfma_f32_16x16x32_bf16 v[122:125], v[40:43], v[94:97], v[122:125]
	v_mfma_f32_16x16x32_bf16 v[122:125], v[44:47], v[126:129], v[122:125]
	v_mfma_f32_16x16x32_bf16 v[32:35], v[32:35], v[64:67], 0
	s_waitcnt vmcnt(1)
	v_mfma_f32_16x16x32_bf16 v[48:51], v[60:63], v[76:79], v[48:51]
	s_nop 4
	v_mul_f32_e32 v82, v121, v122
	v_cndmask_b32_e64 v82, v82, 0, s[0:1]
	v_readlane_b32 s0, v247, 41
	v_mul_f32_e32 v83, v120, v123
	v_readlane_b32 s1, v247, 42
	v_mfma_f32_16x16x32_bf16 v[32:35], v[36:39], v[68:71], v[32:35]
	v_mul_f32_e32 v119, v119, v124
	v_cndmask_b32_e64 v83, v83, 0, s[0:1]
	v_readlane_b32 s0, v247, 43
	v_readlane_b32 s1, v247, 44
	v_mfma_f32_16x16x32_bf16 v[86:89], v[16:19], v[86:89], 0
	v_mul_f32_e32 v48, v113, v48
	v_cndmask_b32_e64 v119, v119, 0, s[0:1]
	v_readlane_b32 s0, v247, 31
	v_readlane_b32 s1, v247, 32
	v_mfma_f32_16x16x32_bf16 v[32:35], v[40:43], v[72:75], v[32:35]
	v_mul_f32_e32 v49, v112, v49
	v_cndmask_b32_e64 v48, v48, 0, s[0:1]
	v_readlane_b32 s0, v247, 33
	v_mfma_f32_16x16x32_bf16 v[16:19], v[16:19], v[64:67], 0
	v_readlane_b32 s1, v247, 34
	v_mul_f32_e32 v50, v111, v50
	v_mul_f32_e32 v51, v110, v51
	v_cndmask_b32_e64 v49, 0, v49, s[0:1]
	v_readlane_b32 s0, v247, 35
	v_readlane_b32 s1, v247, 36
	v_mfma_f32_16x16x32_bf16 v[32:35], v[44:47], v[76:79], v[32:35]
	v_mul_f32_e32 v118, v118, v125
	v_cndmask_b32_e64 v50, v50, 0, s[0:1]
	v_readlane_b32 s0, v247, 37
	v_mfma_f32_16x16x32_bf16 v[16:19], v[20:23], v[68:71], v[16:19]
	v_readlane_b32 s1, v247, 38
	s_nop 2
	v_mul_f32_e32 v32, v109, v32
	v_mul_f32_e32 v33, v108, v33
	v_mfma_f32_16x16x32_bf16 v[0:3], v[0:3], v[64:67], 0
	v_cndmask_b32_e64 v51, v51, 0, s[0:1]
	v_readlane_b32 s0, v247, 45
	v_readlane_b32 s1, v247, 46
	v_mfma_f32_16x16x32_bf16 v[86:89], v[20:23], v[90:93], v[86:89]
	v_mul_f32_e32 v34, v107, v34
	v_cndmask_b32_e64 v32, v32, 0, s[0:1]
	v_readlane_b32 s0, v247, 47
	v_mfma_f32_16x16x32_bf16 v[16:19], v[24:27], v[72:75], v[16:19]
	v_readlane_b32 s1, v247, 48
	v_mul_f32_e32 v35, v106, v35
	v_cndmask_b32_e64 v118, v118, 0, s[48:49]
	v_mfma_f32_16x16x32_bf16 v[0:3], v[4:7], v[68:71], v[0:3]
	v_cndmask_b32_e64 v33, v33, 0, s[0:1]
	v_readlane_b32 s0, v247, 49
	v_readlane_b32 s1, v247, 50
	v_mfma_f32_16x16x32_bf16 v[86:89], v[24:27], v[94:97], v[86:89]
	v_cvt_pk_bf16_f32 v82, v82, v83
	v_cndmask_b32_e64 v34, v34, 0, s[0:1]
	v_readlane_b32 s0, v247, 51
	v_mfma_f32_16x16x32_bf16 v[16:19], v[28:31], v[76:79], v[16:19]
	v_readlane_b32 s1, v247, 52
	v_cvt_pk_bf16_f32 v83, v119, v118
	global_store_dwordx2 v[84:85], v[82:83], off offset:32
	v_mfma_f32_16x16x32_bf16 v[0:3], v[8:11], v[72:75], v[0:3]
	v_cndmask_b32_e64 v35, v35, 0, s[0:1]
	v_readlane_b32 s0, v247, 53
	s_nop 1
	v_mul_f32_e32 v16, v105, v16
	v_mfma_f32_16x16x32_bf16 v[86:89], v[28:31], v[126:129], v[86:89]
	v_readlane_b32 s1, v247, 54
	v_mul_f32_e32 v17, v104, v17
	v_mul_f32_e32 v18, v103, v18
	v_mfma_f32_16x16x32_bf16 v[0:3], v[12:15], v[76:79], v[0:3]
	v_cndmask_b32_e64 v16, v16, 0, s[0:1]
	v_readlane_b32 s0, v247, 55
	v_readlane_b32 s1, v247, 56
	s_nop 0
	v_mul_f32_e32 v82, v114, v86
	v_mul_f32_e32 v83, v115, v87
	v_cndmask_b32_e64 v17, v17, 0, s[0:1]
	v_readlane_b32 s0, v247, 57
	v_mul_f32_e32 v86, v116, v88
	v_mul_f32_e32 v87, v117, v89
	v_readlane_b32 s1, v247, 58
	v_mul_f32_e32 v0, v98, v0
	v_mul_f32_e32 v1, v99, v1
	v_mul_f32_e32 v2, v100, v2
	v_mul_f32_e32 v3, v101, v3
	v_cndmask_b32_e64 v82, v82, 0, s[44:45]
	v_cndmask_b32_e64 v83, v83, 0, s[50:51]
	v_cndmask_b32_e64 v86, v86, 0, s[52:53]
	v_cndmask_b32_e64 v87, v87, 0, s[54:55]
	v_cndmask_b32_e64 v18, v18, 0, s[0:1]
	v_readlane_b32 s0, v247, 59
	v_cndmask_b32_e64 v0, v0, 0, s[44:45]
	v_cndmask_b32_e64 v1, v1, 0, s[10:11]
	v_cndmask_b32_e64 v2, v2, 0, s[12:13]
	v_cndmask_b32_e64 v3, v3, 0, s[46:47]
	v_cvt_pk_bf16_f32 v82, v82, v83
	v_cvt_pk_bf16_f32 v83, v86, v87
	v_mul_f32_e32 v19, v102, v19
	v_readlane_b32 s1, v247, 60
	v_cvt_pk_bf16_f32 v0, v0, v1
	v_cvt_pk_bf16_f32 v1, v2, v3
	global_store_dwordx2 v[84:85], v[82:83], off offset:64
	global_store_dwordx2 v[84:85], v[80:81], off offset:96
	v_cndmask_b32_e64 v19, v19, 0, s[0:1]
	global_store_dwordx2 v[84:85], v[0:1], off offset:2144
	v_lshl_add_u64 v[0:1], v[144:145], 0, v[150:151]
	v_readlane_b32 s0, v247, 61
	v_lshl_add_u64 v[0:1], v[142:143], 0, v[0:1]
	v_readlane_b32 s2, v247, 63
	v_readlane_b32 s3, v246, 0
	s_mov_b32 s0, 0x2bb40000
	v_cvt_pk_bf16_f32 v48, v48, v49
	v_lshl_add_u64 v[0:1], s[2:3], 0, v[0:1]
	v_add_co_u32_e32 v2, vcc, s0, v0
	s_mov_b32 s0, 0x2bb41000
	s_nop 0
	v_addc_co_u32_e32 v3, vcc, 0, v1, vcc
	v_cvt_pk_bf16_f32 v49, v50, v51
	v_cvt_pk_bf16_f32 v32, v32, v33
	v_cvt_pk_bf16_f32 v33, v34, v35
	v_cvt_pk_bf16_f32 v16, v16, v17
	v_cvt_pk_bf16_f32 v17, v18, v19
	v_add_co_u32_e32 v4, vcc, s0, v0
	global_store_dwordx2 v[84:85], v[48:49], off offset:2048
	global_store_dwordx2 v[84:85], v[32:33], off offset:2080
	global_store_dwordx2 v[84:85], v[16:17], off offset:2112
	v_addc_co_u32_e32 v5, vcc, 0, v1, vcc
	s_mov_b32 s0, 0x2bb42000
	s_waitcnt lgkmcnt(0)
	ds_read2st64_b32 v[64:65], v131 offset0:0 offset1:1
	ds_read2st64_b32 v[66:67], v131 offset0:2 offset1:3
	ds_read2st64_b32 v[68:69], v131 offset0:4 offset1:5
	ds_read2st64_b32 v[70:71], v131 offset0:6 offset1:7
	ds_read2st64_b32 v[72:73], v131 offset0:8 offset1:9
	ds_read2st64_b32 v[74:75], v131 offset0:10 offset1:11
	ds_read2st64_b32 v[76:77], v131 offset0:12 offset1:13
	ds_read2st64_b32 v[78:79], v131 offset0:14 offset1:15
	ds_read2st64_b32 v[80:81], v131 offset0:16 offset1:17
	ds_read2st64_b32 v[82:83], v131 offset0:18 offset1:19
	ds_read2st64_b32 v[84:85], v131 offset0:20 offset1:21
	ds_read2st64_b32 v[86:87], v131 offset0:22 offset1:23
	ds_read2st64_b32 v[88:89], v131 offset0:24 offset1:25
	ds_read2st64_b32 v[90:91], v131 offset0:26 offset1:27
	ds_read2st64_b32 v[92:93], v131 offset0:28 offset1:29
	ds_read2st64_b32 v[94:95], v131 offset0:30 offset1:31
	ds_read2st64_b32 v[96:97], v131 offset0:32 offset1:33
	ds_read2st64_b32 v[98:99], v131 offset0:34 offset1:35
	ds_read2st64_b32 v[100:101], v131 offset0:36 offset1:37
	ds_read2st64_b32 v[102:103], v131 offset0:38 offset1:39
	ds_read2st64_b32 v[104:105], v131 offset0:40 offset1:41
	ds_read2st64_b32 v[106:107], v131 offset0:42 offset1:43
	ds_read2st64_b32 v[108:109], v131 offset0:44 offset1:45
	ds_read2st64_b32 v[110:111], v131 offset0:46 offset1:47
	ds_read2st64_b32 v[112:113], v131 offset0:48 offset1:49
	ds_read2st64_b32 v[114:115], v131 offset0:50 offset1:51
	ds_read2st64_b32 v[116:117], v131 offset0:52 offset1:53
	ds_read2st64_b32 v[118:119], v131 offset0:54 offset1:55
	ds_read2st64_b32 v[120:121], v131 offset0:56 offset1:57
	ds_read2st64_b32 v[122:123], v131 offset0:58 offset1:59
	ds_read2st64_b32 v[124:125], v131 offset0:60 offset1:61
	ds_read2st64_b32 v[126:127], v131 offset0:62 offset1:63
	v_readfirstlane_b32 s98, v131
	s_nop 3
	v_mov_b32_e32 v128, s98
	s_waitcnt lgkmcnt(0)
	ds_read_b128 v[8:11], v128 offset:256
	ds_read_b128 v[12:15], v128 offset:512
	ds_read_b128 v[16:19], v128 offset:768
	ds_read_b128 v[20:23], v128 offset:1024
	ds_read_b128 v[24:27], v128 offset:1280
	ds_read_b128 v[28:31], v128 offset:1536
	ds_read_b128 v[32:35], v128 offset:1792
	ds_read_b128 v[36:39], v128 offset:1296
	ds_read_b128 v[40:43], v128 offset:1552
	ds_read_b128 v[44:47], v128 offset:1808
	ds_read_b128 v[48:51], v128 offset:2048
	ds_read_b128 v[52:55], v128 offset:2304
	ds_read_b128 v[56:59], v128 offset:2560
	s_waitcnt lgkmcnt(12)
	v_mov_b32_e32 v129, v8
	ds_read_b128 v[60:63], v128 offset:2816
	s_waitcnt lgkmcnt(12)
	v_mov_b32_e32 v132, v12
	v_mov_b32_e32 v239, v13
	ds_read_b128 v[8:11], v128 offset:2064
	s_waitcnt lgkmcnt(12)
	v_mov_b32_e32 v249, v16
	v_mov_b32_e32 v6, v17
	v_mov_b32_e32 v7, v18
	v_fmac_f32_e32 v65, v129, v64
	v_fmac_f32_e32 v66, v132, v64
	v_fmac_f32_e32 v67, v249, v64
	v_fmac_f32_e32 v66, v239, v65
	v_fmac_f32_e32 v67, v6, v65
	v_fmac_f32_e32 v67, v7, v66
	ds_read_b128 v[12:15], v128 offset:2320
	s_waitcnt lgkmcnt(12)
	v_pk_mul_f32 v[134:135], v[20:21], v[64:65]
	v_pk_fma_f32 v[134:135], v[22:23], v[66:67], v[134:135]
	ds_read_b128 v[16:19], v128 offset:2576
	s_waitcnt lgkmcnt(12)
	v_pk_mul_f32 v[136:137], v[24:25], v[64:65]
	v_pk_fma_f32 v[136:137], v[26:27], v[66:67], v[136:137]
	ds_read_b128 v[20:23], v128 offset:2832
	s_waitcnt lgkmcnt(12)
	v_pk_mul_f32 v[240:241], v[28:29], v[64:65]
	v_pk_fma_f32 v[240:241], v[30:31], v[66:67], v[240:241]
	ds_read_b128 v[24:27], v128 offset:2336
	s_waitcnt lgkmcnt(12)
	v_pk_mul_f32 v[242:243], v[32:33], v[64:65]
	v_pk_fma_f32 v[242:243], v[34:35], v[66:67], v[242:243]
	ds_read_b128 v[28:31], v128 offset:2592
	s_waitcnt lgkmcnt(12)
	v_mov_b32_e32 v129, v36
	ds_read_b128 v[32:35], v128 offset:2848
	s_waitcnt lgkmcnt(12)
	v_mov_b32_e32 v132, v40
	v_mov_b32_e32 v239, v41
	ds_read_b128 v[36:39], v128 offset:3072
	s_waitcnt lgkmcnt(12)
	v_mov_b32_e32 v249, v44
	v_mov_b32_e32 v6, v45
	v_mov_b32_e32 v7, v46
	v_add_f32_e32 v134, v134, v135
	v_add_f32_e32 v136, v136, v137
	v_add_f32_e32 v240, v240, v241
	v_add_f32_e32 v242, v242, v243
	v_add_f32_e32 v68, v68, v134
	v_add_f32_e32 v69, v69, v136
	v_add_f32_e32 v70, v70, v240
	v_add_f32_e32 v71, v71, v242
	v_fmac_f32_e32 v69, v129, v68
	v_fmac_f32_e32 v70, v132, v68
	v_fmac_f32_e32 v71, v249, v68
	v_fmac_f32_e32 v70, v239, v69
	v_fmac_f32_e32 v71, v6, v69
	v_fmac_f32_e32 v71, v7, v70
	ds_read_b128 v[40:43], v128 offset:3328
	s_waitcnt lgkmcnt(12)
	v_pk_mul_f32 v[134:135], v[48:49], v[64:65]
	v_pk_fma_f32 v[134:135], v[50:51], v[66:67], v[134:135]
	ds_read_b128 v[44:47], v128 offset:3584
	s_waitcnt lgkmcnt(12)
	v_pk_mul_f32 v[136:137], v[52:53], v[64:65]
	v_pk_fma_f32 v[136:137], v[54:55], v[66:67], v[136:137]
	ds_read_b128 v[48:51], v128 offset:3840
	s_waitcnt lgkmcnt(12)
	v_pk_mul_f32 v[240:241], v[56:57], v[64:65]
	v_pk_fma_f32 v[240:241], v[58:59], v[66:67], v[240:241]
	ds_read_b128 v[52:55], v128 offset:3088
	s_waitcnt lgkmcnt(12)
	v_pk_mul_f32 v[242:243], v[60:61], v[64:65]
	v_pk_fma_f32 v[242:243], v[62:63], v[66:67], v[242:243]
	ds_read_b128 v[56:59], v128 offset:3344
	s_waitcnt lgkmcnt(12)
	v_pk_fma_f32 v[134:135], v[8:9], v[68:69], v[134:135]
	v_pk_fma_f32 v[134:135], v[10:11], v[70:71], v[134:135]
	ds_read_b128 v[60:63], v128 offset:3600
	s_waitcnt lgkmcnt(12)
	v_pk_fma_f32 v[136:137], v[12:13], v[68:69], v[136:137]
	v_pk_fma_f32 v[136:137], v[14:15], v[70:71], v[136:137]
	ds_read_b128 v[8:11], v128 offset:3856
	s_waitcnt lgkmcnt(12)
	v_pk_fma_f32 v[240:241], v[16:17], v[68:69], v[240:241]
	v_pk_fma_f32 v[240:241], v[18:19], v[70:71], v[240:241]
	ds_read_b128 v[12:15], v128 offset:3104
	s_waitcnt lgkmcnt(12)
	v_pk_fma_f32 v[242:243], v[20:21], v[68:69], v[242:243]
	v_pk_fma_f32 v[242:243], v[22:23], v[70:71], v[242:243]
	ds_read_b128 v[16:19], v128 offset:3360
	s_waitcnt lgkmcnt(12)
	v_mov_b32_e32 v129, v24
	ds_read_b128 v[20:23], v128 offset:3616
	s_waitcnt lgkmcnt(12)
	v_mov_b32_e32 v132, v28
	v_mov_b32_e32 v239, v29
	ds_read_b128 v[24:27], v128 offset:3872
	s_waitcnt lgkmcnt(12)
	v_mov_b32_e32 v249, v32
	v_mov_b32_e32 v6, v33
	v_mov_b32_e32 v7, v34
	v_add_f32_e32 v134, v134, v135
	v_add_f32_e32 v136, v136, v137
	v_add_f32_e32 v240, v240, v241
	v_add_f32_e32 v242, v242, v243
	v_add_f32_e32 v72, v72, v134
	v_add_f32_e32 v73, v73, v136
	v_add_f32_e32 v74, v74, v240
	v_add_f32_e32 v75, v75, v242
	v_fmac_f32_e32 v73, v129, v72
	v_fmac_f32_e32 v74, v132, v72
	v_fmac_f32_e32 v75, v249, v72
	v_fmac_f32_e32 v74, v239, v73
	v_fmac_f32_e32 v75, v6, v73
	v_fmac_f32_e32 v75, v7, v74
	ds_read_b128 v[28:31], v128 offset:3376
	s_waitcnt lgkmcnt(12)
	v_pk_mul_f32 v[134:135], v[36:37], v[64:65]
	v_pk_fma_f32 v[134:135], v[38:39], v[66:67], v[134:135]
	ds_read_b128 v[32:35], v128 offset:3632
	s_waitcnt lgkmcnt(12)
	v_pk_mul_f32 v[136:137], v[40:41], v[64:65]
	v_pk_fma_f32 v[136:137], v[42:43], v[66:67], v[136:137]
	ds_read_b128 v[36:39], v128 offset:3888
	s_waitcnt lgkmcnt(12)
	v_pk_mul_f32 v[240:241], v[44:45], v[64:65]
	v_pk_fma_f32 v[240:241], v[46:47], v[66:67], v[240:241]
	ds_read_b128 v[40:43], v128 offset:4096
	s_waitcnt lgkmcnt(12)
	v_pk_mul_f32 v[242:243], v[48:49], v[64:65]
	v_pk_fma_f32 v[242:243], v[50:51], v[66:67], v[242:243]
	ds_read_b128 v[44:47], v128 offset:4352
	s_waitcnt lgkmcnt(12)
	v_pk_fma_f32 v[134:135], v[52:53], v[68:69], v[134:135]
	v_pk_fma_f32 v[134:135], v[54:55], v[70:71], v[134:135]
	ds_read_b128 v[48:51], v128 offset:4608
	s_waitcnt lgkmcnt(12)
	v_pk_fma_f32 v[136:137], v[56:57], v[68:69], v[136:137]
	v_pk_fma_f32 v[136:137], v[58:59], v[70:71], v[136:137]
	ds_read_b128 v[52:55], v128 offset:4864
	s_waitcnt lgkmcnt(12)
	v_pk_fma_f32 v[240:241], v[60:61], v[68:69], v[240:241]
	v_pk_fma_f32 v[240:241], v[62:63], v[70:71], v[240:241]
	ds_read_b128 v[56:59], v128 offset:4112
	s_waitcnt lgkmcnt(12)
	v_pk_fma_f32 v[242:243], v[8:9], v[68:69], v[242:243]
	v_pk_fma_f32 v[242:243], v[10:11], v[70:71], v[242:243]
	ds_read_b128 v[60:63], v128 offset:4368
	s_waitcnt lgkmcnt(12)
	v_pk_fma_f32 v[134:135], v[12:13], v[72:73], v[134:135]
	v_pk_fma_f32 v[134:135], v[14:15], v[74:75], v[134:135]
	ds_read_b128 v[8:11], v128 offset:4624
	s_waitcnt lgkmcnt(12)
	v_pk_fma_f32 v[136:137], v[16:17], v[72:73], v[136:137]
	v_pk_fma_f32 v[136:137], v[18:19], v[74:75], v[136:137]
	ds_read_b128 v[12:15], v128 offset:4880
	s_waitcnt lgkmcnt(12)
	v_pk_fma_f32 v[240:241], v[20:21], v[72:73], v[240:241]
	v_pk_fma_f32 v[240:241], v[22:23], v[74:75], v[240:241]
	ds_read_b128 v[16:19], v128 offset:4128
	s_waitcnt lgkmcnt(12)
	v_pk_fma_f32 v[242:243], v[24:25], v[72:73], v[242:243]
	v_pk_fma_f32 v[242:243], v[26:27], v[74:75], v[242:243]
	ds_read_b128 v[20:23], v128 offset:4384
	s_waitcnt lgkmcnt(12)
	v_mov_b32_e32 v129, v28
	ds_read_b128 v[24:27], v128 offset:4640
	s_waitcnt lgkmcnt(12)
	v_mov_b32_e32 v132, v32
	v_mov_b32_e32 v239, v33
	ds_read_b128 v[28:31], v128 offset:4896
	s_waitcnt lgkmcnt(12)
	v_mov_b32_e32 v249, v36
	v_mov_b32_e32 v6, v37
	v_mov_b32_e32 v7, v38
	v_add_f32_e32 v134, v134, v135
	v_add_f32_e32 v136, v136, v137
	v_add_f32_e32 v240, v240, v241
	v_add_f32_e32 v242, v242, v243
	v_add_f32_e32 v76, v76, v134
	v_add_f32_e32 v77, v77, v136
	v_add_f32_e32 v78, v78, v240
	v_add_f32_e32 v79, v79, v242
	v_fmac_f32_e32 v77, v129, v76
	v_fmac_f32_e32 v78, v132, v76
	v_fmac_f32_e32 v79, v249, v76
	v_fmac_f32_e32 v78, v239, v77
	v_fmac_f32_e32 v79, v6, v77
	v_fmac_f32_e32 v79, v7, v78
	ds_read_b128 v[32:35], v128 offset:4144
	s_waitcnt lgkmcnt(12)
	v_pk_mul_f32 v[134:135], v[40:41], v[64:65]
	v_pk_fma_f32 v[134:135], v[42:43], v[66:67], v[134:135]
	ds_read_b128 v[36:39], v128 offset:4400
	s_waitcnt lgkmcnt(12)
	v_pk_mul_f32 v[136:137], v[44:45], v[64:65]
	v_pk_fma_f32 v[136:137], v[46:47], v[66:67], v[136:137]
	ds_read_b128 v[40:43], v128 offset:4656
	s_waitcnt lgkmcnt(12)
	v_pk_mul_f32 v[240:241], v[48:49], v[64:65]
	v_pk_fma_f32 v[240:241], v[50:51], v[66:67], v[240:241]
	ds_read_b128 v[44:47], v128 offset:4912
	s_waitcnt lgkmcnt(12)
	v_pk_mul_f32 v[242:243], v[52:53], v[64:65]
	v_pk_fma_f32 v[242:243], v[54:55], v[66:67], v[242:243]
	ds_read_b128 v[48:51], v128 offset:4416
	s_waitcnt lgkmcnt(12)
	v_pk_fma_f32 v[134:135], v[56:57], v[68:69], v[134:135]
	v_pk_fma_f32 v[134:135], v[58:59], v[70:71], v[134:135]
	ds_read_b128 v[52:55], v128 offset:4672
	s_waitcnt lgkmcnt(12)
	v_pk_fma_f32 v[136:137], v[60:61], v[68:69], v[136:137]
	v_pk_fma_f32 v[136:137], v[62:63], v[70:71], v[136:137]
	ds_read_b128 v[56:59], v128 offset:4928
	s_waitcnt lgkmcnt(12)
	v_pk_fma_f32 v[240:241], v[8:9], v[68:69], v[240:241]
	v_pk_fma_f32 v[240:241], v[10:11], v[70:71], v[240:241]
	ds_read_b128 v[60:63], v128 offset:5120
	s_waitcnt lgkmcnt(12)
	v_pk_fma_f32 v[242:243], v[12:13], v[68:69], v[242:243]
	v_pk_fma_f32 v[242:243], v[14:15], v[70:71], v[242:243]
	ds_read_b128 v[8:11], v128 offset:5376
	s_waitcnt lgkmcnt(12)
	v_pk_fma_f32 v[134:135], v[16:17], v[72:73], v[134:135]
	v_pk_fma_f32 v[134:135], v[18:19], v[74:75], v[134:135]
	ds_read_b128 v[12:15], v128 offset:5632
	s_waitcnt lgkmcnt(12)
	v_pk_fma_f32 v[136:137], v[20:21], v[72:73], v[136:137]
	v_pk_fma_f32 v[136:137], v[22:23], v[74:75], v[136:137]
	ds_read_b128 v[16:19], v128 offset:5888
	s_waitcnt lgkmcnt(12)
	v_pk_fma_f32 v[240:241], v[24:25], v[72:73], v[240:241]
	v_pk_fma_f32 v[240:241], v[26:27], v[74:75], v[240:241]
	ds_read_b128 v[20:23], v128 offset:5136
	s_waitcnt lgkmcnt(12)
	v_pk_fma_f32 v[242:243], v[28:29], v[72:73], v[242:243]
	v_pk_fma_f32 v[242:243], v[30:31], v[74:75], v[242:243]
	ds_read_b128 v[24:27], v128 offset:5392
	s_waitcnt lgkmcnt(12)
	v_pk_fma_f32 v[134:135], v[32:33], v[76:77], v[134:135]
	v_pk_fma_f32 v[134:135], v[34:35], v[78:79], v[134:135]
	ds_read_b128 v[28:31], v128 offset:5648
	s_waitcnt lgkmcnt(12)
	v_pk_fma_f32 v[136:137], v[36:37], v[76:77], v[136:137]
	v_pk_fma_f32 v[136:137], v[38:39], v[78:79], v[136:137]
	ds_read_b128 v[32:35], v128 offset:5904
	s_waitcnt lgkmcnt(12)
	v_pk_fma_f32 v[240:241], v[40:41], v[76:77], v[240:241]
	v_pk_fma_f32 v[240:241], v[42:43], v[78:79], v[240:241]
	ds_read_b128 v[36:39], v128 offset:5152
	s_waitcnt lgkmcnt(12)
	v_pk_fma_f32 v[242:243], v[44:45], v[76:77], v[242:243]
	v_pk_fma_f32 v[242:243], v[46:47], v[78:79], v[242:243]
	ds_read_b128 v[40:43], v128 offset:5408
	s_waitcnt lgkmcnt(12)
	v_mov_b32_e32 v129, v48
	ds_read_b128 v[44:47], v128 offset:5664
	s_waitcnt lgkmcnt(12)
	v_mov_b32_e32 v132, v52
	v_mov_b32_e32 v239, v53
	ds_read_b128 v[48:51], v128 offset:5920
	s_waitcnt lgkmcnt(12)
	v_mov_b32_e32 v249, v56
	v_mov_b32_e32 v6, v57
	v_mov_b32_e32 v7, v58
	v_add_f32_e32 v134, v134, v135
	v_add_f32_e32 v136, v136, v137
	v_add_f32_e32 v240, v240, v241
	v_add_f32_e32 v242, v242, v243
	v_add_f32_e32 v80, v80, v134
	v_add_f32_e32 v81, v81, v136
	v_add_f32_e32 v82, v82, v240
	v_add_f32_e32 v83, v83, v242
	v_fmac_f32_e32 v81, v129, v80
	v_fmac_f32_e32 v82, v132, v80
	v_fmac_f32_e32 v83, v249, v80
	v_fmac_f32_e32 v82, v239, v81
	v_fmac_f32_e32 v83, v6, v81
	v_fmac_f32_e32 v83, v7, v82
	ds_read_b128 v[52:55], v128 offset:5168
	s_waitcnt lgkmcnt(12)
	v_pk_mul_f32 v[134:135], v[60:61], v[64:65]
	v_pk_fma_f32 v[134:135], v[62:63], v[66:67], v[134:135]
	ds_read_b128 v[56:59], v128 offset:5424
	s_waitcnt lgkmcnt(12)
	v_pk_mul_f32 v[136:137], v[8:9], v[64:65]
	v_pk_fma_f32 v[136:137], v[10:11], v[66:67], v[136:137]
	ds_read_b128 v[60:63], v128 offset:5680
	s_waitcnt lgkmcnt(12)
	v_pk_mul_f32 v[240:241], v[12:13], v[64:65]
	v_pk_fma_f32 v[240:241], v[14:15], v[66:67], v[240:241]
	ds_read_b128 v[8:11], v128 offset:5936
	s_waitcnt lgkmcnt(12)
	v_pk_mul_f32 v[242:243], v[16:17], v[64:65]
	v_pk_fma_f32 v[242:243], v[18:19], v[66:67], v[242:243]
	ds_read_b128 v[12:15], v128 offset:5184
	s_waitcnt lgkmcnt(12)
	v_pk_fma_f32 v[134:135], v[20:21], v[68:69], v[134:135]
	v_pk_fma_f32 v[134:135], v[22:23], v[70:71], v[134:135]
	ds_read_b128 v[16:19], v128 offset:5440
	s_waitcnt lgkmcnt(12)
	v_pk_fma_f32 v[136:137], v[24:25], v[68:69], v[136:137]
	v_pk_fma_f32 v[136:137], v[26:27], v[70:71], v[136:137]
	ds_read_b128 v[20:23], v128 offset:5696
	s_waitcnt lgkmcnt(12)
	v_pk_fma_f32 v[240:241], v[28:29], v[68:69], v[240:241]
	v_pk_fma_f32 v[240:241], v[30:31], v[70:71], v[240:241]
	ds_read_b128 v[24:27], v128 offset:5952
	s_waitcnt lgkmcnt(12)
	v_pk_fma_f32 v[242:243], v[32:33], v[68:69], v[242:243]
	v_pk_fma_f32 v[242:243], v[34:35], v[70:71], v[242:243]
	ds_read_b128 v[28:31], v128 offset:5456
	s_waitcnt lgkmcnt(12)
	v_pk_fma_f32 v[134:135], v[36:37], v[72:73], v[134:135]
	v_pk_fma_f32 v[134:135], v[38:39], v[74:75], v[134:135]
	ds_read_b128 v[32:35], v128 offset:5712
	s_waitcnt lgkmcnt(12)
	v_pk_fma_f32 v[136:137], v[40:41], v[72:73], v[136:137]
	v_pk_fma_f32 v[136:137], v[42:43], v[74:75], v[136:137]
	ds_read_b128 v[36:39], v128 offset:5968
	s_waitcnt lgkmcnt(12)
	v_pk_fma_f32 v[240:241], v[44:45], v[72:73], v[240:241]
	v_pk_fma_f32 v[240:241], v[46:47], v[74:75], v[240:241]
	ds_read_b128 v[40:43], v128 offset:6144
	s_waitcnt lgkmcnt(12)
	v_pk_fma_f32 v[242:243], v[48:49], v[72:73], v[242:243]
	v_pk_fma_f32 v[242:243], v[50:51], v[74:75], v[242:243]
	ds_read_b128 v[44:47], v128 offset:6400
	s_waitcnt lgkmcnt(12)
	v_pk_fma_f32 v[134:135], v[52:53], v[76:77], v[134:135]
	v_pk_fma_f32 v[134:135], v[54:55], v[78:79], v[134:135]
	ds_read_b128 v[48:51], v128 offset:6656
	s_waitcnt lgkmcnt(12)
	v_pk_fma_f32 v[136:137], v[56:57], v[76:77], v[136:137]
	v_pk_fma_f32 v[136:137], v[58:59], v[78:79], v[136:137]
	ds_read_b128 v[52:55], v128 offset:6912
	s_waitcnt lgkmcnt(12)
	v_pk_fma_f32 v[240:241], v[60:61], v[76:77], v[240:241]
	v_pk_fma_f32 v[240:241], v[62:63], v[78:79], v[240:241]
	ds_read_b128 v[56:59], v128 offset:6160
	s_waitcnt lgkmcnt(12)
	v_pk_fma_f32 v[242:243], v[8:9], v[76:77], v[242:243]
	v_pk_fma_f32 v[242:243], v[10:11], v[78:79], v[242:243]
	ds_read_b128 v[60:63], v128 offset:6416
	s_waitcnt lgkmcnt(12)
	v_pk_fma_f32 v[134:135], v[12:13], v[80:81], v[134:135]
	v_pk_fma_f32 v[134:135], v[14:15], v[82:83], v[134:135]
	ds_read_b128 v[8:11], v128 offset:6672
	s_waitcnt lgkmcnt(12)
	v_pk_fma_f32 v[136:137], v[16:17], v[80:81], v[136:137]
	v_pk_fma_f32 v[136:137], v[18:19], v[82:83], v[136:137]
	ds_read_b128 v[12:15], v128 offset:6928
	s_waitcnt lgkmcnt(12)
	v_pk_fma_f32 v[240:241], v[20:21], v[80:81], v[240:241]
	v_pk_fma_f32 v[240:241], v[22:23], v[82:83], v[240:241]
	ds_read_b128 v[16:19], v128 offset:6176
	s_waitcnt lgkmcnt(12)
	v_pk_fma_f32 v[242:243], v[24:25], v[80:81], v[242:243]
	v_pk_fma_f32 v[242:243], v[26:27], v[82:83], v[242:243]
	ds_read_b128 v[20:23], v128 offset:6432
	s_waitcnt lgkmcnt(12)
	v_mov_b32_e32 v129, v28
	ds_read_b128 v[24:27], v128 offset:6688
	s_waitcnt lgkmcnt(12)
	v_mov_b32_e32 v132, v32
	v_mov_b32_e32 v239, v33
	ds_read_b128 v[28:31], v128 offset:6944
	s_waitcnt lgkmcnt(12)
	v_mov_b32_e32 v249, v36
	v_mov_b32_e32 v6, v37
	v_mov_b32_e32 v7, v38
	v_add_f32_e32 v134, v134, v135
	v_add_f32_e32 v136, v136, v137
	v_add_f32_e32 v240, v240, v241
	v_add_f32_e32 v242, v242, v243
	v_add_f32_e32 v84, v84, v134
	v_add_f32_e32 v85, v85, v136
	v_add_f32_e32 v86, v86, v240
	v_add_f32_e32 v87, v87, v242
	v_fmac_f32_e32 v85, v129, v84
	v_fmac_f32_e32 v86, v132, v84
	v_fmac_f32_e32 v87, v249, v84
	v_fmac_f32_e32 v86, v239, v85
	v_fmac_f32_e32 v87, v6, v85
	v_fmac_f32_e32 v87, v7, v86
	ds_read_b128 v[32:35], v128 offset:6192
	s_waitcnt lgkmcnt(12)
	v_pk_mul_f32 v[134:135], v[40:41], v[64:65]
	v_pk_fma_f32 v[134:135], v[42:43], v[66:67], v[134:135]
	ds_read_b128 v[36:39], v128 offset:6448
	s_waitcnt lgkmcnt(12)
	v_pk_mul_f32 v[136:137], v[44:45], v[64:65]
	v_pk_fma_f32 v[136:137], v[46:47], v[66:67], v[136:137]
	ds_read_b128 v[40:43], v128 offset:6704
	s_waitcnt lgkmcnt(12)
	v_pk_mul_f32 v[240:241], v[48:49], v[64:65]
	v_pk_fma_f32 v[240:241], v[50:51], v[66:67], v[240:241]
	ds_read_b128 v[44:47], v128 offset:6960
	s_waitcnt lgkmcnt(12)
	v_pk_mul_f32 v[242:243], v[52:53], v[64:65]
	v_pk_fma_f32 v[242:243], v[54:55], v[66:67], v[242:243]
	ds_read_b128 v[48:51], v128 offset:6208
	s_waitcnt lgkmcnt(12)
	v_pk_fma_f32 v[134:135], v[56:57], v[68:69], v[134:135]
	v_pk_fma_f32 v[134:135], v[58:59], v[70:71], v[134:135]
	ds_read_b128 v[52:55], v128 offset:6464
	s_waitcnt lgkmcnt(12)
	v_pk_fma_f32 v[136:137], v[60:61], v[68:69], v[136:137]
	v_pk_fma_f32 v[136:137], v[62:63], v[70:71], v[136:137]
	ds_read_b128 v[56:59], v128 offset:6720
	s_waitcnt lgkmcnt(12)
	v_pk_fma_f32 v[240:241], v[8:9], v[68:69], v[240:241]
	v_pk_fma_f32 v[240:241], v[10:11], v[70:71], v[240:241]
	ds_read_b128 v[60:63], v128 offset:6976
	s_waitcnt lgkmcnt(12)
	v_pk_fma_f32 v[242:243], v[12:13], v[68:69], v[242:243]
	v_pk_fma_f32 v[242:243], v[14:15], v[70:71], v[242:243]
	ds_read_b128 v[8:11], v128 offset:6224
	s_waitcnt lgkmcnt(12)
	v_pk_fma_f32 v[134:135], v[16:17], v[72:73], v[134:135]
	v_pk_fma_f32 v[134:135], v[18:19], v[74:75], v[134:135]
	ds_read_b128 v[12:15], v128 offset:6480
	s_waitcnt lgkmcnt(12)
	v_pk_fma_f32 v[136:137], v[20:21], v[72:73], v[136:137]
	v_pk_fma_f32 v[136:137], v[22:23], v[74:75], v[136:137]
	ds_read_b128 v[16:19], v128 offset:6736
	s_waitcnt lgkmcnt(12)
	v_pk_fma_f32 v[240:241], v[24:25], v[72:73], v[240:241]
	v_pk_fma_f32 v[240:241], v[26:27], v[74:75], v[240:241]
	ds_read_b128 v[20:23], v128 offset:6992
	s_waitcnt lgkmcnt(12)
	v_pk_fma_f32 v[242:243], v[28:29], v[72:73], v[242:243]
	v_pk_fma_f32 v[242:243], v[30:31], v[74:75], v[242:243]
	ds_read_b128 v[24:27], v128 offset:6496
	s_waitcnt lgkmcnt(12)
	v_pk_fma_f32 v[134:135], v[32:33], v[76:77], v[134:135]
	v_pk_fma_f32 v[134:135], v[34:35], v[78:79], v[134:135]
	ds_read_b128 v[28:31], v128 offset:6752
	s_waitcnt lgkmcnt(12)
	v_pk_fma_f32 v[136:137], v[36:37], v[76:77], v[136:137]
	v_pk_fma_f32 v[136:137], v[38:39], v[78:79], v[136:137]
	ds_read_b128 v[32:35], v128 offset:7008
	s_waitcnt lgkmcnt(12)
	v_pk_fma_f32 v[240:241], v[40:41], v[76:77], v[240:241]
	v_pk_fma_f32 v[240:241], v[42:43], v[78:79], v[240:241]
	ds_read_b128 v[36:39], v128 offset:7168
	s_waitcnt lgkmcnt(12)
	v_pk_fma_f32 v[242:243], v[44:45], v[76:77], v[242:243]
	v_pk_fma_f32 v[242:243], v[46:47], v[78:79], v[242:243]
	ds_read_b128 v[40:43], v128 offset:7424
	s_waitcnt lgkmcnt(12)
	v_pk_fma_f32 v[134:135], v[48:49], v[80:81], v[134:135]
	v_pk_fma_f32 v[134:135], v[50:51], v[82:83], v[134:135]
	ds_read_b128 v[44:47], v128 offset:7680
	s_waitcnt lgkmcnt(12)
	v_pk_fma_f32 v[136:137], v[52:53], v[80:81], v[136:137]
	v_pk_fma_f32 v[136:137], v[54:55], v[82:83], v[136:137]
	ds_read_b128 v[48:51], v128 offset:7936
	s_waitcnt lgkmcnt(12)
	v_pk_fma_f32 v[240:241], v[56:57], v[80:81], v[240:241]
	v_pk_fma_f32 v[240:241], v[58:59], v[82:83], v[240:241]
	ds_read_b128 v[52:55], v128 offset:7184
	s_waitcnt lgkmcnt(12)
	v_pk_fma_f32 v[242:243], v[60:61], v[80:81], v[242:243]
	v_pk_fma_f32 v[242:243], v[62:63], v[82:83], v[242:243]
	ds_read_b128 v[56:59], v128 offset:7440
	s_waitcnt lgkmcnt(12)
	v_pk_fma_f32 v[134:135], v[8:9], v[84:85], v[134:135]
	v_pk_fma_f32 v[134:135], v[10:11], v[86:87], v[134:135]
	ds_read_b128 v[60:63], v128 offset:7696
	s_waitcnt lgkmcnt(12)
	v_pk_fma_f32 v[136:137], v[12:13], v[84:85], v[136:137]
	v_pk_fma_f32 v[136:137], v[14:15], v[86:87], v[136:137]
	ds_read_b128 v[8:11], v128 offset:7952
	s_waitcnt lgkmcnt(12)
	v_pk_fma_f32 v[240:241], v[16:17], v[84:85], v[240:241]
	v_pk_fma_f32 v[240:241], v[18:19], v[86:87], v[240:241]
	ds_read_b128 v[12:15], v128 offset:7200
	s_waitcnt lgkmcnt(12)
	v_pk_fma_f32 v[242:243], v[20:21], v[84:85], v[242:243]
	v_pk_fma_f32 v[242:243], v[22:23], v[86:87], v[242:243]
	ds_read_b128 v[16:19], v128 offset:7456
	s_waitcnt lgkmcnt(12)
	v_mov_b32_e32 v129, v24
	ds_read_b128 v[20:23], v128 offset:7712
	s_waitcnt lgkmcnt(12)
	v_mov_b32_e32 v132, v28
	v_mov_b32_e32 v239, v29
	ds_read_b128 v[24:27], v128 offset:7968
	s_waitcnt lgkmcnt(12)
	v_mov_b32_e32 v249, v32
	v_mov_b32_e32 v6, v33
	v_mov_b32_e32 v7, v34
	v_add_f32_e32 v134, v134, v135
	v_add_f32_e32 v136, v136, v137
	v_add_f32_e32 v240, v240, v241
	v_add_f32_e32 v242, v242, v243
	v_add_f32_e32 v88, v88, v134
	v_add_f32_e32 v89, v89, v136
	v_add_f32_e32 v90, v90, v240
	v_add_f32_e32 v91, v91, v242
	v_fmac_f32_e32 v89, v129, v88
	v_fmac_f32_e32 v90, v132, v88
	v_fmac_f32_e32 v91, v249, v88
	v_fmac_f32_e32 v90, v239, v89
	v_fmac_f32_e32 v91, v6, v89
	v_fmac_f32_e32 v91, v7, v90
	ds_read_b128 v[28:31], v128 offset:7216
	s_waitcnt lgkmcnt(12)
	v_pk_mul_f32 v[134:135], v[36:37], v[64:65]
	v_pk_fma_f32 v[134:135], v[38:39], v[66:67], v[134:135]
	ds_read_b128 v[32:35], v128 offset:7472
	s_waitcnt lgkmcnt(12)
	v_pk_mul_f32 v[136:137], v[40:41], v[64:65]
	v_pk_fma_f32 v[136:137], v[42:43], v[66:67], v[136:137]
	ds_read_b128 v[36:39], v128 offset:7728
	s_waitcnt lgkmcnt(12)
	v_pk_mul_f32 v[240:241], v[44:45], v[64:65]
	v_pk_fma_f32 v[240:241], v[46:47], v[66:67], v[240:241]
	ds_read_b128 v[40:43], v128 offset:7984
	s_waitcnt lgkmcnt(12)
	v_pk_mul_f32 v[242:243], v[48:49], v[64:65]
	v_pk_fma_f32 v[242:243], v[50:51], v[66:67], v[242:243]
	ds_read_b128 v[44:47], v128 offset:7232
	s_waitcnt lgkmcnt(12)
	v_pk_fma_f32 v[134:135], v[52:53], v[68:69], v[134:135]
	v_pk_fma_f32 v[134:135], v[54:55], v[70:71], v[134:135]
	ds_read_b128 v[48:51], v128 offset:7488
	s_waitcnt lgkmcnt(12)
	v_pk_fma_f32 v[136:137], v[56:57], v[68:69], v[136:137]
	v_pk_fma_f32 v[136:137], v[58:59], v[70:71], v[136:137]
	ds_read_b128 v[52:55], v128 offset:7744
	s_waitcnt lgkmcnt(12)
	v_pk_fma_f32 v[240:241], v[60:61], v[68:69], v[240:241]
	v_pk_fma_f32 v[240:241], v[62:63], v[70:71], v[240:241]
	ds_read_b128 v[56:59], v128 offset:8000
	s_waitcnt lgkmcnt(12)
	v_pk_fma_f32 v[242:243], v[8:9], v[68:69], v[242:243]
	v_pk_fma_f32 v[242:243], v[10:11], v[70:71], v[242:243]
	ds_read_b128 v[60:63], v128 offset:7248
	s_waitcnt lgkmcnt(12)
	v_pk_fma_f32 v[134:135], v[12:13], v[72:73], v[134:135]
	v_pk_fma_f32 v[134:135], v[14:15], v[74:75], v[134:135]
	ds_read_b128 v[8:11], v128 offset:7504
	s_waitcnt lgkmcnt(12)
	v_pk_fma_f32 v[136:137], v[16:17], v[72:73], v[136:137]
	v_pk_fma_f32 v[136:137], v[18:19], v[74:75], v[136:137]
	ds_read_b128 v[12:15], v128 offset:7760
	s_waitcnt lgkmcnt(12)
	v_pk_fma_f32 v[240:241], v[20:21], v[72:73], v[240:241]
	v_pk_fma_f32 v[240:241], v[22:23], v[74:75], v[240:241]
	ds_read_b128 v[16:19], v128 offset:8016
	s_waitcnt lgkmcnt(12)
	v_pk_fma_f32 v[242:243], v[24:25], v[72:73], v[242:243]
	v_pk_fma_f32 v[242:243], v[26:27], v[74:75], v[242:243]
	ds_read_b128 v[20:23], v128 offset:7264
	s_waitcnt lgkmcnt(12)
	v_pk_fma_f32 v[134:135], v[28:29], v[76:77], v[134:135]
	v_pk_fma_f32 v[134:135], v[30:31], v[78:79], v[134:135]
	ds_read_b128 v[24:27], v128 offset:7520
	s_waitcnt lgkmcnt(12)
	v_pk_fma_f32 v[136:137], v[32:33], v[76:77], v[136:137]
	v_pk_fma_f32 v[136:137], v[34:35], v[78:79], v[136:137]
	ds_read_b128 v[28:31], v128 offset:7776
	s_waitcnt lgkmcnt(12)
	v_pk_fma_f32 v[240:241], v[36:37], v[76:77], v[240:241]
	v_pk_fma_f32 v[240:241], v[38:39], v[78:79], v[240:241]
	ds_read_b128 v[32:35], v128 offset:8032
	s_waitcnt lgkmcnt(12)
	v_pk_fma_f32 v[242:243], v[40:41], v[76:77], v[242:243]
	v_pk_fma_f32 v[242:243], v[42:43], v[78:79], v[242:243]
	ds_read_b128 v[36:39], v128 offset:7536
	s_waitcnt lgkmcnt(12)
	v_pk_fma_f32 v[134:135], v[44:45], v[80:81], v[134:135]
	v_pk_fma_f32 v[134:135], v[46:47], v[82:83], v[134:135]
	ds_read_b128 v[40:43], v128 offset:7792
	s_waitcnt lgkmcnt(12)
	v_pk_fma_f32 v[136:137], v[48:49], v[80:81], v[136:137]
	v_pk_fma_f32 v[136:137], v[50:51], v[82:83], v[136:137]
	ds_read_b128 v[44:47], v128 offset:8048
	s_waitcnt lgkmcnt(12)
	v_pk_fma_f32 v[240:241], v[52:53], v[80:81], v[240:241]
	v_pk_fma_f32 v[240:241], v[54:55], v[82:83], v[240:241]
	ds_read_b128 v[48:51], v128 offset:8192
	s_waitcnt lgkmcnt(12)
	v_pk_fma_f32 v[242:243], v[56:57], v[80:81], v[242:243]
	v_pk_fma_f32 v[242:243], v[58:59], v[82:83], v[242:243]
	ds_read_b128 v[52:55], v128 offset:8448
	s_waitcnt lgkmcnt(12)
	v_pk_fma_f32 v[134:135], v[60:61], v[84:85], v[134:135]
	v_pk_fma_f32 v[134:135], v[62:63], v[86:87], v[134:135]
	ds_read_b128 v[56:59], v128 offset:8704
	s_waitcnt lgkmcnt(12)
	v_pk_fma_f32 v[136:137], v[8:9], v[84:85], v[136:137]
	v_pk_fma_f32 v[136:137], v[10:11], v[86:87], v[136:137]
	ds_read_b128 v[60:63], v128 offset:8960
	s_waitcnt lgkmcnt(12)
	v_pk_fma_f32 v[240:241], v[12:13], v[84:85], v[240:241]
	v_pk_fma_f32 v[240:241], v[14:15], v[86:87], v[240:241]
	ds_read_b128 v[8:11], v128 offset:8208
	s_waitcnt lgkmcnt(12)
	v_pk_fma_f32 v[242:243], v[16:17], v[84:85], v[242:243]
	v_pk_fma_f32 v[242:243], v[18:19], v[86:87], v[242:243]
	ds_read_b128 v[12:15], v128 offset:8464
	s_waitcnt lgkmcnt(12)
	v_pk_fma_f32 v[134:135], v[20:21], v[88:89], v[134:135]
	v_pk_fma_f32 v[134:135], v[22:23], v[90:91], v[134:135]
	ds_read_b128 v[16:19], v128 offset:8720
	s_waitcnt lgkmcnt(12)
	v_pk_fma_f32 v[136:137], v[24:25], v[88:89], v[136:137]
	v_pk_fma_f32 v[136:137], v[26:27], v[90:91], v[136:137]
	ds_read_b128 v[20:23], v128 offset:8976
	s_waitcnt lgkmcnt(12)
	v_pk_fma_f32 v[240:241], v[28:29], v[88:89], v[240:241]
	v_pk_fma_f32 v[240:241], v[30:31], v[90:91], v[240:241]
	ds_read_b128 v[24:27], v128 offset:8224
	s_waitcnt lgkmcnt(12)
	v_pk_fma_f32 v[242:243], v[32:33], v[88:89], v[242:243]
	v_pk_fma_f32 v[242:243], v[34:35], v[90:91], v[242:243]
	ds_read_b128 v[28:31], v128 offset:8480
	s_waitcnt lgkmcnt(12)
	v_mov_b32_e32 v129, v36
	ds_read_b128 v[32:35], v128 offset:8736
	s_waitcnt lgkmcnt(12)
	v_mov_b32_e32 v132, v40
	v_mov_b32_e32 v239, v41
	ds_read_b128 v[36:39], v128 offset:8992
	s_waitcnt lgkmcnt(12)
	v_mov_b32_e32 v249, v44
	v_mov_b32_e32 v6, v45
	v_mov_b32_e32 v7, v46
	v_add_f32_e32 v134, v134, v135
	v_add_f32_e32 v136, v136, v137
	v_add_f32_e32 v240, v240, v241
	v_add_f32_e32 v242, v242, v243
	v_add_f32_e32 v92, v92, v134
	v_add_f32_e32 v93, v93, v136
	v_add_f32_e32 v94, v94, v240
	v_add_f32_e32 v95, v95, v242
	v_fmac_f32_e32 v93, v129, v92
	v_fmac_f32_e32 v94, v132, v92
	v_fmac_f32_e32 v95, v249, v92
	v_fmac_f32_e32 v94, v239, v93
	v_fmac_f32_e32 v95, v6, v93
	v_fmac_f32_e32 v95, v7, v94
	ds_read_b128 v[40:43], v128 offset:8240
	s_waitcnt lgkmcnt(12)
	v_pk_mul_f32 v[134:135], v[48:49], v[64:65]
	v_pk_fma_f32 v[134:135], v[50:51], v[66:67], v[134:135]
	ds_read_b128 v[44:47], v128 offset:8496
	s_waitcnt lgkmcnt(12)
	v_pk_mul_f32 v[136:137], v[52:53], v[64:65]
	v_pk_fma_f32 v[136:137], v[54:55], v[66:67], v[136:137]
	ds_read_b128 v[48:51], v128 offset:8752
	s_waitcnt lgkmcnt(12)
	v_pk_mul_f32 v[240:241], v[56:57], v[64:65]
	v_pk_fma_f32 v[240:241], v[58:59], v[66:67], v[240:241]
	ds_read_b128 v[52:55], v128 offset:9008
	s_waitcnt lgkmcnt(12)
	v_pk_mul_f32 v[242:243], v[60:61], v[64:65]
	v_pk_fma_f32 v[242:243], v[62:63], v[66:67], v[242:243]
	ds_read_b128 v[56:59], v128 offset:8256
	s_waitcnt lgkmcnt(12)
	v_pk_fma_f32 v[134:135], v[8:9], v[68:69], v[134:135]
	v_pk_fma_f32 v[134:135], v[10:11], v[70:71], v[134:135]
	ds_read_b128 v[60:63], v128 offset:8512
	s_waitcnt lgkmcnt(12)
	v_pk_fma_f32 v[136:137], v[12:13], v[68:69], v[136:137]
	v_pk_fma_f32 v[136:137], v[14:15], v[70:71], v[136:137]
	ds_read_b128 v[8:11], v128 offset:8768
	s_waitcnt lgkmcnt(12)
	v_pk_fma_f32 v[240:241], v[16:17], v[68:69], v[240:241]
	v_pk_fma_f32 v[240:241], v[18:19], v[70:71], v[240:241]
	ds_read_b128 v[12:15], v128 offset:9024
	s_waitcnt lgkmcnt(12)
	v_pk_fma_f32 v[242:243], v[20:21], v[68:69], v[242:243]
	v_pk_fma_f32 v[242:243], v[22:23], v[70:71], v[242:243]
	ds_read_b128 v[16:19], v128 offset:8272
	s_waitcnt lgkmcnt(12)
	v_pk_fma_f32 v[134:135], v[24:25], v[72:73], v[134:135]
	v_pk_fma_f32 v[134:135], v[26:27], v[74:75], v[134:135]
	ds_read_b128 v[20:23], v128 offset:8528
	s_waitcnt lgkmcnt(12)
	v_pk_fma_f32 v[136:137], v[28:29], v[72:73], v[136:137]
	v_pk_fma_f32 v[136:137], v[30:31], v[74:75], v[136:137]
	ds_read_b128 v[24:27], v128 offset:8784
	s_waitcnt lgkmcnt(12)
	v_pk_fma_f32 v[240:241], v[32:33], v[72:73], v[240:241]
	v_pk_fma_f32 v[240:241], v[34:35], v[74:75], v[240:241]
	ds_read_b128 v[28:31], v128 offset:9040
	s_waitcnt lgkmcnt(12)
	v_pk_fma_f32 v[242:243], v[36:37], v[72:73], v[242:243]
	v_pk_fma_f32 v[242:243], v[38:39], v[74:75], v[242:243]
	ds_read_b128 v[32:35], v128 offset:8288
	s_waitcnt lgkmcnt(12)
	v_pk_fma_f32 v[134:135], v[40:41], v[76:77], v[134:135]
	v_pk_fma_f32 v[134:135], v[42:43], v[78:79], v[134:135]
	ds_read_b128 v[36:39], v128 offset:8544
	s_waitcnt lgkmcnt(12)
	v_pk_fma_f32 v[136:137], v[44:45], v[76:77], v[136:137]
	v_pk_fma_f32 v[136:137], v[46:47], v[78:79], v[136:137]
	ds_read_b128 v[40:43], v128 offset:8800
	s_waitcnt lgkmcnt(12)
	v_pk_fma_f32 v[240:241], v[48:49], v[76:77], v[240:241]
	v_pk_fma_f32 v[240:241], v[50:51], v[78:79], v[240:241]
	ds_read_b128 v[44:47], v128 offset:9056
	s_waitcnt lgkmcnt(12)
	v_pk_fma_f32 v[242:243], v[52:53], v[76:77], v[242:243]
	v_pk_fma_f32 v[242:243], v[54:55], v[78:79], v[242:243]
	ds_read_b128 v[48:51], v128 offset:8304
	s_waitcnt lgkmcnt(12)
	v_pk_fma_f32 v[134:135], v[56:57], v[80:81], v[134:135]
	v_pk_fma_f32 v[134:135], v[58:59], v[82:83], v[134:135]
	ds_read_b128 v[52:55], v128 offset:8560
	s_waitcnt lgkmcnt(12)
	v_pk_fma_f32 v[136:137], v[60:61], v[80:81], v[136:137]
	v_pk_fma_f32 v[136:137], v[62:63], v[82:83], v[136:137]
	ds_read_b128 v[56:59], v128 offset:8816
	s_waitcnt lgkmcnt(12)
	v_pk_fma_f32 v[240:241], v[8:9], v[80:81], v[240:241]
	v_pk_fma_f32 v[240:241], v[10:11], v[82:83], v[240:241]
	ds_read_b128 v[60:63], v128 offset:9072
	s_waitcnt lgkmcnt(12)
	v_pk_fma_f32 v[242:243], v[12:13], v[80:81], v[242:243]
	v_pk_fma_f32 v[242:243], v[14:15], v[82:83], v[242:243]
	ds_read_b128 v[8:11], v128 offset:8576
	s_waitcnt lgkmcnt(12)
	v_pk_fma_f32 v[134:135], v[16:17], v[84:85], v[134:135]
	v_pk_fma_f32 v[134:135], v[18:19], v[86:87], v[134:135]
	ds_read_b128 v[12:15], v128 offset:8832
	s_waitcnt lgkmcnt(12)
	v_pk_fma_f32 v[136:137], v[20:21], v[84:85], v[136:137]
	v_pk_fma_f32 v[136:137], v[22:23], v[86:87], v[136:137]
	ds_read_b128 v[16:19], v128 offset:9088
	s_waitcnt lgkmcnt(12)
	v_pk_fma_f32 v[240:241], v[24:25], v[84:85], v[240:241]
	v_pk_fma_f32 v[240:241], v[26:27], v[86:87], v[240:241]
	ds_read_b128 v[20:23], v128 offset:9216
	s_waitcnt lgkmcnt(12)
	v_pk_fma_f32 v[242:243], v[28:29], v[84:85], v[242:243]
	v_pk_fma_f32 v[242:243], v[30:31], v[86:87], v[242:243]
	ds_read_b128 v[24:27], v128 offset:9472
	s_waitcnt lgkmcnt(12)
	v_pk_fma_f32 v[134:135], v[32:33], v[88:89], v[134:135]
	v_pk_fma_f32 v[134:135], v[34:35], v[90:91], v[134:135]
	ds_read_b128 v[28:31], v128 offset:9728
	s_waitcnt lgkmcnt(12)
	v_pk_fma_f32 v[136:137], v[36:37], v[88:89], v[136:137]
	v_pk_fma_f32 v[136:137], v[38:39], v[90:91], v[136:137]
	ds_read_b128 v[32:35], v128 offset:9984
	s_waitcnt lgkmcnt(12)
	v_pk_fma_f32 v[240:241], v[40:41], v[88:89], v[240:241]
	v_pk_fma_f32 v[240:241], v[42:43], v[90:91], v[240:241]
	ds_read_b128 v[36:39], v128 offset:9232
	s_waitcnt lgkmcnt(12)
	v_pk_fma_f32 v[242:243], v[44:45], v[88:89], v[242:243]
	v_pk_fma_f32 v[242:243], v[46:47], v[90:91], v[242:243]
	ds_read_b128 v[40:43], v128 offset:9488
	s_waitcnt lgkmcnt(12)
	v_pk_fma_f32 v[134:135], v[48:49], v[92:93], v[134:135]
	v_pk_fma_f32 v[134:135], v[50:51], v[94:95], v[134:135]
	ds_read_b128 v[44:47], v128 offset:9744
	s_waitcnt lgkmcnt(12)
	v_pk_fma_f32 v[136:137], v[52:53], v[92:93], v[136:137]
	v_pk_fma_f32 v[136:137], v[54:55], v[94:95], v[136:137]
	ds_read_b128 v[48:51], v128 offset:10000
	s_waitcnt lgkmcnt(12)
	v_pk_fma_f32 v[240:241], v[56:57], v[92:93], v[240:241]
	v_pk_fma_f32 v[240:241], v[58:59], v[94:95], v[240:241]
	ds_read_b128 v[52:55], v128 offset:9248
	s_waitcnt lgkmcnt(12)
	v_pk_fma_f32 v[242:243], v[60:61], v[92:93], v[242:243]
	v_pk_fma_f32 v[242:243], v[62:63], v[94:95], v[242:243]
	ds_read_b128 v[56:59], v128 offset:9504
	s_waitcnt lgkmcnt(12)
	v_mov_b32_e32 v129, v8
	ds_read_b128 v[60:63], v128 offset:9760
	s_waitcnt lgkmcnt(12)
	v_mov_b32_e32 v132, v12
	v_mov_b32_e32 v239, v13
	ds_read_b128 v[8:11], v128 offset:10016
	s_waitcnt lgkmcnt(12)
	v_mov_b32_e32 v249, v16
	v_mov_b32_e32 v6, v17
	v_mov_b32_e32 v7, v18
	v_add_f32_e32 v134, v134, v135
	v_add_f32_e32 v136, v136, v137
	v_add_f32_e32 v240, v240, v241
	v_add_f32_e32 v242, v242, v243
	v_add_f32_e32 v96, v96, v134
	v_add_f32_e32 v97, v97, v136
	v_add_f32_e32 v98, v98, v240
	v_add_f32_e32 v99, v99, v242
	v_fmac_f32_e32 v97, v129, v96
	v_fmac_f32_e32 v98, v132, v96
	v_fmac_f32_e32 v99, v249, v96
	v_fmac_f32_e32 v98, v239, v97
	v_fmac_f32_e32 v99, v6, v97
	v_fmac_f32_e32 v99, v7, v98
	ds_read_b128 v[12:15], v128 offset:9264
	s_waitcnt lgkmcnt(12)
	v_pk_mul_f32 v[134:135], v[20:21], v[64:65]
	v_pk_fma_f32 v[134:135], v[22:23], v[66:67], v[134:135]
	ds_read_b128 v[16:19], v128 offset:9520
	s_waitcnt lgkmcnt(12)
	v_pk_mul_f32 v[136:137], v[24:25], v[64:65]
	v_pk_fma_f32 v[136:137], v[26:27], v[66:67], v[136:137]
	ds_read_b128 v[20:23], v128 offset:9776
	s_waitcnt lgkmcnt(12)
	v_pk_mul_f32 v[240:241], v[28:29], v[64:65]
	v_pk_fma_f32 v[240:241], v[30:31], v[66:67], v[240:241]
	ds_read_b128 v[24:27], v128 offset:10032
	s_waitcnt lgkmcnt(12)
	v_pk_mul_f32 v[242:243], v[32:33], v[64:65]
	v_pk_fma_f32 v[242:243], v[34:35], v[66:67], v[242:243]
	ds_read_b128 v[28:31], v128 offset:9280
	s_waitcnt lgkmcnt(12)
	v_pk_fma_f32 v[134:135], v[36:37], v[68:69], v[134:135]
	v_pk_fma_f32 v[134:135], v[38:39], v[70:71], v[134:135]
	ds_read_b128 v[32:35], v128 offset:9536
	s_waitcnt lgkmcnt(12)
	v_pk_fma_f32 v[136:137], v[40:41], v[68:69], v[136:137]
	v_pk_fma_f32 v[136:137], v[42:43], v[70:71], v[136:137]
	ds_read_b128 v[36:39], v128 offset:9792
	s_waitcnt lgkmcnt(12)
	v_pk_fma_f32 v[240:241], v[44:45], v[68:69], v[240:241]
	v_pk_fma_f32 v[240:241], v[46:47], v[70:71], v[240:241]
	ds_read_b128 v[40:43], v128 offset:10048
	s_waitcnt lgkmcnt(12)
	v_pk_fma_f32 v[242:243], v[48:49], v[68:69], v[242:243]
	v_pk_fma_f32 v[242:243], v[50:51], v[70:71], v[242:243]
	ds_read_b128 v[44:47], v128 offset:9296
	s_waitcnt lgkmcnt(12)
	v_pk_fma_f32 v[134:135], v[52:53], v[72:73], v[134:135]
	v_pk_fma_f32 v[134:135], v[54:55], v[74:75], v[134:135]
	ds_read_b128 v[48:51], v128 offset:9552
	s_waitcnt lgkmcnt(12)
	v_pk_fma_f32 v[136:137], v[56:57], v[72:73], v[136:137]
	v_pk_fma_f32 v[136:137], v[58:59], v[74:75], v[136:137]
	ds_read_b128 v[52:55], v128 offset:9808
	s_waitcnt lgkmcnt(12)
	v_pk_fma_f32 v[240:241], v[60:61], v[72:73], v[240:241]
	v_pk_fma_f32 v[240:241], v[62:63], v[74:75], v[240:241]
	ds_read_b128 v[56:59], v128 offset:10064
	s_waitcnt lgkmcnt(12)
	v_pk_fma_f32 v[242:243], v[8:9], v[72:73], v[242:243]
	v_pk_fma_f32 v[242:243], v[10:11], v[74:75], v[242:243]
	ds_read_b128 v[60:63], v128 offset:9312
	s_waitcnt lgkmcnt(12)
	v_pk_fma_f32 v[134:135], v[12:13], v[76:77], v[134:135]
	v_pk_fma_f32 v[134:135], v[14:15], v[78:79], v[134:135]
	ds_read_b128 v[8:11], v128 offset:9568
	s_waitcnt lgkmcnt(12)
	v_pk_fma_f32 v[136:137], v[16:17], v[76:77], v[136:137]
	v_pk_fma_f32 v[136:137], v[18:19], v[78:79], v[136:137]
	ds_read_b128 v[12:15], v128 offset:9824
	s_waitcnt lgkmcnt(12)
	v_pk_fma_f32 v[240:241], v[20:21], v[76:77], v[240:241]
	v_pk_fma_f32 v[240:241], v[22:23], v[78:79], v[240:241]
	ds_read_b128 v[16:19], v128 offset:10080
	s_waitcnt lgkmcnt(12)
	v_pk_fma_f32 v[242:243], v[24:25], v[76:77], v[242:243]
	v_pk_fma_f32 v[242:243], v[26:27], v[78:79], v[242:243]
	ds_read_b128 v[20:23], v128 offset:9328
	s_waitcnt lgkmcnt(12)
	v_pk_fma_f32 v[134:135], v[28:29], v[80:81], v[134:135]
	v_pk_fma_f32 v[134:135], v[30:31], v[82:83], v[134:135]
	ds_read_b128 v[24:27], v128 offset:9584
	s_waitcnt lgkmcnt(12)
	v_pk_fma_f32 v[136:137], v[32:33], v[80:81], v[136:137]
	v_pk_fma_f32 v[136:137], v[34:35], v[82:83], v[136:137]
	ds_read_b128 v[28:31], v128 offset:9840
	s_waitcnt lgkmcnt(12)
	v_pk_fma_f32 v[240:241], v[36:37], v[80:81], v[240:241]
	v_pk_fma_f32 v[240:241], v[38:39], v[82:83], v[240:241]
	ds_read_b128 v[32:35], v128 offset:10096
	s_waitcnt lgkmcnt(12)
	v_pk_fma_f32 v[242:243], v[40:41], v[80:81], v[242:243]
	v_pk_fma_f32 v[242:243], v[42:43], v[82:83], v[242:243]
	ds_read_b128 v[36:39], v128 offset:9344
	s_waitcnt lgkmcnt(12)
	v_pk_fma_f32 v[134:135], v[44:45], v[84:85], v[134:135]
	v_pk_fma_f32 v[134:135], v[46:47], v[86:87], v[134:135]
	ds_read_b128 v[40:43], v128 offset:9600
	s_waitcnt lgkmcnt(12)
	v_pk_fma_f32 v[136:137], v[48:49], v[84:85], v[136:137]
	v_pk_fma_f32 v[136:137], v[50:51], v[86:87], v[136:137]
	ds_read_b128 v[44:47], v128 offset:9856
	s_waitcnt lgkmcnt(12)
	v_pk_fma_f32 v[240:241], v[52:53], v[84:85], v[240:241]
	v_pk_fma_f32 v[240:241], v[54:55], v[86:87], v[240:241]
	ds_read_b128 v[48:51], v128 offset:10112
	s_waitcnt lgkmcnt(12)
	v_pk_fma_f32 v[242:243], v[56:57], v[84:85], v[242:243]
	v_pk_fma_f32 v[242:243], v[58:59], v[86:87], v[242:243]
	ds_read_b128 v[52:55], v128 offset:9616
	s_waitcnt lgkmcnt(12)
	v_pk_fma_f32 v[134:135], v[60:61], v[88:89], v[134:135]
	v_pk_fma_f32 v[134:135], v[62:63], v[90:91], v[134:135]
	ds_read_b128 v[56:59], v128 offset:9872
	s_waitcnt lgkmcnt(12)
	v_pk_fma_f32 v[136:137], v[8:9], v[88:89], v[136:137]
	v_pk_fma_f32 v[136:137], v[10:11], v[90:91], v[136:137]
	ds_read_b128 v[60:63], v128 offset:10128
	s_waitcnt lgkmcnt(12)
	v_pk_fma_f32 v[240:241], v[12:13], v[88:89], v[240:241]
	v_pk_fma_f32 v[240:241], v[14:15], v[90:91], v[240:241]
	ds_read_b128 v[8:11], v128 offset:10240
	s_waitcnt lgkmcnt(12)
	v_pk_fma_f32 v[242:243], v[16:17], v[88:89], v[242:243]
	v_pk_fma_f32 v[242:243], v[18:19], v[90:91], v[242:243]
	ds_read_b128 v[12:15], v128 offset:10496
	s_waitcnt lgkmcnt(12)
	v_pk_fma_f32 v[134:135], v[20:21], v[92:93], v[134:135]
	v_pk_fma_f32 v[134:135], v[22:23], v[94:95], v[134:135]
	ds_read_b128 v[16:19], v128 offset:10752
	s_waitcnt lgkmcnt(12)
	v_pk_fma_f32 v[136:137], v[24:25], v[92:93], v[136:137]
	v_pk_fma_f32 v[136:137], v[26:27], v[94:95], v[136:137]
	ds_read_b128 v[20:23], v128 offset:11008
	s_waitcnt lgkmcnt(12)
	v_pk_fma_f32 v[240:241], v[28:29], v[92:93], v[240:241]
	v_pk_fma_f32 v[240:241], v[30:31], v[94:95], v[240:241]
	ds_read_b128 v[24:27], v128 offset:10256
	s_waitcnt lgkmcnt(12)
	v_pk_fma_f32 v[242:243], v[32:33], v[92:93], v[242:243]
	v_pk_fma_f32 v[242:243], v[34:35], v[94:95], v[242:243]
	ds_read_b128 v[28:31], v128 offset:10512
	s_waitcnt lgkmcnt(12)
	v_pk_fma_f32 v[134:135], v[36:37], v[96:97], v[134:135]
	v_pk_fma_f32 v[134:135], v[38:39], v[98:99], v[134:135]
	ds_read_b128 v[32:35], v128 offset:10768
	s_waitcnt lgkmcnt(12)
	v_pk_fma_f32 v[136:137], v[40:41], v[96:97], v[136:137]
	v_pk_fma_f32 v[136:137], v[42:43], v[98:99], v[136:137]
	ds_read_b128 v[36:39], v128 offset:11024
	s_waitcnt lgkmcnt(12)
	v_pk_fma_f32 v[240:241], v[44:45], v[96:97], v[240:241]
	v_pk_fma_f32 v[240:241], v[46:47], v[98:99], v[240:241]
	ds_read_b128 v[40:43], v128 offset:10272
	s_waitcnt lgkmcnt(12)
	v_pk_fma_f32 v[242:243], v[48:49], v[96:97], v[242:243]
	v_pk_fma_f32 v[242:243], v[50:51], v[98:99], v[242:243]
	ds_read_b128 v[44:47], v128 offset:10528
	s_waitcnt lgkmcnt(12)
	v_mov_b32_e32 v129, v52
	ds_read_b128 v[48:51], v128 offset:10784
	s_waitcnt lgkmcnt(12)
	v_mov_b32_e32 v132, v56
	v_mov_b32_e32 v239, v57
	ds_read_b128 v[52:55], v128 offset:11040
	s_waitcnt lgkmcnt(12)
	v_mov_b32_e32 v249, v60
	v_mov_b32_e32 v6, v61
	v_mov_b32_e32 v7, v62
	v_add_f32_e32 v134, v134, v135
	v_add_f32_e32 v136, v136, v137
	v_add_f32_e32 v240, v240, v241
	v_add_f32_e32 v242, v242, v243
	v_add_f32_e32 v100, v100, v134
	v_add_f32_e32 v101, v101, v136
	v_add_f32_e32 v102, v102, v240
	v_add_f32_e32 v103, v103, v242
	v_fmac_f32_e32 v101, v129, v100
	v_fmac_f32_e32 v102, v132, v100
	v_fmac_f32_e32 v103, v249, v100
	v_fmac_f32_e32 v102, v239, v101
	v_fmac_f32_e32 v103, v6, v101
	v_fmac_f32_e32 v103, v7, v102
	ds_read_b128 v[56:59], v128 offset:10288
	s_waitcnt lgkmcnt(12)
	v_pk_mul_f32 v[134:135], v[8:9], v[64:65]
	v_pk_fma_f32 v[134:135], v[10:11], v[66:67], v[134:135]
	ds_read_b128 v[60:63], v128 offset:10544
	s_waitcnt lgkmcnt(12)
	v_pk_mul_f32 v[136:137], v[12:13], v[64:65]
	v_pk_fma_f32 v[136:137], v[14:15], v[66:67], v[136:137]
	ds_read_b128 v[8:11], v128 offset:10800
	s_waitcnt lgkmcnt(12)
	v_pk_mul_f32 v[240:241], v[16:17], v[64:65]
	v_pk_fma_f32 v[240:241], v[18:19], v[66:67], v[240:241]
	ds_read_b128 v[12:15], v128 offset:11056
	s_waitcnt lgkmcnt(12)
	v_pk_mul_f32 v[242:243], v[20:21], v[64:65]
	v_pk_fma_f32 v[242:243], v[22:23], v[66:67], v[242:243]
	ds_read_b128 v[16:19], v128 offset:10304
	s_waitcnt lgkmcnt(12)
	v_pk_fma_f32 v[134:135], v[24:25], v[68:69], v[134:135]
	v_pk_fma_f32 v[134:135], v[26:27], v[70:71], v[134:135]
	ds_read_b128 v[20:23], v128 offset:10560
	s_waitcnt lgkmcnt(12)
	v_pk_fma_f32 v[136:137], v[28:29], v[68:69], v[136:137]
	v_pk_fma_f32 v[136:137], v[30:31], v[70:71], v[136:137]
	ds_read_b128 v[24:27], v128 offset:10816
	s_waitcnt lgkmcnt(12)
	v_pk_fma_f32 v[240:241], v[32:33], v[68:69], v[240:241]
	v_pk_fma_f32 v[240:241], v[34:35], v[70:71], v[240:241]
	ds_read_b128 v[28:31], v128 offset:11072
	s_waitcnt lgkmcnt(12)
	v_pk_fma_f32 v[242:243], v[36:37], v[68:69], v[242:243]
	v_pk_fma_f32 v[242:243], v[38:39], v[70:71], v[242:243]
	ds_read_b128 v[32:35], v128 offset:10320
	s_waitcnt lgkmcnt(12)
	v_pk_fma_f32 v[134:135], v[40:41], v[72:73], v[134:135]
	v_pk_fma_f32 v[134:135], v[42:43], v[74:75], v[134:135]
	ds_read_b128 v[36:39], v128 offset:10576
	s_waitcnt lgkmcnt(12)
	v_pk_fma_f32 v[136:137], v[44:45], v[72:73], v[136:137]
	v_pk_fma_f32 v[136:137], v[46:47], v[74:75], v[136:137]
	ds_read_b128 v[40:43], v128 offset:10832
	s_waitcnt lgkmcnt(12)
	v_pk_fma_f32 v[240:241], v[48:49], v[72:73], v[240:241]
	v_pk_fma_f32 v[240:241], v[50:51], v[74:75], v[240:241]
	ds_read_b128 v[44:47], v128 offset:11088
	s_waitcnt lgkmcnt(12)
	v_pk_fma_f32 v[242:243], v[52:53], v[72:73], v[242:243]
	v_pk_fma_f32 v[242:243], v[54:55], v[74:75], v[242:243]
	ds_read_b128 v[48:51], v128 offset:10336
	s_waitcnt lgkmcnt(12)
	v_pk_fma_f32 v[134:135], v[56:57], v[76:77], v[134:135]
	v_pk_fma_f32 v[134:135], v[58:59], v[78:79], v[134:135]
	ds_read_b128 v[52:55], v128 offset:10592
	s_waitcnt lgkmcnt(12)
	v_pk_fma_f32 v[136:137], v[60:61], v[76:77], v[136:137]
	v_pk_fma_f32 v[136:137], v[62:63], v[78:79], v[136:137]
	ds_read_b128 v[56:59], v128 offset:10848
	s_waitcnt lgkmcnt(12)
	v_pk_fma_f32 v[240:241], v[8:9], v[76:77], v[240:241]
	v_pk_fma_f32 v[240:241], v[10:11], v[78:79], v[240:241]
	ds_read_b128 v[60:63], v128 offset:11104
	s_waitcnt lgkmcnt(12)
	v_pk_fma_f32 v[242:243], v[12:13], v[76:77], v[242:243]
	v_pk_fma_f32 v[242:243], v[14:15], v[78:79], v[242:243]
	ds_read_b128 v[8:11], v128 offset:10352
	s_waitcnt lgkmcnt(12)
	v_pk_fma_f32 v[134:135], v[16:17], v[80:81], v[134:135]
	v_pk_fma_f32 v[134:135], v[18:19], v[82:83], v[134:135]
	ds_read_b128 v[12:15], v128 offset:10608
	s_waitcnt lgkmcnt(12)
	v_pk_fma_f32 v[136:137], v[20:21], v[80:81], v[136:137]
	v_pk_fma_f32 v[136:137], v[22:23], v[82:83], v[136:137]
	ds_read_b128 v[16:19], v128 offset:10864
	s_waitcnt lgkmcnt(12)
	v_pk_fma_f32 v[240:241], v[24:25], v[80:81], v[240:241]
	v_pk_fma_f32 v[240:241], v[26:27], v[82:83], v[240:241]
	ds_read_b128 v[20:23], v128 offset:11120
	s_waitcnt lgkmcnt(12)
	v_pk_fma_f32 v[242:243], v[28:29], v[80:81], v[242:243]
	v_pk_fma_f32 v[242:243], v[30:31], v[82:83], v[242:243]
	ds_read_b128 v[24:27], v128 offset:10368
	s_waitcnt lgkmcnt(12)
	v_pk_fma_f32 v[134:135], v[32:33], v[84:85], v[134:135]
	v_pk_fma_f32 v[134:135], v[34:35], v[86:87], v[134:135]
	ds_read_b128 v[28:31], v128 offset:10624
	s_waitcnt lgkmcnt(12)
	v_pk_fma_f32 v[136:137], v[36:37], v[84:85], v[136:137]
	v_pk_fma_f32 v[136:137], v[38:39], v[86:87], v[136:137]
	ds_read_b128 v[32:35], v128 offset:10880
	s_waitcnt lgkmcnt(12)
	v_pk_fma_f32 v[240:241], v[40:41], v[84:85], v[240:241]
	v_pk_fma_f32 v[240:241], v[42:43], v[86:87], v[240:241]
	ds_read_b128 v[36:39], v128 offset:11136
	s_waitcnt lgkmcnt(12)
	v_pk_fma_f32 v[242:243], v[44:45], v[84:85], v[242:243]
	v_pk_fma_f32 v[242:243], v[46:47], v[86:87], v[242:243]
	ds_read_b128 v[40:43], v128 offset:10384
	s_waitcnt lgkmcnt(12)
	v_pk_fma_f32 v[134:135], v[48:49], v[88:89], v[134:135]
	v_pk_fma_f32 v[134:135], v[50:51], v[90:91], v[134:135]
	ds_read_b128 v[44:47], v128 offset:10640
	s_waitcnt lgkmcnt(12)
	v_pk_fma_f32 v[136:137], v[52:53], v[88:89], v[136:137]
	v_pk_fma_f32 v[136:137], v[54:55], v[90:91], v[136:137]
	ds_read_b128 v[48:51], v128 offset:10896
	s_waitcnt lgkmcnt(12)
	v_pk_fma_f32 v[240:241], v[56:57], v[88:89], v[240:241]
	v_pk_fma_f32 v[240:241], v[58:59], v[90:91], v[240:241]
	ds_read_b128 v[52:55], v128 offset:11152
	s_waitcnt lgkmcnt(12)
	v_pk_fma_f32 v[242:243], v[60:61], v[88:89], v[242:243]
	v_pk_fma_f32 v[242:243], v[62:63], v[90:91], v[242:243]
	ds_read_b128 v[56:59], v128 offset:10656
	s_waitcnt lgkmcnt(12)
	v_pk_fma_f32 v[134:135], v[8:9], v[92:93], v[134:135]
	v_pk_fma_f32 v[134:135], v[10:11], v[94:95], v[134:135]
	ds_read_b128 v[60:63], v128 offset:10912
	s_waitcnt lgkmcnt(12)
	v_pk_fma_f32 v[136:137], v[12:13], v[92:93], v[136:137]
	v_pk_fma_f32 v[136:137], v[14:15], v[94:95], v[136:137]
	ds_read_b128 v[8:11], v128 offset:11168
	s_waitcnt lgkmcnt(12)
	v_pk_fma_f32 v[240:241], v[16:17], v[92:93], v[240:241]
	v_pk_fma_f32 v[240:241], v[18:19], v[94:95], v[240:241]
	ds_read_b128 v[12:15], v128 offset:11264
	s_waitcnt lgkmcnt(12)
	v_pk_fma_f32 v[242:243], v[20:21], v[92:93], v[242:243]
	v_pk_fma_f32 v[242:243], v[22:23], v[94:95], v[242:243]
	ds_read_b128 v[16:19], v128 offset:11520
	s_waitcnt lgkmcnt(12)
	v_pk_fma_f32 v[134:135], v[24:25], v[96:97], v[134:135]
	v_pk_fma_f32 v[134:135], v[26:27], v[98:99], v[134:135]
	ds_read_b128 v[20:23], v128 offset:11776
	s_waitcnt lgkmcnt(12)
	v_pk_fma_f32 v[136:137], v[28:29], v[96:97], v[136:137]
	v_pk_fma_f32 v[136:137], v[30:31], v[98:99], v[136:137]
	ds_read_b128 v[24:27], v128 offset:12032
	s_waitcnt lgkmcnt(12)
	v_pk_fma_f32 v[240:241], v[32:33], v[96:97], v[240:241]
	v_pk_fma_f32 v[240:241], v[34:35], v[98:99], v[240:241]
	ds_read_b128 v[28:31], v128 offset:11280
	s_waitcnt lgkmcnt(12)
	v_pk_fma_f32 v[242:243], v[36:37], v[96:97], v[242:243]
	v_pk_fma_f32 v[242:243], v[38:39], v[98:99], v[242:243]
	ds_read_b128 v[32:35], v128 offset:11536
	s_waitcnt lgkmcnt(12)
	v_pk_fma_f32 v[134:135], v[40:41], v[100:101], v[134:135]
	v_pk_fma_f32 v[134:135], v[42:43], v[102:103], v[134:135]
	ds_read_b128 v[36:39], v128 offset:11792
	s_waitcnt lgkmcnt(12)
	v_pk_fma_f32 v[136:137], v[44:45], v[100:101], v[136:137]
	v_pk_fma_f32 v[136:137], v[46:47], v[102:103], v[136:137]
	ds_read_b128 v[40:43], v128 offset:12048
	s_waitcnt lgkmcnt(12)
	v_pk_fma_f32 v[240:241], v[48:49], v[100:101], v[240:241]
	v_pk_fma_f32 v[240:241], v[50:51], v[102:103], v[240:241]
	ds_read_b128 v[44:47], v128 offset:11296
	s_waitcnt lgkmcnt(12)
	v_pk_fma_f32 v[242:243], v[52:53], v[100:101], v[242:243]
	v_pk_fma_f32 v[242:243], v[54:55], v[102:103], v[242:243]
	ds_read_b128 v[48:51], v128 offset:11552
	s_waitcnt lgkmcnt(12)
	v_mov_b32_e32 v129, v56
	ds_read_b128 v[52:55], v128 offset:11808
	s_waitcnt lgkmcnt(12)
	v_mov_b32_e32 v132, v60
	v_mov_b32_e32 v239, v61
	ds_read_b128 v[56:59], v128 offset:12064
	s_waitcnt lgkmcnt(12)
	v_mov_b32_e32 v249, v8
	v_mov_b32_e32 v6, v9
	v_mov_b32_e32 v7, v10
	v_add_f32_e32 v134, v134, v135
	v_add_f32_e32 v136, v136, v137
	v_add_f32_e32 v240, v240, v241
	v_add_f32_e32 v242, v242, v243
	v_add_f32_e32 v104, v104, v134
	v_add_f32_e32 v105, v105, v136
	v_add_f32_e32 v106, v106, v240
	v_add_f32_e32 v107, v107, v242
	v_fmac_f32_e32 v105, v129, v104
	v_fmac_f32_e32 v106, v132, v104
	v_fmac_f32_e32 v107, v249, v104
	v_fmac_f32_e32 v106, v239, v105
	v_fmac_f32_e32 v107, v6, v105
	v_fmac_f32_e32 v107, v7, v106
	ds_read_b128 v[60:63], v128 offset:11312
	s_waitcnt lgkmcnt(12)
	v_pk_mul_f32 v[134:135], v[12:13], v[64:65]
	v_pk_fma_f32 v[134:135], v[14:15], v[66:67], v[134:135]
	ds_read_b128 v[8:11], v128 offset:11568
	s_waitcnt lgkmcnt(12)
	v_pk_mul_f32 v[136:137], v[16:17], v[64:65]
	v_pk_fma_f32 v[136:137], v[18:19], v[66:67], v[136:137]
	ds_read_b128 v[12:15], v128 offset:11824
	s_waitcnt lgkmcnt(12)
	v_pk_mul_f32 v[240:241], v[20:21], v[64:65]
	v_pk_fma_f32 v[240:241], v[22:23], v[66:67], v[240:241]
	ds_read_b128 v[16:19], v128 offset:12080
	s_waitcnt lgkmcnt(12)
	v_pk_mul_f32 v[242:243], v[24:25], v[64:65]
	v_pk_fma_f32 v[242:243], v[26:27], v[66:67], v[242:243]
	ds_read_b128 v[20:23], v128 offset:11328
	s_waitcnt lgkmcnt(12)
	v_pk_fma_f32 v[134:135], v[28:29], v[68:69], v[134:135]
	v_pk_fma_f32 v[134:135], v[30:31], v[70:71], v[134:135]
	ds_read_b128 v[24:27], v128 offset:11584
	s_waitcnt lgkmcnt(12)
	v_pk_fma_f32 v[136:137], v[32:33], v[68:69], v[136:137]
	v_pk_fma_f32 v[136:137], v[34:35], v[70:71], v[136:137]
	ds_read_b128 v[28:31], v128 offset:11840
	s_waitcnt lgkmcnt(12)
	v_pk_fma_f32 v[240:241], v[36:37], v[68:69], v[240:241]
	v_pk_fma_f32 v[240:241], v[38:39], v[70:71], v[240:241]
	ds_read_b128 v[32:35], v128 offset:12096
	s_waitcnt lgkmcnt(12)
	v_pk_fma_f32 v[242:243], v[40:41], v[68:69], v[242:243]
	v_pk_fma_f32 v[242:243], v[42:43], v[70:71], v[242:243]
	ds_read_b128 v[36:39], v128 offset:11344
	s_waitcnt lgkmcnt(12)
	v_pk_fma_f32 v[134:135], v[44:45], v[72:73], v[134:135]
	v_pk_fma_f32 v[134:135], v[46:47], v[74:75], v[134:135]
	ds_read_b128 v[40:43], v128 offset:11600
	s_waitcnt lgkmcnt(12)
	v_pk_fma_f32 v[136:137], v[48:49], v[72:73], v[136:137]
	v_pk_fma_f32 v[136:137], v[50:51], v[74:75], v[136:137]
	ds_read_b128 v[44:47], v128 offset:11856
	s_waitcnt lgkmcnt(12)
	v_pk_fma_f32 v[240:241], v[52:53], v[72:73], v[240:241]
	v_pk_fma_f32 v[240:241], v[54:55], v[74:75], v[240:241]
	ds_read_b128 v[48:51], v128 offset:12112
	s_waitcnt lgkmcnt(12)
	v_pk_fma_f32 v[242:243], v[56:57], v[72:73], v[242:243]
	v_pk_fma_f32 v[242:243], v[58:59], v[74:75], v[242:243]
	ds_read_b128 v[52:55], v128 offset:11360
	s_waitcnt lgkmcnt(12)
	v_pk_fma_f32 v[134:135], v[60:61], v[76:77], v[134:135]
	v_pk_fma_f32 v[134:135], v[62:63], v[78:79], v[134:135]
	ds_read_b128 v[56:59], v128 offset:11616
	s_waitcnt lgkmcnt(12)
	v_pk_fma_f32 v[136:137], v[8:9], v[76:77], v[136:137]
	v_pk_fma_f32 v[136:137], v[10:11], v[78:79], v[136:137]
	ds_read_b128 v[60:63], v128 offset:11872
	s_waitcnt lgkmcnt(12)
	v_pk_fma_f32 v[240:241], v[12:13], v[76:77], v[240:241]
	v_pk_fma_f32 v[240:241], v[14:15], v[78:79], v[240:241]
	ds_read_b128 v[8:11], v128 offset:12128
	s_waitcnt lgkmcnt(12)
	v_pk_fma_f32 v[242:243], v[16:17], v[76:77], v[242:243]
	v_pk_fma_f32 v[242:243], v[18:19], v[78:79], v[242:243]
	ds_read_b128 v[12:15], v128 offset:11376
	s_waitcnt lgkmcnt(12)
	v_pk_fma_f32 v[134:135], v[20:21], v[80:81], v[134:135]
	v_pk_fma_f32 v[134:135], v[22:23], v[82:83], v[134:135]
	ds_read_b128 v[16:19], v128 offset:11632
	s_waitcnt lgkmcnt(12)
	v_pk_fma_f32 v[136:137], v[24:25], v[80:81], v[136:137]
	v_pk_fma_f32 v[136:137], v[26:27], v[82:83], v[136:137]
	ds_read_b128 v[20:23], v128 offset:11888
	s_waitcnt lgkmcnt(12)
	v_pk_fma_f32 v[240:241], v[28:29], v[80:81], v[240:241]
	v_pk_fma_f32 v[240:241], v[30:31], v[82:83], v[240:241]
	ds_read_b128 v[24:27], v128 offset:12144
	s_waitcnt lgkmcnt(12)
	v_pk_fma_f32 v[242:243], v[32:33], v[80:81], v[242:243]
	v_pk_fma_f32 v[242:243], v[34:35], v[82:83], v[242:243]
	ds_read_b128 v[28:31], v128 offset:11392
	s_waitcnt lgkmcnt(12)
	v_pk_fma_f32 v[134:135], v[36:37], v[84:85], v[134:135]
	v_pk_fma_f32 v[134:135], v[38:39], v[86:87], v[134:135]
	ds_read_b128 v[32:35], v128 offset:11648
	s_waitcnt lgkmcnt(12)
	v_pk_fma_f32 v[136:137], v[40:41], v[84:85], v[136:137]
	v_pk_fma_f32 v[136:137], v[42:43], v[86:87], v[136:137]
	ds_read_b128 v[36:39], v128 offset:11904
	s_waitcnt lgkmcnt(12)
	v_pk_fma_f32 v[240:241], v[44:45], v[84:85], v[240:241]
	v_pk_fma_f32 v[240:241], v[46:47], v[86:87], v[240:241]
	ds_read_b128 v[40:43], v128 offset:12160
	s_waitcnt lgkmcnt(12)
	v_pk_fma_f32 v[242:243], v[48:49], v[84:85], v[242:243]
	v_pk_fma_f32 v[242:243], v[50:51], v[86:87], v[242:243]
	ds_read_b128 v[44:47], v128 offset:11408
	s_waitcnt lgkmcnt(12)
	v_pk_fma_f32 v[134:135], v[52:53], v[88:89], v[134:135]
	v_pk_fma_f32 v[134:135], v[54:55], v[90:91], v[134:135]
	ds_read_b128 v[48:51], v128 offset:11664
	s_waitcnt lgkmcnt(12)
	v_pk_fma_f32 v[136:137], v[56:57], v[88:89], v[136:137]
	v_pk_fma_f32 v[136:137], v[58:59], v[90:91], v[136:137]
	ds_read_b128 v[52:55], v128 offset:11920
	s_waitcnt lgkmcnt(12)
	v_pk_fma_f32 v[240:241], v[60:61], v[88:89], v[240:241]
	v_pk_fma_f32 v[240:241], v[62:63], v[90:91], v[240:241]
	ds_read_b128 v[56:59], v128 offset:12176
	s_waitcnt lgkmcnt(12)
	v_pk_fma_f32 v[242:243], v[8:9], v[88:89], v[242:243]
	v_pk_fma_f32 v[242:243], v[10:11], v[90:91], v[242:243]
	ds_read_b128 v[60:63], v128 offset:11424
	s_waitcnt lgkmcnt(12)
	v_pk_fma_f32 v[134:135], v[12:13], v[92:93], v[134:135]
	v_pk_fma_f32 v[134:135], v[14:15], v[94:95], v[134:135]
	ds_read_b128 v[8:11], v128 offset:11680
	s_waitcnt lgkmcnt(12)
	v_pk_fma_f32 v[136:137], v[16:17], v[92:93], v[136:137]
	v_pk_fma_f32 v[136:137], v[18:19], v[94:95], v[136:137]
	ds_read_b128 v[12:15], v128 offset:11936
	s_waitcnt lgkmcnt(12)
	v_pk_fma_f32 v[240:241], v[20:21], v[92:93], v[240:241]
	v_pk_fma_f32 v[240:241], v[22:23], v[94:95], v[240:241]
	ds_read_b128 v[16:19], v128 offset:12192
	s_waitcnt lgkmcnt(12)
	v_pk_fma_f32 v[242:243], v[24:25], v[92:93], v[242:243]
	v_pk_fma_f32 v[242:243], v[26:27], v[94:95], v[242:243]
	ds_read_b128 v[20:23], v128 offset:11696
	s_waitcnt lgkmcnt(12)
	v_pk_fma_f32 v[134:135], v[28:29], v[96:97], v[134:135]
	v_pk_fma_f32 v[134:135], v[30:31], v[98:99], v[134:135]
	ds_read_b128 v[24:27], v128 offset:11952
	s_waitcnt lgkmcnt(12)
	v_pk_fma_f32 v[136:137], v[32:33], v[96:97], v[136:137]
	v_pk_fma_f32 v[136:137], v[34:35], v[98:99], v[136:137]
	ds_read_b128 v[28:31], v128 offset:12208
	s_waitcnt lgkmcnt(12)
	v_pk_fma_f32 v[240:241], v[36:37], v[96:97], v[240:241]
	v_pk_fma_f32 v[240:241], v[38:39], v[98:99], v[240:241]
	ds_read_b128 v[32:35], v128 offset:12288
	s_waitcnt lgkmcnt(12)
	v_pk_fma_f32 v[242:243], v[40:41], v[96:97], v[242:243]
	v_pk_fma_f32 v[242:243], v[42:43], v[98:99], v[242:243]
	ds_read_b128 v[36:39], v128 offset:12544
	s_waitcnt lgkmcnt(12)
	v_pk_fma_f32 v[134:135], v[44:45], v[100:101], v[134:135]
	v_pk_fma_f32 v[134:135], v[46:47], v[102:103], v[134:135]
	ds_read_b128 v[40:43], v128 offset:12800
	s_waitcnt lgkmcnt(12)
	v_pk_fma_f32 v[136:137], v[48:49], v[100:101], v[136:137]
	v_pk_fma_f32 v[136:137], v[50:51], v[102:103], v[136:137]
	ds_read_b128 v[44:47], v128 offset:13056
	s_waitcnt lgkmcnt(12)
	v_pk_fma_f32 v[240:241], v[52:53], v[100:101], v[240:241]
	v_pk_fma_f32 v[240:241], v[54:55], v[102:103], v[240:241]
	ds_read_b128 v[48:51], v128 offset:12304
	s_waitcnt lgkmcnt(12)
	v_pk_fma_f32 v[242:243], v[56:57], v[100:101], v[242:243]
	v_pk_fma_f32 v[242:243], v[58:59], v[102:103], v[242:243]
	ds_read_b128 v[52:55], v128 offset:12560
	s_waitcnt lgkmcnt(12)
	v_pk_fma_f32 v[134:135], v[60:61], v[104:105], v[134:135]
	v_pk_fma_f32 v[134:135], v[62:63], v[106:107], v[134:135]
	ds_read_b128 v[56:59], v128 offset:12816
	s_waitcnt lgkmcnt(12)
	v_pk_fma_f32 v[136:137], v[8:9], v[104:105], v[136:137]
	v_pk_fma_f32 v[136:137], v[10:11], v[106:107], v[136:137]
	ds_read_b128 v[60:63], v128 offset:13072
	s_waitcnt lgkmcnt(12)
	v_pk_fma_f32 v[240:241], v[12:13], v[104:105], v[240:241]
	v_pk_fma_f32 v[240:241], v[14:15], v[106:107], v[240:241]
	ds_read_b128 v[8:11], v128 offset:12320
	s_waitcnt lgkmcnt(12)
	v_pk_fma_f32 v[242:243], v[16:17], v[104:105], v[242:243]
	v_pk_fma_f32 v[242:243], v[18:19], v[106:107], v[242:243]
	ds_read_b128 v[12:15], v128 offset:12576
	s_waitcnt lgkmcnt(12)
	v_mov_b32_e32 v129, v20
	ds_read_b128 v[16:19], v128 offset:12832
	s_waitcnt lgkmcnt(12)
	v_mov_b32_e32 v132, v24
	v_mov_b32_e32 v239, v25
	ds_read_b128 v[20:23], v128 offset:13088
	s_waitcnt lgkmcnt(12)
	v_mov_b32_e32 v249, v28
	v_mov_b32_e32 v6, v29
	v_mov_b32_e32 v7, v30
	v_add_f32_e32 v134, v134, v135
	v_add_f32_e32 v136, v136, v137
	v_add_f32_e32 v240, v240, v241
	v_add_f32_e32 v242, v242, v243
	v_add_f32_e32 v108, v108, v134
	v_add_f32_e32 v109, v109, v136
	v_add_f32_e32 v110, v110, v240
	v_add_f32_e32 v111, v111, v242
	v_fmac_f32_e32 v109, v129, v108
	v_fmac_f32_e32 v110, v132, v108
	v_fmac_f32_e32 v111, v249, v108
	v_fmac_f32_e32 v110, v239, v109
	v_fmac_f32_e32 v111, v6, v109
	v_fmac_f32_e32 v111, v7, v110
	ds_read_b128 v[24:27], v128 offset:12336
	s_waitcnt lgkmcnt(12)
	v_pk_mul_f32 v[134:135], v[32:33], v[64:65]
	v_pk_fma_f32 v[134:135], v[34:35], v[66:67], v[134:135]
	ds_read_b128 v[28:31], v128 offset:12592
	s_waitcnt lgkmcnt(12)
	v_pk_mul_f32 v[136:137], v[36:37], v[64:65]
	v_pk_fma_f32 v[136:137], v[38:39], v[66:67], v[136:137]
	ds_read_b128 v[32:35], v128 offset:12848
	s_waitcnt lgkmcnt(12)
	v_pk_mul_f32 v[240:241], v[40:41], v[64:65]
	v_pk_fma_f32 v[240:241], v[42:43], v[66:67], v[240:241]
	ds_read_b128 v[36:39], v128 offset:13104
	s_waitcnt lgkmcnt(12)
	v_pk_mul_f32 v[242:243], v[44:45], v[64:65]
	v_pk_fma_f32 v[242:243], v[46:47], v[66:67], v[242:243]
	ds_read_b128 v[40:43], v128 offset:12352
	s_waitcnt lgkmcnt(12)
	v_pk_fma_f32 v[134:135], v[48:49], v[68:69], v[134:135]
	v_pk_fma_f32 v[134:135], v[50:51], v[70:71], v[134:135]
	ds_read_b128 v[44:47], v128 offset:12608
	s_waitcnt lgkmcnt(12)
	v_pk_fma_f32 v[136:137], v[52:53], v[68:69], v[136:137]
	v_pk_fma_f32 v[136:137], v[54:55], v[70:71], v[136:137]
	ds_read_b128 v[48:51], v128 offset:12864
	s_waitcnt lgkmcnt(12)
	v_pk_fma_f32 v[240:241], v[56:57], v[68:69], v[240:241]
	v_pk_fma_f32 v[240:241], v[58:59], v[70:71], v[240:241]
	ds_read_b128 v[52:55], v128 offset:13120
	s_waitcnt lgkmcnt(12)
	v_pk_fma_f32 v[242:243], v[60:61], v[68:69], v[242:243]
	v_pk_fma_f32 v[242:243], v[62:63], v[70:71], v[242:243]
	ds_read_b128 v[56:59], v128 offset:12368
	s_waitcnt lgkmcnt(12)
	v_pk_fma_f32 v[134:135], v[8:9], v[72:73], v[134:135]
	v_pk_fma_f32 v[134:135], v[10:11], v[74:75], v[134:135]
	ds_read_b128 v[60:63], v128 offset:12624
	s_waitcnt lgkmcnt(12)
	v_pk_fma_f32 v[136:137], v[12:13], v[72:73], v[136:137]
	v_pk_fma_f32 v[136:137], v[14:15], v[74:75], v[136:137]
	ds_read_b128 v[8:11], v128 offset:12880
	s_waitcnt lgkmcnt(12)
	v_pk_fma_f32 v[240:241], v[16:17], v[72:73], v[240:241]
	v_pk_fma_f32 v[240:241], v[18:19], v[74:75], v[240:241]
	ds_read_b128 v[12:15], v128 offset:13136
	s_waitcnt lgkmcnt(12)
	v_pk_fma_f32 v[242:243], v[20:21], v[72:73], v[242:243]
	v_pk_fma_f32 v[242:243], v[22:23], v[74:75], v[242:243]
	ds_read_b128 v[16:19], v128 offset:12384
	s_waitcnt lgkmcnt(12)
	v_pk_fma_f32 v[134:135], v[24:25], v[76:77], v[134:135]
	v_pk_fma_f32 v[134:135], v[26:27], v[78:79], v[134:135]
	ds_read_b128 v[20:23], v128 offset:12640
	s_waitcnt lgkmcnt(12)
	v_pk_fma_f32 v[136:137], v[28:29], v[76:77], v[136:137]
	v_pk_fma_f32 v[136:137], v[30:31], v[78:79], v[136:137]
	ds_read_b128 v[24:27], v128 offset:12896
	s_waitcnt lgkmcnt(12)
	v_pk_fma_f32 v[240:241], v[32:33], v[76:77], v[240:241]
	v_pk_fma_f32 v[240:241], v[34:35], v[78:79], v[240:241]
	ds_read_b128 v[28:31], v128 offset:13152
	s_waitcnt lgkmcnt(12)
	v_pk_fma_f32 v[242:243], v[36:37], v[76:77], v[242:243]
	v_pk_fma_f32 v[242:243], v[38:39], v[78:79], v[242:243]
	ds_read_b128 v[32:35], v128 offset:12400
	s_waitcnt lgkmcnt(12)
	v_pk_fma_f32 v[134:135], v[40:41], v[80:81], v[134:135]
	v_pk_fma_f32 v[134:135], v[42:43], v[82:83], v[134:135]
	ds_read_b128 v[36:39], v128 offset:12656
	s_waitcnt lgkmcnt(12)
	v_pk_fma_f32 v[136:137], v[44:45], v[80:81], v[136:137]
	v_pk_fma_f32 v[136:137], v[46:47], v[82:83], v[136:137]
	ds_read_b128 v[40:43], v128 offset:12912
	s_waitcnt lgkmcnt(12)
	v_pk_fma_f32 v[240:241], v[48:49], v[80:81], v[240:241]
	v_pk_fma_f32 v[240:241], v[50:51], v[82:83], v[240:241]
	ds_read_b128 v[44:47], v128 offset:13168
	s_waitcnt lgkmcnt(12)
	v_pk_fma_f32 v[242:243], v[52:53], v[80:81], v[242:243]
	v_pk_fma_f32 v[242:243], v[54:55], v[82:83], v[242:243]
	ds_read_b128 v[48:51], v128 offset:12416
	s_waitcnt lgkmcnt(12)
	v_pk_fma_f32 v[134:135], v[56:57], v[84:85], v[134:135]
	v_pk_fma_f32 v[134:135], v[58:59], v[86:87], v[134:135]
	ds_read_b128 v[52:55], v128 offset:12672
	s_waitcnt lgkmcnt(12)
	v_pk_fma_f32 v[136:137], v[60:61], v[84:85], v[136:137]
	v_pk_fma_f32 v[136:137], v[62:63], v[86:87], v[136:137]
	ds_read_b128 v[56:59], v128 offset:12928
	s_waitcnt lgkmcnt(12)
	v_pk_fma_f32 v[240:241], v[8:9], v[84:85], v[240:241]
	v_pk_fma_f32 v[240:241], v[10:11], v[86:87], v[240:241]
	ds_read_b128 v[60:63], v128 offset:13184
	s_waitcnt lgkmcnt(12)
	v_pk_fma_f32 v[242:243], v[12:13], v[84:85], v[242:243]
	v_pk_fma_f32 v[242:243], v[14:15], v[86:87], v[242:243]
	ds_read_b128 v[8:11], v128 offset:12432
	s_waitcnt lgkmcnt(12)
	v_pk_fma_f32 v[134:135], v[16:17], v[88:89], v[134:135]
	v_pk_fma_f32 v[134:135], v[18:19], v[90:91], v[134:135]
	ds_read_b128 v[12:15], v128 offset:12688
	s_waitcnt lgkmcnt(12)
	v_pk_fma_f32 v[136:137], v[20:21], v[88:89], v[136:137]
	v_pk_fma_f32 v[136:137], v[22:23], v[90:91], v[136:137]
	ds_read_b128 v[16:19], v128 offset:12944
	s_waitcnt lgkmcnt(12)
	v_pk_fma_f32 v[240:241], v[24:25], v[88:89], v[240:241]
	v_pk_fma_f32 v[240:241], v[26:27], v[90:91], v[240:241]
	ds_read_b128 v[20:23], v128 offset:13200
	s_waitcnt lgkmcnt(12)
	v_pk_fma_f32 v[242:243], v[28:29], v[88:89], v[242:243]
	v_pk_fma_f32 v[242:243], v[30:31], v[90:91], v[242:243]
	ds_read_b128 v[24:27], v128 offset:12448
	s_waitcnt lgkmcnt(12)
	v_pk_fma_f32 v[134:135], v[32:33], v[92:93], v[134:135]
	v_pk_fma_f32 v[134:135], v[34:35], v[94:95], v[134:135]
	ds_read_b128 v[28:31], v128 offset:12704
	s_waitcnt lgkmcnt(12)
	v_pk_fma_f32 v[136:137], v[36:37], v[92:93], v[136:137]
	v_pk_fma_f32 v[136:137], v[38:39], v[94:95], v[136:137]
	ds_read_b128 v[32:35], v128 offset:12960
	s_waitcnt lgkmcnt(12)
	v_pk_fma_f32 v[240:241], v[40:41], v[92:93], v[240:241]
	v_pk_fma_f32 v[240:241], v[42:43], v[94:95], v[240:241]
	ds_read_b128 v[36:39], v128 offset:13216
	s_waitcnt lgkmcnt(12)
	v_pk_fma_f32 v[242:243], v[44:45], v[92:93], v[242:243]
	v_pk_fma_f32 v[242:243], v[46:47], v[94:95], v[242:243]
	ds_read_b128 v[40:43], v128 offset:12464
	s_waitcnt lgkmcnt(12)
	v_pk_fma_f32 v[134:135], v[48:49], v[96:97], v[134:135]
	v_pk_fma_f32 v[134:135], v[50:51], v[98:99], v[134:135]
	ds_read_b128 v[44:47], v128 offset:12720
	s_waitcnt lgkmcnt(12)
	v_pk_fma_f32 v[136:137], v[52:53], v[96:97], v[136:137]
	v_pk_fma_f32 v[136:137], v[54:55], v[98:99], v[136:137]
	ds_read_b128 v[48:51], v128 offset:12976
	s_waitcnt lgkmcnt(12)
	v_pk_fma_f32 v[240:241], v[56:57], v[96:97], v[240:241]
	v_pk_fma_f32 v[240:241], v[58:59], v[98:99], v[240:241]
	ds_read_b128 v[52:55], v128 offset:13232
	s_waitcnt lgkmcnt(12)
	v_pk_fma_f32 v[242:243], v[60:61], v[96:97], v[242:243]
	v_pk_fma_f32 v[242:243], v[62:63], v[98:99], v[242:243]
	ds_read_b128 v[56:59], v128 offset:12736
	s_waitcnt lgkmcnt(12)
	v_pk_fma_f32 v[134:135], v[8:9], v[100:101], v[134:135]
	v_pk_fma_f32 v[134:135], v[10:11], v[102:103], v[134:135]
	ds_read_b128 v[60:63], v128 offset:12992
	s_waitcnt lgkmcnt(12)
	v_pk_fma_f32 v[136:137], v[12:13], v[100:101], v[136:137]
	v_pk_fma_f32 v[136:137], v[14:15], v[102:103], v[136:137]
	ds_read_b128 v[8:11], v128 offset:13248
	s_waitcnt lgkmcnt(12)
	v_pk_fma_f32 v[240:241], v[16:17], v[100:101], v[240:241]
	v_pk_fma_f32 v[240:241], v[18:19], v[102:103], v[240:241]
	ds_read_b128 v[12:15], v128 offset:13312
	s_waitcnt lgkmcnt(12)
	v_pk_fma_f32 v[242:243], v[20:21], v[100:101], v[242:243]
	v_pk_fma_f32 v[242:243], v[22:23], v[102:103], v[242:243]
	ds_read_b128 v[16:19], v128 offset:13568
	s_waitcnt lgkmcnt(12)
	v_pk_fma_f32 v[134:135], v[24:25], v[104:105], v[134:135]
	v_pk_fma_f32 v[134:135], v[26:27], v[106:107], v[134:135]
	ds_read_b128 v[20:23], v128 offset:13824
	s_waitcnt lgkmcnt(12)
	v_pk_fma_f32 v[136:137], v[28:29], v[104:105], v[136:137]
	v_pk_fma_f32 v[136:137], v[30:31], v[106:107], v[136:137]
	ds_read_b128 v[24:27], v128 offset:14080
	s_waitcnt lgkmcnt(12)
	v_pk_fma_f32 v[240:241], v[32:33], v[104:105], v[240:241]
	v_pk_fma_f32 v[240:241], v[34:35], v[106:107], v[240:241]
	ds_read_b128 v[28:31], v128 offset:13328
	s_waitcnt lgkmcnt(12)
	v_pk_fma_f32 v[242:243], v[36:37], v[104:105], v[242:243]
	v_pk_fma_f32 v[242:243], v[38:39], v[106:107], v[242:243]
	ds_read_b128 v[32:35], v128 offset:13584
	s_waitcnt lgkmcnt(12)
	v_pk_fma_f32 v[134:135], v[40:41], v[108:109], v[134:135]
	v_pk_fma_f32 v[134:135], v[42:43], v[110:111], v[134:135]
	ds_read_b128 v[36:39], v128 offset:13840
	s_waitcnt lgkmcnt(12)
	v_pk_fma_f32 v[136:137], v[44:45], v[108:109], v[136:137]
	v_pk_fma_f32 v[136:137], v[46:47], v[110:111], v[136:137]
	ds_read_b128 v[40:43], v128 offset:14096
	s_waitcnt lgkmcnt(12)
	v_pk_fma_f32 v[240:241], v[48:49], v[108:109], v[240:241]
	v_pk_fma_f32 v[240:241], v[50:51], v[110:111], v[240:241]
	ds_read_b128 v[44:47], v128 offset:13344
	s_waitcnt lgkmcnt(12)
	v_pk_fma_f32 v[242:243], v[52:53], v[108:109], v[242:243]
	v_pk_fma_f32 v[242:243], v[54:55], v[110:111], v[242:243]
	ds_read_b128 v[48:51], v128 offset:13600
	s_waitcnt lgkmcnt(12)
	v_mov_b32_e32 v129, v56
	ds_read_b128 v[52:55], v128 offset:13856
	s_waitcnt lgkmcnt(12)
	v_mov_b32_e32 v132, v60
	v_mov_b32_e32 v239, v61
	ds_read_b128 v[56:59], v128 offset:14112
	s_waitcnt lgkmcnt(12)
	v_mov_b32_e32 v249, v8
	v_mov_b32_e32 v6, v9
	v_mov_b32_e32 v7, v10
	v_add_f32_e32 v134, v134, v135
	v_add_f32_e32 v136, v136, v137
	v_add_f32_e32 v240, v240, v241
	v_add_f32_e32 v242, v242, v243
	v_add_f32_e32 v112, v112, v134
	v_add_f32_e32 v113, v113, v136
	v_add_f32_e32 v114, v114, v240
	v_add_f32_e32 v115, v115, v242
	v_fmac_f32_e32 v113, v129, v112
	v_fmac_f32_e32 v114, v132, v112
	v_fmac_f32_e32 v115, v249, v112
	v_fmac_f32_e32 v114, v239, v113
	v_fmac_f32_e32 v115, v6, v113
	v_fmac_f32_e32 v115, v7, v114
	ds_read_b128 v[60:63], v128 offset:13360
	s_waitcnt lgkmcnt(12)
	v_pk_mul_f32 v[134:135], v[12:13], v[64:65]
	v_pk_fma_f32 v[134:135], v[14:15], v[66:67], v[134:135]
	ds_read_b128 v[8:11], v128 offset:13616
	s_waitcnt lgkmcnt(12)
	v_pk_mul_f32 v[136:137], v[16:17], v[64:65]
	v_pk_fma_f32 v[136:137], v[18:19], v[66:67], v[136:137]
	ds_read_b128 v[12:15], v128 offset:13872
	s_waitcnt lgkmcnt(12)
	v_pk_mul_f32 v[240:241], v[20:21], v[64:65]
	v_pk_fma_f32 v[240:241], v[22:23], v[66:67], v[240:241]
	ds_read_b128 v[16:19], v128 offset:14128
	s_waitcnt lgkmcnt(12)
	v_pk_mul_f32 v[242:243], v[24:25], v[64:65]
	v_pk_fma_f32 v[242:243], v[26:27], v[66:67], v[242:243]
	ds_read_b128 v[20:23], v128 offset:13376
	s_waitcnt lgkmcnt(12)
	v_pk_fma_f32 v[134:135], v[28:29], v[68:69], v[134:135]
	v_pk_fma_f32 v[134:135], v[30:31], v[70:71], v[134:135]
	ds_read_b128 v[24:27], v128 offset:13632
	s_waitcnt lgkmcnt(12)
	v_pk_fma_f32 v[136:137], v[32:33], v[68:69], v[136:137]
	v_pk_fma_f32 v[136:137], v[34:35], v[70:71], v[136:137]
	ds_read_b128 v[28:31], v128 offset:13888
	s_waitcnt lgkmcnt(12)
	v_pk_fma_f32 v[240:241], v[36:37], v[68:69], v[240:241]
	v_pk_fma_f32 v[240:241], v[38:39], v[70:71], v[240:241]
	ds_read_b128 v[32:35], v128 offset:14144
	s_waitcnt lgkmcnt(12)
	v_pk_fma_f32 v[242:243], v[40:41], v[68:69], v[242:243]
	v_pk_fma_f32 v[242:243], v[42:43], v[70:71], v[242:243]
	ds_read_b128 v[36:39], v128 offset:13392
	s_waitcnt lgkmcnt(12)
	v_pk_fma_f32 v[134:135], v[44:45], v[72:73], v[134:135]
	v_pk_fma_f32 v[134:135], v[46:47], v[74:75], v[134:135]
	ds_read_b128 v[40:43], v128 offset:13648
	s_waitcnt lgkmcnt(12)
	v_pk_fma_f32 v[136:137], v[48:49], v[72:73], v[136:137]
	v_pk_fma_f32 v[136:137], v[50:51], v[74:75], v[136:137]
	ds_read_b128 v[44:47], v128 offset:13904
	s_waitcnt lgkmcnt(12)
	v_pk_fma_f32 v[240:241], v[52:53], v[72:73], v[240:241]
	v_pk_fma_f32 v[240:241], v[54:55], v[74:75], v[240:241]
	ds_read_b128 v[48:51], v128 offset:14160
	s_waitcnt lgkmcnt(12)
	v_pk_fma_f32 v[242:243], v[56:57], v[72:73], v[242:243]
	v_pk_fma_f32 v[242:243], v[58:59], v[74:75], v[242:243]
	ds_read_b128 v[52:55], v128 offset:13408
	s_waitcnt lgkmcnt(12)
	v_pk_fma_f32 v[134:135], v[60:61], v[76:77], v[134:135]
	v_pk_fma_f32 v[134:135], v[62:63], v[78:79], v[134:135]
	ds_read_b128 v[56:59], v128 offset:13664
	s_waitcnt lgkmcnt(12)
	v_pk_fma_f32 v[136:137], v[8:9], v[76:77], v[136:137]
	v_pk_fma_f32 v[136:137], v[10:11], v[78:79], v[136:137]
	ds_read_b128 v[60:63], v128 offset:13920
	s_waitcnt lgkmcnt(12)
	v_pk_fma_f32 v[240:241], v[12:13], v[76:77], v[240:241]
	v_pk_fma_f32 v[240:241], v[14:15], v[78:79], v[240:241]
	ds_read_b128 v[8:11], v128 offset:14176
	s_waitcnt lgkmcnt(12)
	v_pk_fma_f32 v[242:243], v[16:17], v[76:77], v[242:243]
	v_pk_fma_f32 v[242:243], v[18:19], v[78:79], v[242:243]
	ds_read_b128 v[12:15], v128 offset:13424
	s_waitcnt lgkmcnt(12)
	v_pk_fma_f32 v[134:135], v[20:21], v[80:81], v[134:135]
	v_pk_fma_f32 v[134:135], v[22:23], v[82:83], v[134:135]
	ds_read_b128 v[16:19], v128 offset:13680
	s_waitcnt lgkmcnt(12)
	v_pk_fma_f32 v[136:137], v[24:25], v[80:81], v[136:137]
	v_pk_fma_f32 v[136:137], v[26:27], v[82:83], v[136:137]
	ds_read_b128 v[20:23], v128 offset:13936
	s_waitcnt lgkmcnt(12)
	v_pk_fma_f32 v[240:241], v[28:29], v[80:81], v[240:241]
	v_pk_fma_f32 v[240:241], v[30:31], v[82:83], v[240:241]
	ds_read_b128 v[24:27], v128 offset:14192
	s_waitcnt lgkmcnt(12)
	v_pk_fma_f32 v[242:243], v[32:33], v[80:81], v[242:243]
	v_pk_fma_f32 v[242:243], v[34:35], v[82:83], v[242:243]
	ds_read_b128 v[28:31], v128 offset:13440
	s_waitcnt lgkmcnt(12)
	v_pk_fma_f32 v[134:135], v[36:37], v[84:85], v[134:135]
	v_pk_fma_f32 v[134:135], v[38:39], v[86:87], v[134:135]
	ds_read_b128 v[32:35], v128 offset:13696
	s_waitcnt lgkmcnt(12)
	v_pk_fma_f32 v[136:137], v[40:41], v[84:85], v[136:137]
	v_pk_fma_f32 v[136:137], v[42:43], v[86:87], v[136:137]
	ds_read_b128 v[36:39], v128 offset:13952
	s_waitcnt lgkmcnt(12)
	v_pk_fma_f32 v[240:241], v[44:45], v[84:85], v[240:241]
	v_pk_fma_f32 v[240:241], v[46:47], v[86:87], v[240:241]
	ds_read_b128 v[40:43], v128 offset:14208
	s_waitcnt lgkmcnt(12)
	v_pk_fma_f32 v[242:243], v[48:49], v[84:85], v[242:243]
	v_pk_fma_f32 v[242:243], v[50:51], v[86:87], v[242:243]
	ds_read_b128 v[44:47], v128 offset:13456
	s_waitcnt lgkmcnt(12)
	v_pk_fma_f32 v[134:135], v[52:53], v[88:89], v[134:135]
	v_pk_fma_f32 v[134:135], v[54:55], v[90:91], v[134:135]
	ds_read_b128 v[48:51], v128 offset:13712
	s_waitcnt lgkmcnt(12)
	v_pk_fma_f32 v[136:137], v[56:57], v[88:89], v[136:137]
	v_pk_fma_f32 v[136:137], v[58:59], v[90:91], v[136:137]
	ds_read_b128 v[52:55], v128 offset:13968
	s_waitcnt lgkmcnt(12)
	v_pk_fma_f32 v[240:241], v[60:61], v[88:89], v[240:241]
	v_pk_fma_f32 v[240:241], v[62:63], v[90:91], v[240:241]
	ds_read_b128 v[56:59], v128 offset:14224
	s_waitcnt lgkmcnt(12)
	v_pk_fma_f32 v[242:243], v[8:9], v[88:89], v[242:243]
	v_pk_fma_f32 v[242:243], v[10:11], v[90:91], v[242:243]
	ds_read_b128 v[60:63], v128 offset:13472
	s_waitcnt lgkmcnt(12)
	v_pk_fma_f32 v[134:135], v[12:13], v[92:93], v[134:135]
	v_pk_fma_f32 v[134:135], v[14:15], v[94:95], v[134:135]
	ds_read_b128 v[8:11], v128 offset:13728
	s_waitcnt lgkmcnt(12)
	v_pk_fma_f32 v[136:137], v[16:17], v[92:93], v[136:137]
	v_pk_fma_f32 v[136:137], v[18:19], v[94:95], v[136:137]
	ds_read_b128 v[12:15], v128 offset:13984
	s_waitcnt lgkmcnt(12)
	v_pk_fma_f32 v[240:241], v[20:21], v[92:93], v[240:241]
	v_pk_fma_f32 v[240:241], v[22:23], v[94:95], v[240:241]
	ds_read_b128 v[16:19], v128 offset:14240
	s_waitcnt lgkmcnt(12)
	v_pk_fma_f32 v[242:243], v[24:25], v[92:93], v[242:243]
	v_pk_fma_f32 v[242:243], v[26:27], v[94:95], v[242:243]
	ds_read_b128 v[20:23], v128 offset:13488
	s_waitcnt lgkmcnt(12)
	v_pk_fma_f32 v[134:135], v[28:29], v[96:97], v[134:135]
	v_pk_fma_f32 v[134:135], v[30:31], v[98:99], v[134:135]
	ds_read_b128 v[24:27], v128 offset:13744
	s_waitcnt lgkmcnt(12)
	v_pk_fma_f32 v[136:137], v[32:33], v[96:97], v[136:137]
	v_pk_fma_f32 v[136:137], v[34:35], v[98:99], v[136:137]
	ds_read_b128 v[28:31], v128 offset:14000
	s_waitcnt lgkmcnt(12)
	v_pk_fma_f32 v[240:241], v[36:37], v[96:97], v[240:241]
	v_pk_fma_f32 v[240:241], v[38:39], v[98:99], v[240:241]
	ds_read_b128 v[32:35], v128 offset:14256
	s_waitcnt lgkmcnt(12)
	v_pk_fma_f32 v[242:243], v[40:41], v[96:97], v[242:243]
	v_pk_fma_f32 v[242:243], v[42:43], v[98:99], v[242:243]
	ds_read_b128 v[36:39], v128 offset:13504
	s_waitcnt lgkmcnt(12)
	v_pk_fma_f32 v[134:135], v[44:45], v[100:101], v[134:135]
	v_pk_fma_f32 v[134:135], v[46:47], v[102:103], v[134:135]
	ds_read_b128 v[40:43], v128 offset:13760
	s_waitcnt lgkmcnt(12)
	v_pk_fma_f32 v[136:137], v[48:49], v[100:101], v[136:137]
	v_pk_fma_f32 v[136:137], v[50:51], v[102:103], v[136:137]
	ds_read_b128 v[44:47], v128 offset:14016
	s_waitcnt lgkmcnt(12)
	v_pk_fma_f32 v[240:241], v[52:53], v[100:101], v[240:241]
	v_pk_fma_f32 v[240:241], v[54:55], v[102:103], v[240:241]
	ds_read_b128 v[48:51], v128 offset:14272
	s_waitcnt lgkmcnt(12)
	v_pk_fma_f32 v[242:243], v[56:57], v[100:101], v[242:243]
	v_pk_fma_f32 v[242:243], v[58:59], v[102:103], v[242:243]
	ds_read_b128 v[52:55], v128 offset:13776
	s_waitcnt lgkmcnt(12)
	v_pk_fma_f32 v[134:135], v[60:61], v[104:105], v[134:135]
	v_pk_fma_f32 v[134:135], v[62:63], v[106:107], v[134:135]
	ds_read_b128 v[56:59], v128 offset:14032
	s_waitcnt lgkmcnt(12)
	v_pk_fma_f32 v[136:137], v[8:9], v[104:105], v[136:137]
	v_pk_fma_f32 v[136:137], v[10:11], v[106:107], v[136:137]
	ds_read_b128 v[60:63], v128 offset:14288
	s_waitcnt lgkmcnt(12)
	v_pk_fma_f32 v[240:241], v[12:13], v[104:105], v[240:241]
	v_pk_fma_f32 v[240:241], v[14:15], v[106:107], v[240:241]
	ds_read_b128 v[8:11], v128 offset:14336
	s_waitcnt lgkmcnt(12)
	v_pk_fma_f32 v[242:243], v[16:17], v[104:105], v[242:243]
	v_pk_fma_f32 v[242:243], v[18:19], v[106:107], v[242:243]
	ds_read_b128 v[12:15], v128 offset:14592
	s_waitcnt lgkmcnt(12)
	v_pk_fma_f32 v[134:135], v[20:21], v[108:109], v[134:135]
	v_pk_fma_f32 v[134:135], v[22:23], v[110:111], v[134:135]
	ds_read_b128 v[16:19], v128 offset:14848
	s_waitcnt lgkmcnt(12)
	v_pk_fma_f32 v[136:137], v[24:25], v[108:109], v[136:137]
	v_pk_fma_f32 v[136:137], v[26:27], v[110:111], v[136:137]
	ds_read_b128 v[20:23], v128 offset:15104
	s_waitcnt lgkmcnt(12)
	v_pk_fma_f32 v[240:241], v[28:29], v[108:109], v[240:241]
	v_pk_fma_f32 v[240:241], v[30:31], v[110:111], v[240:241]
	ds_read_b128 v[24:27], v128 offset:14352
	s_waitcnt lgkmcnt(12)
	v_pk_fma_f32 v[242:243], v[32:33], v[108:109], v[242:243]
	v_pk_fma_f32 v[242:243], v[34:35], v[110:111], v[242:243]
	ds_read_b128 v[28:31], v128 offset:14608
	s_waitcnt lgkmcnt(12)
	v_pk_fma_f32 v[134:135], v[36:37], v[112:113], v[134:135]
	v_pk_fma_f32 v[134:135], v[38:39], v[114:115], v[134:135]
	ds_read_b128 v[32:35], v128 offset:14864
	s_waitcnt lgkmcnt(12)
	v_pk_fma_f32 v[136:137], v[40:41], v[112:113], v[136:137]
	v_pk_fma_f32 v[136:137], v[42:43], v[114:115], v[136:137]
	ds_read_b128 v[36:39], v128 offset:15120
	s_waitcnt lgkmcnt(12)
	v_pk_fma_f32 v[240:241], v[44:45], v[112:113], v[240:241]
	v_pk_fma_f32 v[240:241], v[46:47], v[114:115], v[240:241]
	ds_read_b128 v[40:43], v128 offset:14368
	s_waitcnt lgkmcnt(12)
	v_pk_fma_f32 v[242:243], v[48:49], v[112:113], v[242:243]
	v_pk_fma_f32 v[242:243], v[50:51], v[114:115], v[242:243]
	ds_read_b128 v[44:47], v128 offset:14624
	s_waitcnt lgkmcnt(12)
	v_mov_b32_e32 v129, v52
	ds_read_b128 v[48:51], v128 offset:14880
	s_waitcnt lgkmcnt(12)
	v_mov_b32_e32 v132, v56
	v_mov_b32_e32 v239, v57
	ds_read_b128 v[52:55], v128 offset:15136
	s_waitcnt lgkmcnt(12)
	v_mov_b32_e32 v249, v60
	v_mov_b32_e32 v6, v61
	v_mov_b32_e32 v7, v62
	v_add_f32_e32 v134, v134, v135
	v_add_f32_e32 v136, v136, v137
	v_add_f32_e32 v240, v240, v241
	v_add_f32_e32 v242, v242, v243
	v_add_f32_e32 v116, v116, v134
	v_add_f32_e32 v117, v117, v136
	v_add_f32_e32 v118, v118, v240
	v_add_f32_e32 v119, v119, v242
	v_fmac_f32_e32 v117, v129, v116
	v_fmac_f32_e32 v118, v132, v116
	v_fmac_f32_e32 v119, v249, v116
	v_fmac_f32_e32 v118, v239, v117
	v_fmac_f32_e32 v119, v6, v117
	v_fmac_f32_e32 v119, v7, v118
	ds_read_b128 v[56:59], v128 offset:14384
	s_waitcnt lgkmcnt(12)
	v_pk_mul_f32 v[134:135], v[8:9], v[64:65]
	v_pk_fma_f32 v[134:135], v[10:11], v[66:67], v[134:135]
	ds_read_b128 v[60:63], v128 offset:14640
	s_waitcnt lgkmcnt(12)
	v_pk_mul_f32 v[136:137], v[12:13], v[64:65]
	v_pk_fma_f32 v[136:137], v[14:15], v[66:67], v[136:137]
	ds_read_b128 v[8:11], v128 offset:14896
	s_waitcnt lgkmcnt(12)
	v_pk_mul_f32 v[240:241], v[16:17], v[64:65]
	v_pk_fma_f32 v[240:241], v[18:19], v[66:67], v[240:241]
	ds_read_b128 v[12:15], v128 offset:15152
	s_waitcnt lgkmcnt(12)
	v_pk_mul_f32 v[242:243], v[20:21], v[64:65]
	v_pk_fma_f32 v[242:243], v[22:23], v[66:67], v[242:243]
	ds_read_b128 v[16:19], v128 offset:14400
	s_waitcnt lgkmcnt(12)
	v_pk_fma_f32 v[134:135], v[24:25], v[68:69], v[134:135]
	v_pk_fma_f32 v[134:135], v[26:27], v[70:71], v[134:135]
	ds_read_b128 v[20:23], v128 offset:14656
	s_waitcnt lgkmcnt(12)
	v_pk_fma_f32 v[136:137], v[28:29], v[68:69], v[136:137]
	v_pk_fma_f32 v[136:137], v[30:31], v[70:71], v[136:137]
	ds_read_b128 v[24:27], v128 offset:14912
	s_waitcnt lgkmcnt(12)
	v_pk_fma_f32 v[240:241], v[32:33], v[68:69], v[240:241]
	v_pk_fma_f32 v[240:241], v[34:35], v[70:71], v[240:241]
	ds_read_b128 v[28:31], v128 offset:15168
	s_waitcnt lgkmcnt(12)
	v_pk_fma_f32 v[242:243], v[36:37], v[68:69], v[242:243]
	v_pk_fma_f32 v[242:243], v[38:39], v[70:71], v[242:243]
	ds_read_b128 v[32:35], v128 offset:14416
	s_waitcnt lgkmcnt(12)
	v_pk_fma_f32 v[134:135], v[40:41], v[72:73], v[134:135]
	v_pk_fma_f32 v[134:135], v[42:43], v[74:75], v[134:135]
	ds_read_b128 v[36:39], v128 offset:14672
	s_waitcnt lgkmcnt(12)
	v_pk_fma_f32 v[136:137], v[44:45], v[72:73], v[136:137]
	v_pk_fma_f32 v[136:137], v[46:47], v[74:75], v[136:137]
	ds_read_b128 v[40:43], v128 offset:14928
	s_waitcnt lgkmcnt(12)
	v_pk_fma_f32 v[240:241], v[48:49], v[72:73], v[240:241]
	v_pk_fma_f32 v[240:241], v[50:51], v[74:75], v[240:241]
	ds_read_b128 v[44:47], v128 offset:15184
	s_waitcnt lgkmcnt(12)
	v_pk_fma_f32 v[242:243], v[52:53], v[72:73], v[242:243]
	v_pk_fma_f32 v[242:243], v[54:55], v[74:75], v[242:243]
	ds_read_b128 v[48:51], v128 offset:14432
	s_waitcnt lgkmcnt(12)
	v_pk_fma_f32 v[134:135], v[56:57], v[76:77], v[134:135]
	v_pk_fma_f32 v[134:135], v[58:59], v[78:79], v[134:135]
	ds_read_b128 v[52:55], v128 offset:14688
	s_waitcnt lgkmcnt(12)
	v_pk_fma_f32 v[136:137], v[60:61], v[76:77], v[136:137]
	v_pk_fma_f32 v[136:137], v[62:63], v[78:79], v[136:137]
	ds_read_b128 v[56:59], v128 offset:14944
	s_waitcnt lgkmcnt(12)
	v_pk_fma_f32 v[240:241], v[8:9], v[76:77], v[240:241]
	v_pk_fma_f32 v[240:241], v[10:11], v[78:79], v[240:241]
	ds_read_b128 v[60:63], v128 offset:15200
	s_waitcnt lgkmcnt(12)
	v_pk_fma_f32 v[242:243], v[12:13], v[76:77], v[242:243]
	v_pk_fma_f32 v[242:243], v[14:15], v[78:79], v[242:243]
	ds_read_b128 v[8:11], v128 offset:14448
	s_waitcnt lgkmcnt(12)
	v_pk_fma_f32 v[134:135], v[16:17], v[80:81], v[134:135]
	v_pk_fma_f32 v[134:135], v[18:19], v[82:83], v[134:135]
	ds_read_b128 v[12:15], v128 offset:14704
	s_waitcnt lgkmcnt(12)
	v_pk_fma_f32 v[136:137], v[20:21], v[80:81], v[136:137]
	v_pk_fma_f32 v[136:137], v[22:23], v[82:83], v[136:137]
	ds_read_b128 v[16:19], v128 offset:14960
	s_waitcnt lgkmcnt(12)
	v_pk_fma_f32 v[240:241], v[24:25], v[80:81], v[240:241]
	v_pk_fma_f32 v[240:241], v[26:27], v[82:83], v[240:241]
	ds_read_b128 v[20:23], v128 offset:15216
	s_waitcnt lgkmcnt(12)
	v_pk_fma_f32 v[242:243], v[28:29], v[80:81], v[242:243]
	v_pk_fma_f32 v[242:243], v[30:31], v[82:83], v[242:243]
	ds_read_b128 v[24:27], v128 offset:14464
	s_waitcnt lgkmcnt(12)
	v_pk_fma_f32 v[134:135], v[32:33], v[84:85], v[134:135]
	v_pk_fma_f32 v[134:135], v[34:35], v[86:87], v[134:135]
	ds_read_b128 v[28:31], v128 offset:14720
	s_waitcnt lgkmcnt(12)
	v_pk_fma_f32 v[136:137], v[36:37], v[84:85], v[136:137]
	v_pk_fma_f32 v[136:137], v[38:39], v[86:87], v[136:137]
	ds_read_b128 v[32:35], v128 offset:14976
	s_waitcnt lgkmcnt(12)
	v_pk_fma_f32 v[240:241], v[40:41], v[84:85], v[240:241]
	v_pk_fma_f32 v[240:241], v[42:43], v[86:87], v[240:241]
	ds_read_b128 v[36:39], v128 offset:15232
	s_waitcnt lgkmcnt(12)
	v_pk_fma_f32 v[242:243], v[44:45], v[84:85], v[242:243]
	v_pk_fma_f32 v[242:243], v[46:47], v[86:87], v[242:243]
	ds_read_b128 v[40:43], v128 offset:14480
	s_waitcnt lgkmcnt(12)
	v_pk_fma_f32 v[134:135], v[48:49], v[88:89], v[134:135]
	v_pk_fma_f32 v[134:135], v[50:51], v[90:91], v[134:135]
	ds_read_b128 v[44:47], v128 offset:14736
	s_waitcnt lgkmcnt(12)
	v_pk_fma_f32 v[136:137], v[52:53], v[88:89], v[136:137]
	v_pk_fma_f32 v[136:137], v[54:55], v[90:91], v[136:137]
	ds_read_b128 v[48:51], v128 offset:14992
	s_waitcnt lgkmcnt(12)
	v_pk_fma_f32 v[240:241], v[56:57], v[88:89], v[240:241]
	v_pk_fma_f32 v[240:241], v[58:59], v[90:91], v[240:241]
	ds_read_b128 v[52:55], v128 offset:15248
	s_waitcnt lgkmcnt(12)
	v_pk_fma_f32 v[242:243], v[60:61], v[88:89], v[242:243]
	v_pk_fma_f32 v[242:243], v[62:63], v[90:91], v[242:243]
	ds_read_b128 v[56:59], v128 offset:14496
	s_waitcnt lgkmcnt(12)
	v_pk_fma_f32 v[134:135], v[8:9], v[92:93], v[134:135]
	v_pk_fma_f32 v[134:135], v[10:11], v[94:95], v[134:135]
	ds_read_b128 v[60:63], v128 offset:14752
	s_waitcnt lgkmcnt(12)
	v_pk_fma_f32 v[136:137], v[12:13], v[92:93], v[136:137]
	v_pk_fma_f32 v[136:137], v[14:15], v[94:95], v[136:137]
	ds_read_b128 v[8:11], v128 offset:15008
	s_waitcnt lgkmcnt(12)
	v_pk_fma_f32 v[240:241], v[16:17], v[92:93], v[240:241]
	v_pk_fma_f32 v[240:241], v[18:19], v[94:95], v[240:241]
	ds_read_b128 v[12:15], v128 offset:15264
	s_waitcnt lgkmcnt(12)
	v_pk_fma_f32 v[242:243], v[20:21], v[92:93], v[242:243]
	v_pk_fma_f32 v[242:243], v[22:23], v[94:95], v[242:243]
	ds_read_b128 v[16:19], v128 offset:14512
	s_waitcnt lgkmcnt(12)
	v_pk_fma_f32 v[134:135], v[24:25], v[96:97], v[134:135]
	v_pk_fma_f32 v[134:135], v[26:27], v[98:99], v[134:135]
	ds_read_b128 v[20:23], v128 offset:14768
	s_waitcnt lgkmcnt(12)
	v_pk_fma_f32 v[136:137], v[28:29], v[96:97], v[136:137]
	v_pk_fma_f32 v[136:137], v[30:31], v[98:99], v[136:137]
	ds_read_b128 v[24:27], v128 offset:15024
	s_waitcnt lgkmcnt(12)
	v_pk_fma_f32 v[240:241], v[32:33], v[96:97], v[240:241]
	v_pk_fma_f32 v[240:241], v[34:35], v[98:99], v[240:241]
	ds_read_b128 v[28:31], v128 offset:15280
	s_waitcnt lgkmcnt(12)
	v_pk_fma_f32 v[242:243], v[36:37], v[96:97], v[242:243]
	v_pk_fma_f32 v[242:243], v[38:39], v[98:99], v[242:243]
	ds_read_b128 v[32:35], v128 offset:14528
	s_waitcnt lgkmcnt(12)
	v_pk_fma_f32 v[134:135], v[40:41], v[100:101], v[134:135]
	v_pk_fma_f32 v[134:135], v[42:43], v[102:103], v[134:135]
	ds_read_b128 v[36:39], v128 offset:14784
	s_waitcnt lgkmcnt(12)
	v_pk_fma_f32 v[136:137], v[44:45], v[100:101], v[136:137]
	v_pk_fma_f32 v[136:137], v[46:47], v[102:103], v[136:137]
	ds_read_b128 v[40:43], v128 offset:15040
	s_waitcnt lgkmcnt(12)
	v_pk_fma_f32 v[240:241], v[48:49], v[100:101], v[240:241]
	v_pk_fma_f32 v[240:241], v[50:51], v[102:103], v[240:241]
	ds_read_b128 v[44:47], v128 offset:15296
	s_waitcnt lgkmcnt(12)
	v_pk_fma_f32 v[242:243], v[52:53], v[100:101], v[242:243]
	v_pk_fma_f32 v[242:243], v[54:55], v[102:103], v[242:243]
	ds_read_b128 v[48:51], v128 offset:14544
	s_waitcnt lgkmcnt(12)
	v_pk_fma_f32 v[134:135], v[56:57], v[104:105], v[134:135]
	v_pk_fma_f32 v[134:135], v[58:59], v[106:107], v[134:135]
	ds_read_b128 v[52:55], v128 offset:14800
	s_waitcnt lgkmcnt(12)
	v_pk_fma_f32 v[136:137], v[60:61], v[104:105], v[136:137]
	v_pk_fma_f32 v[136:137], v[62:63], v[106:107], v[136:137]
	ds_read_b128 v[56:59], v128 offset:15056
	s_waitcnt lgkmcnt(12)
	v_pk_fma_f32 v[240:241], v[8:9], v[104:105], v[240:241]
	v_pk_fma_f32 v[240:241], v[10:11], v[106:107], v[240:241]
	ds_read_b128 v[60:63], v128 offset:15312
	s_waitcnt lgkmcnt(12)
	v_pk_fma_f32 v[242:243], v[12:13], v[104:105], v[242:243]
	v_pk_fma_f32 v[242:243], v[14:15], v[106:107], v[242:243]
	ds_read_b128 v[8:11], v128 offset:14816
	s_waitcnt lgkmcnt(12)
	v_pk_fma_f32 v[134:135], v[16:17], v[108:109], v[134:135]
	v_pk_fma_f32 v[134:135], v[18:19], v[110:111], v[134:135]
	ds_read_b128 v[12:15], v128 offset:15072
	s_waitcnt lgkmcnt(12)
	v_pk_fma_f32 v[136:137], v[20:21], v[108:109], v[136:137]
	v_pk_fma_f32 v[136:137], v[22:23], v[110:111], v[136:137]
	ds_read_b128 v[16:19], v128 offset:15328
	s_waitcnt lgkmcnt(12)
	v_pk_fma_f32 v[240:241], v[24:25], v[108:109], v[240:241]
	v_pk_fma_f32 v[240:241], v[26:27], v[110:111], v[240:241]
	ds_read_b128 v[20:23], v128 offset:15360
	s_waitcnt lgkmcnt(12)
	v_pk_fma_f32 v[242:243], v[28:29], v[108:109], v[242:243]
	v_pk_fma_f32 v[242:243], v[30:31], v[110:111], v[242:243]
	ds_read_b128 v[24:27], v128 offset:15616
	s_waitcnt lgkmcnt(12)
	v_pk_fma_f32 v[134:135], v[32:33], v[112:113], v[134:135]
	v_pk_fma_f32 v[134:135], v[34:35], v[114:115], v[134:135]
	ds_read_b128 v[28:31], v128 offset:15872
	s_waitcnt lgkmcnt(12)
	v_pk_fma_f32 v[136:137], v[36:37], v[112:113], v[136:137]
	v_pk_fma_f32 v[136:137], v[38:39], v[114:115], v[136:137]
	ds_read_b128 v[32:35], v128 offset:16128
	s_waitcnt lgkmcnt(12)
	v_pk_fma_f32 v[240:241], v[40:41], v[112:113], v[240:241]
	v_pk_fma_f32 v[240:241], v[42:43], v[114:115], v[240:241]
	ds_read_b128 v[36:39], v128 offset:15376
	s_waitcnt lgkmcnt(12)
	v_pk_fma_f32 v[242:243], v[44:45], v[112:113], v[242:243]
	v_pk_fma_f32 v[242:243], v[46:47], v[114:115], v[242:243]
	ds_read_b128 v[40:43], v128 offset:15632
	s_waitcnt lgkmcnt(12)
	v_pk_fma_f32 v[134:135], v[48:49], v[116:117], v[134:135]
	v_pk_fma_f32 v[134:135], v[50:51], v[118:119], v[134:135]
	ds_read_b128 v[44:47], v128 offset:15888
	s_waitcnt lgkmcnt(12)
	v_pk_fma_f32 v[136:137], v[52:53], v[116:117], v[136:137]
	v_pk_fma_f32 v[136:137], v[54:55], v[118:119], v[136:137]
	ds_read_b128 v[48:51], v128 offset:16144
	s_waitcnt lgkmcnt(12)
	v_pk_fma_f32 v[240:241], v[56:57], v[116:117], v[240:241]
	v_pk_fma_f32 v[240:241], v[58:59], v[118:119], v[240:241]
	ds_read_b128 v[52:55], v128 offset:15392
	s_waitcnt lgkmcnt(12)
	v_pk_fma_f32 v[242:243], v[60:61], v[116:117], v[242:243]
	v_pk_fma_f32 v[242:243], v[62:63], v[118:119], v[242:243]
	ds_read_b128 v[56:59], v128 offset:15648
	s_waitcnt lgkmcnt(12)
	v_mov_b32_e32 v129, v8
	ds_read_b128 v[60:63], v128 offset:15904
	s_waitcnt lgkmcnt(12)
	v_mov_b32_e32 v132, v12
	v_mov_b32_e32 v239, v13
	ds_read_b128 v[8:11], v128 offset:16160
	s_waitcnt lgkmcnt(12)
	v_mov_b32_e32 v249, v16
	v_mov_b32_e32 v6, v17
	v_mov_b32_e32 v7, v18
	v_add_f32_e32 v134, v134, v135
	v_add_f32_e32 v136, v136, v137
	v_add_f32_e32 v240, v240, v241
	v_add_f32_e32 v242, v242, v243
	v_add_f32_e32 v120, v120, v134
	v_add_f32_e32 v121, v121, v136
	v_add_f32_e32 v122, v122, v240
	v_add_f32_e32 v123, v123, v242
	v_fmac_f32_e32 v121, v129, v120
	v_fmac_f32_e32 v122, v132, v120
	v_fmac_f32_e32 v123, v249, v120
	v_fmac_f32_e32 v122, v239, v121
	v_fmac_f32_e32 v123, v6, v121
	v_fmac_f32_e32 v123, v7, v122
	ds_read_b128 v[12:15], v128 offset:15408
	s_waitcnt lgkmcnt(12)
	v_pk_mul_f32 v[134:135], v[20:21], v[64:65]
	v_pk_fma_f32 v[134:135], v[22:23], v[66:67], v[134:135]
	ds_read_b128 v[16:19], v128 offset:15664
	s_waitcnt lgkmcnt(12)
	v_pk_mul_f32 v[136:137], v[24:25], v[64:65]
	v_pk_fma_f32 v[136:137], v[26:27], v[66:67], v[136:137]
	ds_read_b128 v[20:23], v128 offset:15920
	s_waitcnt lgkmcnt(12)
	v_pk_mul_f32 v[240:241], v[28:29], v[64:65]
	v_pk_fma_f32 v[240:241], v[30:31], v[66:67], v[240:241]
	ds_read_b128 v[24:27], v128 offset:16176
	s_waitcnt lgkmcnt(12)
	v_pk_mul_f32 v[242:243], v[32:33], v[64:65]
	v_pk_fma_f32 v[242:243], v[34:35], v[66:67], v[242:243]
	ds_read_b128 v[28:31], v128 offset:15424
	s_waitcnt lgkmcnt(12)
	v_pk_fma_f32 v[134:135], v[36:37], v[68:69], v[134:135]
	v_pk_fma_f32 v[134:135], v[38:39], v[70:71], v[134:135]
	ds_read_b128 v[32:35], v128 offset:15680
	s_waitcnt lgkmcnt(12)
	v_pk_fma_f32 v[136:137], v[40:41], v[68:69], v[136:137]
	v_pk_fma_f32 v[136:137], v[42:43], v[70:71], v[136:137]
	ds_read_b128 v[36:39], v128 offset:15936
	s_waitcnt lgkmcnt(12)
	v_pk_fma_f32 v[240:241], v[44:45], v[68:69], v[240:241]
	v_pk_fma_f32 v[240:241], v[46:47], v[70:71], v[240:241]
	ds_read_b128 v[40:43], v128 offset:16192
	s_waitcnt lgkmcnt(12)
	v_pk_fma_f32 v[242:243], v[48:49], v[68:69], v[242:243]
	v_pk_fma_f32 v[242:243], v[50:51], v[70:71], v[242:243]
	ds_read_b128 v[44:47], v128 offset:15440
	s_waitcnt lgkmcnt(12)
	v_pk_fma_f32 v[134:135], v[52:53], v[72:73], v[134:135]
	v_pk_fma_f32 v[134:135], v[54:55], v[74:75], v[134:135]
	ds_read_b128 v[48:51], v128 offset:15696
	s_waitcnt lgkmcnt(12)
	v_pk_fma_f32 v[136:137], v[56:57], v[72:73], v[136:137]
	v_pk_fma_f32 v[136:137], v[58:59], v[74:75], v[136:137]
	ds_read_b128 v[52:55], v128 offset:15952
	s_waitcnt lgkmcnt(12)
	v_pk_fma_f32 v[240:241], v[60:61], v[72:73], v[240:241]
	v_pk_fma_f32 v[240:241], v[62:63], v[74:75], v[240:241]
	ds_read_b128 v[56:59], v128 offset:16208
	s_waitcnt lgkmcnt(12)
	v_pk_fma_f32 v[242:243], v[8:9], v[72:73], v[242:243]
	v_pk_fma_f32 v[242:243], v[10:11], v[74:75], v[242:243]
	ds_read_b128 v[60:63], v128 offset:15456
	s_waitcnt lgkmcnt(12)
	v_pk_fma_f32 v[134:135], v[12:13], v[76:77], v[134:135]
	v_pk_fma_f32 v[134:135], v[14:15], v[78:79], v[134:135]
	ds_read_b128 v[8:11], v128 offset:15712
	s_waitcnt lgkmcnt(12)
	v_pk_fma_f32 v[136:137], v[16:17], v[76:77], v[136:137]
	v_pk_fma_f32 v[136:137], v[18:19], v[78:79], v[136:137]
	ds_read_b128 v[12:15], v128 offset:15968
	s_waitcnt lgkmcnt(12)
	v_pk_fma_f32 v[240:241], v[20:21], v[76:77], v[240:241]
	v_pk_fma_f32 v[240:241], v[22:23], v[78:79], v[240:241]
	ds_read_b128 v[16:19], v128 offset:16224
	s_waitcnt lgkmcnt(12)
	v_pk_fma_f32 v[242:243], v[24:25], v[76:77], v[242:243]
	v_pk_fma_f32 v[242:243], v[26:27], v[78:79], v[242:243]
	ds_read_b128 v[20:23], v128 offset:15472
	s_waitcnt lgkmcnt(12)
	v_pk_fma_f32 v[134:135], v[28:29], v[80:81], v[134:135]
	v_pk_fma_f32 v[134:135], v[30:31], v[82:83], v[134:135]
	ds_read_b128 v[24:27], v128 offset:15728
	s_waitcnt lgkmcnt(12)
	v_pk_fma_f32 v[136:137], v[32:33], v[80:81], v[136:137]
	v_pk_fma_f32 v[136:137], v[34:35], v[82:83], v[136:137]
	ds_read_b128 v[28:31], v128 offset:15984
	s_waitcnt lgkmcnt(12)
	v_pk_fma_f32 v[240:241], v[36:37], v[80:81], v[240:241]
	v_pk_fma_f32 v[240:241], v[38:39], v[82:83], v[240:241]
	ds_read_b128 v[32:35], v128 offset:16240
	s_waitcnt lgkmcnt(12)
	v_pk_fma_f32 v[242:243], v[40:41], v[80:81], v[242:243]
	v_pk_fma_f32 v[242:243], v[42:43], v[82:83], v[242:243]
	ds_read_b128 v[36:39], v128 offset:15488
	s_waitcnt lgkmcnt(12)
	v_pk_fma_f32 v[134:135], v[44:45], v[84:85], v[134:135]
	v_pk_fma_f32 v[134:135], v[46:47], v[86:87], v[134:135]
	ds_read_b128 v[40:43], v128 offset:15744
	s_waitcnt lgkmcnt(12)
	v_pk_fma_f32 v[136:137], v[48:49], v[84:85], v[136:137]
	v_pk_fma_f32 v[136:137], v[50:51], v[86:87], v[136:137]
	ds_read_b128 v[44:47], v128 offset:16000
	s_waitcnt lgkmcnt(12)
	v_pk_fma_f32 v[240:241], v[52:53], v[84:85], v[240:241]
	v_pk_fma_f32 v[240:241], v[54:55], v[86:87], v[240:241]
	ds_read_b128 v[48:51], v128 offset:16256
	s_waitcnt lgkmcnt(12)
	v_pk_fma_f32 v[242:243], v[56:57], v[84:85], v[242:243]
	v_pk_fma_f32 v[242:243], v[58:59], v[86:87], v[242:243]
	ds_read_b128 v[52:55], v128 offset:15504
	s_waitcnt lgkmcnt(12)
	v_pk_fma_f32 v[134:135], v[60:61], v[88:89], v[134:135]
	v_pk_fma_f32 v[134:135], v[62:63], v[90:91], v[134:135]
	ds_read_b128 v[56:59], v128 offset:15760
	s_waitcnt lgkmcnt(12)
	v_pk_fma_f32 v[136:137], v[8:9], v[88:89], v[136:137]
	v_pk_fma_f32 v[136:137], v[10:11], v[90:91], v[136:137]
	ds_read_b128 v[60:63], v128 offset:16016
	s_waitcnt lgkmcnt(12)
	v_pk_fma_f32 v[240:241], v[12:13], v[88:89], v[240:241]
	v_pk_fma_f32 v[240:241], v[14:15], v[90:91], v[240:241]
	ds_read_b128 v[8:11], v128 offset:16272
	s_waitcnt lgkmcnt(12)
	v_pk_fma_f32 v[242:243], v[16:17], v[88:89], v[242:243]
	v_pk_fma_f32 v[242:243], v[18:19], v[90:91], v[242:243]
	ds_read_b128 v[12:15], v128 offset:15520
	s_waitcnt lgkmcnt(12)
	v_pk_fma_f32 v[134:135], v[20:21], v[92:93], v[134:135]
	v_pk_fma_f32 v[134:135], v[22:23], v[94:95], v[134:135]
	ds_read_b128 v[16:19], v128 offset:15776
	s_waitcnt lgkmcnt(12)
	v_pk_fma_f32 v[136:137], v[24:25], v[92:93], v[136:137]
	v_pk_fma_f32 v[136:137], v[26:27], v[94:95], v[136:137]
	ds_read_b128 v[20:23], v128 offset:16032
	s_waitcnt lgkmcnt(12)
	v_pk_fma_f32 v[240:241], v[28:29], v[92:93], v[240:241]
	v_pk_fma_f32 v[240:241], v[30:31], v[94:95], v[240:241]
	ds_read_b128 v[24:27], v128 offset:16288
	s_waitcnt lgkmcnt(12)
	v_pk_fma_f32 v[242:243], v[32:33], v[92:93], v[242:243]
	v_pk_fma_f32 v[242:243], v[34:35], v[94:95], v[242:243]
	ds_read_b128 v[28:31], v128 offset:15536
	s_waitcnt lgkmcnt(12)
	v_pk_fma_f32 v[134:135], v[36:37], v[96:97], v[134:135]
	v_pk_fma_f32 v[134:135], v[38:39], v[98:99], v[134:135]
	ds_read_b128 v[32:35], v128 offset:15792
	s_waitcnt lgkmcnt(12)
	v_pk_fma_f32 v[136:137], v[40:41], v[96:97], v[136:137]
	v_pk_fma_f32 v[136:137], v[42:43], v[98:99], v[136:137]
	ds_read_b128 v[36:39], v128 offset:16048
	s_waitcnt lgkmcnt(12)
	v_pk_fma_f32 v[240:241], v[44:45], v[96:97], v[240:241]
	v_pk_fma_f32 v[240:241], v[46:47], v[98:99], v[240:241]
	ds_read_b128 v[40:43], v128 offset:16304
	s_waitcnt lgkmcnt(12)
	v_pk_fma_f32 v[242:243], v[48:49], v[96:97], v[242:243]
	v_pk_fma_f32 v[242:243], v[50:51], v[98:99], v[242:243]
	ds_read_b128 v[44:47], v128 offset:15552
	s_waitcnt lgkmcnt(12)
	v_pk_fma_f32 v[134:135], v[52:53], v[100:101], v[134:135]
	v_pk_fma_f32 v[134:135], v[54:55], v[102:103], v[134:135]
	ds_read_b128 v[48:51], v128 offset:15808
	s_waitcnt lgkmcnt(12)
	v_pk_fma_f32 v[136:137], v[56:57], v[100:101], v[136:137]
	v_pk_fma_f32 v[136:137], v[58:59], v[102:103], v[136:137]
	ds_read_b128 v[52:55], v128 offset:16064
	s_waitcnt lgkmcnt(12)
	v_pk_fma_f32 v[240:241], v[60:61], v[100:101], v[240:241]
	v_pk_fma_f32 v[240:241], v[62:63], v[102:103], v[240:241]
	ds_read_b128 v[56:59], v128 offset:16320
	s_waitcnt lgkmcnt(12)
	v_pk_fma_f32 v[242:243], v[8:9], v[100:101], v[242:243]
	v_pk_fma_f32 v[242:243], v[10:11], v[102:103], v[242:243]
	ds_read_b128 v[60:63], v128 offset:15568
	s_waitcnt lgkmcnt(12)
	v_pk_fma_f32 v[134:135], v[12:13], v[104:105], v[134:135]
	v_pk_fma_f32 v[134:135], v[14:15], v[106:107], v[134:135]
	ds_read_b128 v[8:11], v128 offset:15824
	s_waitcnt lgkmcnt(12)
	v_pk_fma_f32 v[136:137], v[16:17], v[104:105], v[136:137]
	v_pk_fma_f32 v[136:137], v[18:19], v[106:107], v[136:137]
	ds_read_b128 v[12:15], v128 offset:16080
	s_waitcnt lgkmcnt(12)
	v_pk_fma_f32 v[240:241], v[20:21], v[104:105], v[240:241]
	v_pk_fma_f32 v[240:241], v[22:23], v[106:107], v[240:241]
	ds_read_b128 v[16:19], v128 offset:16336
	s_waitcnt lgkmcnt(12)
	v_pk_fma_f32 v[242:243], v[24:25], v[104:105], v[242:243]
	v_pk_fma_f32 v[242:243], v[26:27], v[106:107], v[242:243]
	ds_read_b128 v[20:23], v128 offset:15584
	s_waitcnt lgkmcnt(12)
	v_pk_fma_f32 v[134:135], v[28:29], v[108:109], v[134:135]
	v_pk_fma_f32 v[134:135], v[30:31], v[110:111], v[134:135]
	ds_read_b128 v[24:27], v128 offset:15840
	s_waitcnt lgkmcnt(12)
	v_pk_fma_f32 v[136:137], v[32:33], v[108:109], v[136:137]
	v_pk_fma_f32 v[136:137], v[34:35], v[110:111], v[136:137]
	ds_read_b128 v[28:31], v128 offset:16096
	s_waitcnt lgkmcnt(12)
	v_pk_fma_f32 v[240:241], v[36:37], v[108:109], v[240:241]
	v_pk_fma_f32 v[240:241], v[38:39], v[110:111], v[240:241]
	ds_read_b128 v[32:35], v128 offset:16352
	s_waitcnt lgkmcnt(12)
	v_pk_fma_f32 v[242:243], v[40:41], v[108:109], v[242:243]
	v_pk_fma_f32 v[242:243], v[42:43], v[110:111], v[242:243]
	ds_read_b128 v[36:39], v128 offset:15856
	s_waitcnt lgkmcnt(12)
	v_pk_fma_f32 v[134:135], v[44:45], v[112:113], v[134:135]
	v_pk_fma_f32 v[134:135], v[46:47], v[114:115], v[134:135]
	ds_read_b128 v[40:43], v128 offset:16112
	s_waitcnt lgkmcnt(12)
	v_pk_fma_f32 v[136:137], v[48:49], v[112:113], v[136:137]
	v_pk_fma_f32 v[136:137], v[50:51], v[114:115], v[136:137]
	ds_read_b128 v[44:47], v128 offset:16368
	s_waitcnt lgkmcnt(12)
	v_pk_fma_f32 v[240:241], v[52:53], v[112:113], v[240:241]
	v_pk_fma_f32 v[240:241], v[54:55], v[114:115], v[240:241]
	s_waitcnt lgkmcnt(11)
	v_pk_fma_f32 v[242:243], v[56:57], v[112:113], v[242:243]
	v_pk_fma_f32 v[242:243], v[58:59], v[114:115], v[242:243]
	s_waitcnt lgkmcnt(10)
	v_pk_fma_f32 v[134:135], v[60:61], v[116:117], v[134:135]
	v_pk_fma_f32 v[134:135], v[62:63], v[118:119], v[134:135]
	s_waitcnt lgkmcnt(9)
	v_pk_fma_f32 v[136:137], v[8:9], v[116:117], v[136:137]
	v_pk_fma_f32 v[136:137], v[10:11], v[118:119], v[136:137]
	s_waitcnt lgkmcnt(8)
	v_pk_fma_f32 v[240:241], v[12:13], v[116:117], v[240:241]
	v_pk_fma_f32 v[240:241], v[14:15], v[118:119], v[240:241]
	s_waitcnt lgkmcnt(7)
	v_pk_fma_f32 v[242:243], v[16:17], v[116:117], v[242:243]
	v_pk_fma_f32 v[242:243], v[18:19], v[118:119], v[242:243]
	s_waitcnt lgkmcnt(6)
	v_pk_fma_f32 v[134:135], v[20:21], v[120:121], v[134:135]
	v_pk_fma_f32 v[134:135], v[22:23], v[122:123], v[134:135]
	s_waitcnt lgkmcnt(5)
	v_pk_fma_f32 v[136:137], v[24:25], v[120:121], v[136:137]
	v_pk_fma_f32 v[136:137], v[26:27], v[122:123], v[136:137]
	s_waitcnt lgkmcnt(4)
	v_pk_fma_f32 v[240:241], v[28:29], v[120:121], v[240:241]
	v_pk_fma_f32 v[240:241], v[30:31], v[122:123], v[240:241]
	s_waitcnt lgkmcnt(3)
	v_pk_fma_f32 v[242:243], v[32:33], v[120:121], v[242:243]
	v_pk_fma_f32 v[242:243], v[34:35], v[122:123], v[242:243]
	s_waitcnt lgkmcnt(2)
	v_mov_b32_e32 v129, v36
	s_waitcnt lgkmcnt(1)
	v_mov_b32_e32 v132, v40
	v_mov_b32_e32 v239, v41
	s_waitcnt lgkmcnt(0)
	v_mov_b32_e32 v249, v44
	v_mov_b32_e32 v6, v45
	v_mov_b32_e32 v7, v46
	v_add_f32_e32 v134, v134, v135
	v_add_f32_e32 v136, v136, v137
	v_add_f32_e32 v240, v240, v241
	v_add_f32_e32 v242, v242, v243
	v_add_f32_e32 v124, v124, v134
	v_add_f32_e32 v125, v125, v136
	v_add_f32_e32 v126, v126, v240
	v_add_f32_e32 v127, v127, v242
	v_fmac_f32_e32 v125, v129, v124
	v_fmac_f32_e32 v126, v132, v124
	v_fmac_f32_e32 v127, v249, v124
	v_fmac_f32_e32 v126, v239, v125
	v_fmac_f32_e32 v127, v6, v125
	v_fmac_f32_e32 v127, v7, v126
	ds_write2st64_b32 v131, v66, v67 offset0:2 offset1:3
	ds_write2st64_b32 v131, v68, v69 offset0:4 offset1:5
	ds_write2st64_b32 v131, v70, v71 offset0:6 offset1:7
	ds_write2st64_b32 v131, v72, v73 offset0:8 offset1:9
	ds_write2st64_b32 v131, v74, v75 offset0:10 offset1:11
	ds_write2st64_b32 v131, v76, v77 offset0:12 offset1:13
	ds_write2st64_b32 v131, v78, v79 offset0:14 offset1:15
	ds_write2st64_b32 v131, v80, v81 offset0:16 offset1:17
	ds_write2st64_b32 v131, v82, v83 offset0:18 offset1:19
	ds_write2st64_b32 v131, v84, v85 offset0:20 offset1:21
	ds_write2st64_b32 v131, v86, v87 offset0:22 offset1:23
	ds_write2st64_b32 v131, v88, v89 offset0:24 offset1:25
	ds_write2st64_b32 v131, v90, v91 offset0:26 offset1:27
	ds_write2st64_b32 v131, v92, v93 offset0:28 offset1:29
	ds_write2st64_b32 v131, v94, v95 offset0:30 offset1:31
	ds_write2st64_b32 v131, v96, v97 offset0:32 offset1:33
	ds_write2st64_b32 v131, v98, v99 offset0:34 offset1:35
	ds_write2st64_b32 v131, v100, v101 offset0:36 offset1:37
	ds_write2st64_b32 v131, v102, v103 offset0:38 offset1:39
	ds_write2st64_b32 v131, v104, v105 offset0:40 offset1:41
	ds_write2st64_b32 v131, v106, v107 offset0:42 offset1:43
	ds_write2st64_b32 v131, v108, v109 offset0:44 offset1:45
	ds_write2st64_b32 v131, v110, v111 offset0:46 offset1:47
	ds_write2st64_b32 v131, v112, v113 offset0:48 offset1:49
	ds_write2st64_b32 v131, v114, v115 offset0:50 offset1:51
	ds_write2st64_b32 v131, v116, v117 offset0:52 offset1:53
	ds_write2st64_b32 v131, v118, v119 offset0:54 offset1:55
	ds_write2st64_b32 v131, v120, v121 offset0:56 offset1:57
	ds_write2st64_b32 v131, v122, v123 offset0:58 offset1:59
	ds_write2st64_b32 v131, v124, v125 offset0:60 offset1:61
	ds_write2st64_b32 v131, v126, v127 offset0:62 offset1:63
	global_load_dwordx4 v[56:59], v[4:5], off offset:-4096
	global_load_dwordx4 v[60:63], v[2:3], off offset:64
	global_load_dwordx4 v[48:51], v[2:3], off offset:2048
	global_load_dwordx4 v[52:55], v[2:3], off offset:2112
	global_load_dwordx4 v[40:43], v[4:5], off
	global_load_dwordx4 v[44:47], v[4:5], off offset:64
	global_load_dwordx4 v[32:35], v[4:5], off offset:2048
	global_load_dwordx4 v[36:39], v[4:5], off offset:2112
	v_add_co_u32_e32 v2, vcc, s0, v0
	s_mov_b32 s0, 0x2bb43000
	s_nop 0
	v_addc_co_u32_e32 v3, vcc, 0, v1, vcc
	v_add_co_u32_e32 v4, vcc, s0, v0
	v_readlane_b32 s1, v247, 62
	s_nop 0
	v_addc_co_u32_e32 v5, vcc, 0, v1, vcc
	global_load_dwordx4 v[24:27], v[4:5], off offset:-4096
	global_load_dwordx4 v[28:31], v[2:3], off offset:64
	global_load_dwordx4 v[16:19], v[2:3], off offset:2048
	global_load_dwordx4 v[20:23], v[2:3], off offset:2112
	global_load_dwordx4 v[8:11], v[4:5], off
	global_load_dwordx4 v[12:15], v[4:5], off offset:64
	s_nop 0
	global_load_dwordx4 v[0:3], v[4:5], off offset:2048
	s_nop 0
	global_load_dwordx4 v[4:7], v[4:5], off offset:2112
	v_lshl_add_u32 v69, v130, 5, v166
	v_cmp_eq_u32_e64 s[0:1], v177, v148
	v_and_or_b32 v64, v148, 56, v169
	v_lshlrev_b32_e32 v66, 2, v64
	ds_bpermute_b32 v64, v66, v157
	ds_bpermute_b32 v65, v66, v157 offset:4
	ds_bpermute_b32 v86, v66, v153
	ds_bpermute_b32 v87, v66, v153 offset:4
	v_add_u32_e32 v118, v69, v175
	s_waitcnt lgkmcnt(3)
	v_mul_f32_e32 v64, 0x3fb8aa3b, v64
	s_waitcnt lgkmcnt(2)
	v_mul_f32_e32 v65, 0x3fb8aa3b, v65
	v_exp_f32_e32 v64, v64
	v_exp_f32_e32 v65, v65
	s_waitcnt lgkmcnt(0)
	ds_bpermute_b32 v70, v66, v153 offset:8
	ds_bpermute_b32 v71, v66, v153 offset:12
	s_waitcnt lgkmcnt(2)
	v_pk_mul_f32 v[106:107], v[64:65], v[86:87]
	ds_bpermute_b32 v64, v66, v157 offset:8
	ds_bpermute_b32 v102, v66, v153 offset:16
	ds_bpermute_b32 v103, v66, v153 offset:20
	ds_bpermute_b32 v78, v66, v153 offset:24
	ds_bpermute_b32 v79, v66, v153 offset:28
	s_waitcnt lgkmcnt(4)
	v_mul_f32_e32 v64, 0x3fb8aa3b, v64
	v_exp_f32_e32 v108, v64
	ds_bpermute_b32 v64, v66, v157 offset:12
	v_or_b32_e32 v81, 1, v148
	v_cmp_eq_u32_e32 vcc, v177, v81
	v_cndmask_b32_e64 v110, 0, 1.0, s[0:1]
	v_cmp_eq_u32_e64 s[0:1], v178, v148
	s_waitcnt lgkmcnt(0)
	v_mul_f32_e32 v64, 0x3fb8aa3b, v64
	v_exp_f32_e32 v109, v64
	ds_bpermute_b32 v64, v66, v157 offset:16
	v_cndmask_b32_e64 v111, 0, 1.0, vcc
	v_cmp_eq_u32_e32 vcc, v178, v81
	v_lshl_add_u32 v119, v179, 8, v69
	v_readlane_b32 s56, v247, 61
	s_waitcnt lgkmcnt(0)
	v_mul_f32_e32 v64, 0x3fb8aa3b, v64
	v_exp_f32_e32 v82, v64
	ds_bpermute_b32 v64, v66, v157 offset:20
	v_readlane_b32 s58, v247, 63
	v_readlane_b32 s59, v246, 0
	s_movk_i32 s2, 0x1000
	v_readlane_b32 s60, v246, 3
	s_waitcnt lgkmcnt(0)
	v_mul_f32_e32 v64, 0x3fb8aa3b, v64
	v_exp_f32_e32 v83, v64
	ds_bpermute_b32 v64, v66, v157 offset:24
	v_add_u32_e32 v164, s60, v164
	v_readlane_b32 s62, v246, 5
	v_readlane_b32 s57, v247, 62
	v_readlane_b32 s63, v246, 6
	s_waitcnt lgkmcnt(0)
	v_mul_f32_e32 v64, 0x3fb8aa3b, v64
	v_exp_f32_e32 v104, v64
	ds_bpermute_b32 v64, v66, v157 offset:28
	v_readlane_b32 s61, v246, 4
	s_waitcnt lgkmcnt(0)
	v_mul_f32_e32 v64, 0x3fb8aa3b, v64
	v_exp_f32_e32 v105, v64
	ds_read_b128 v[64:67], v118
	ds_read_b128 v[74:77], v118 offset:16
	s_waitcnt lgkmcnt(1)
	v_pk_add_f32 v[64:65], v[110:111], v[64:65]
	v_lshl_add_u32 v111, v178, 8, v69
	ds_read_b128 v[112:115], v111
	ds_read_b128 v[90:93], v111 offset:16
	v_pk_mul_f32 v[72:73], v[106:107], v[64:65]
	v_pk_mul_f32 v[64:65], v[64:65], v[86:87]
	ds_read_b128 v[120:123], v119
	ds_read_b128 v[98:101], v119 offset:16
	v_cvt_pk_bf16_f32 v80, v64, v65
	v_cvt_pk_bf16_f32 v64, v72, v73
	v_cndmask_b32_e64 v72, 0, 1.0, s[0:1]
	v_cndmask_b32_e64 v73, 0, 1.0, vcc
	s_waitcnt lgkmcnt(3)
	v_pk_add_f32 v[72:73], v[72:73], v[112:113]
	v_cmp_eq_u32_e32 vcc, v179, v81
	v_pk_mul_f32 v[88:89], v[106:107], v[72:73]
	v_pk_mul_f32 v[72:73], v[72:73], v[86:87]
	v_cmp_eq_u32_e64 s[0:1], v179, v148
	v_cvt_pk_bf16_f32 v84, v72, v73
	v_cndmask_b32_e64 v73, 0, 1.0, vcc
	v_cndmask_b32_e64 v72, 0, 1.0, s[0:1]
	s_waitcnt lgkmcnt(1)
	v_pk_add_f32 v[72:73], v[72:73], v[120:121]
	v_lshl_add_u32 v120, v180, 8, v69
	v_pk_mul_f32 v[94:95], v[106:107], v[72:73]
	v_pk_mul_f32 v[72:73], v[72:73], v[86:87]
	v_cvt_pk_bf16_f32 v68, v88, v89
	v_cvt_pk_bf16_f32 v88, v72, v73
	v_cvt_pk_bf16_f32 v72, v94, v95
	ds_read_b128 v[124:127], v120
	ds_read_b128 v[94:97], v120 offset:16
	v_cmp_eq_u32_e32 vcc, v180, v81
	v_cmp_eq_u32_e64 s[0:1], v180, v148
	s_nop 0
	v_cndmask_b32_e64 v113, 0, 1.0, vcc
	v_cndmask_b32_e64 v112, 0, 1.0, s[0:1]
	s_waitcnt lgkmcnt(1)
	v_pk_add_f32 v[116:117], v[112:113], v[124:125]
	s_nop 0
	v_pk_mul_f32 v[112:113], v[106:107], v[116:117]
	v_pk_mul_f32 v[106:107], v[116:117], v[86:87]
	v_or_b32_e32 v116, 3, v148
	v_or_b32_e32 v117, 2, v148
	v_cmp_eq_u32_e32 vcc, v177, v117
	v_cmp_eq_u32_e64 s[0:1], v177, v116
	v_pk_mul_f32 v[86:87], v[108:109], v[70:71]
	v_cndmask_b32_e64 v108, 0, 1.0, vcc
	v_cndmask_b32_e64 v109, 0, 1.0, s[0:1]
	v_pk_add_f32 v[66:67], v[108:109], v[66:67]
	v_cmp_eq_u32_e32 vcc, v178, v117
	v_pk_mul_f32 v[108:109], v[86:87], v[66:67]
	v_pk_mul_f32 v[66:67], v[66:67], v[70:71]
	v_cmp_eq_u32_e64 s[0:1], v178, v116
	v_cvt_pk_bf16_f32 v81, v66, v67
	v_cndmask_b32_e64 v66, 0, 1.0, vcc
	v_cndmask_b32_e64 v67, 0, 1.0, s[0:1]
	v_pk_add_f32 v[66:67], v[66:67], v[114:115]
	v_cvt_pk_bf16_f32 v65, v108, v109
	v_pk_mul_f32 v[108:109], v[86:87], v[66:67]
	v_pk_mul_f32 v[66:67], v[66:67], v[70:71]
	v_cmp_eq_u32_e32 vcc, v179, v117
	v_cmp_eq_u32_e64 s[0:1], v179, v116
	v_cvt_pk_bf16_f32 v85, v66, v67
	v_cndmask_b32_e64 v66, 0, 1.0, vcc
	v_cndmask_b32_e64 v67, 0, 1.0, s[0:1]
	v_pk_add_f32 v[66:67], v[66:67], v[122:123]
	v_cvt_pk_bf16_f32 v69, v108, v109
	v_pk_mul_f32 v[108:109], v[86:87], v[66:67]
	v_pk_mul_f32 v[66:67], v[66:67], v[70:71]
	v_cmp_eq_u32_e32 vcc, v180, v117
	v_cmp_eq_u32_e64 s[0:1], v180, v116
	v_cvt_pk_bf16_f32 v89, v66, v67
	v_cndmask_b32_e64 v66, 0, 1.0, vcc
	v_cndmask_b32_e64 v67, 0, 1.0, s[0:1]
	v_pk_add_f32 v[66:67], v[66:67], v[126:127]
	v_cvt_pk_bf16_f32 v73, v108, v109
	v_pk_mul_f32 v[108:109], v[86:87], v[66:67]
	v_pk_mul_f32 v[116:117], v[82:83], v[102:103]
	v_or_b32_e32 v83, 5, v148
	v_or_b32_e32 v87, 4, v148
	v_cmp_eq_u32_e32 vcc, v177, v87
	v_cmp_eq_u32_e64 s[0:1], v177, v83
	v_pk_mul_f32 v[114:115], v[66:67], v[70:71]
	v_cndmask_b32_e64 v66, 0, 1.0, vcc
	v_cndmask_b32_e64 v67, 0, 1.0, s[0:1]
	v_pk_add_f32 v[66:67], v[66:67], v[74:75]
	v_cmp_eq_u32_e32 vcc, v178, v87
	v_pk_mul_f32 v[70:71], v[116:117], v[66:67]
	v_pk_mul_f32 v[66:67], v[66:67], v[102:103]
	v_cmp_eq_u32_e64 s[0:1], v178, v83
	v_cvt_pk_bf16_f32 v82, v66, v67
	v_cvt_pk_bf16_f32 v66, v70, v71
	v_cndmask_b32_e64 v71, 0, 1.0, s[0:1]
	v_cndmask_b32_e64 v70, 0, 1.0, vcc
	v_pk_add_f32 v[70:71], v[70:71], v[90:91]
	v_cmp_eq_u32_e32 vcc, v179, v87
	v_pk_mul_f32 v[74:75], v[116:117], v[70:71]
	v_pk_mul_f32 v[70:71], v[70:71], v[102:103]
	v_cmp_eq_u32_e64 s[0:1], v179, v83
	v_cvt_pk_bf16_f32 v86, v70, v71
	v_cvt_pk_bf16_f32 v70, v74, v75
	v_cndmask_b32_e64 v75, 0, 1.0, s[0:1]
	v_cndmask_b32_e64 v74, 0, 1.0, vcc
	v_pk_add_f32 v[74:75], v[74:75], v[98:99]
	v_cmp_eq_u32_e32 vcc, v180, v87
	v_pk_mul_f32 v[98:99], v[116:117], v[74:75]
	v_pk_mul_f32 v[74:75], v[74:75], v[102:103]
	v_cmp_eq_u32_e64 s[0:1], v180, v83
	v_cvt_pk_bf16_f32 v90, v74, v75
	v_cvt_pk_bf16_f32 v74, v98, v99
	v_cndmask_b32_e64 v99, 0, 1.0, s[0:1]
	v_cndmask_b32_e64 v98, 0, 1.0, vcc
	s_waitcnt lgkmcnt(0)
	v_pk_add_f32 v[98:99], v[98:99], v[94:95]
	s_nop 0
	v_pk_mul_f32 v[94:95], v[116:117], v[98:99]
	v_or_b32_e32 v116, 7, v148
	v_or_b32_e32 v117, 6, v148
	v_cmp_eq_u32_e32 vcc, v177, v117
	v_cmp_eq_u32_e64 s[0:1], v177, v116
	v_pk_mul_f32 v[98:99], v[98:99], v[102:103]
	v_pk_mul_f32 v[102:103], v[104:105], v[78:79]
	v_cndmask_b32_e64 v105, 0, 1.0, s[0:1]
	v_cndmask_b32_e64 v104, 0, 1.0, vcc
	v_pk_add_f32 v[76:77], v[104:105], v[76:77]
	v_cmp_eq_u32_e32 vcc, v178, v117
	v_pk_mul_f32 v[104:105], v[102:103], v[76:77]
	v_pk_mul_f32 v[76:77], v[76:77], v[78:79]
	v_cmp_eq_u32_e64 s[0:1], v178, v116
	v_cvt_pk_bf16_f32 v83, v76, v77
	v_cndmask_b32_e64 v76, 0, 1.0, vcc
	v_cndmask_b32_e64 v77, 0, 1.0, s[0:1]
	v_pk_add_f32 v[76:77], v[76:77], v[92:93]
	v_cmp_eq_u32_e32 vcc, v179, v117
	v_pk_mul_f32 v[92:93], v[102:103], v[76:77]
	v_pk_mul_f32 v[76:77], v[76:77], v[78:79]
	v_cmp_eq_u32_e64 s[0:1], v179, v116
	v_cvt_pk_bf16_f32 v87, v76, v77
	v_cndmask_b32_e64 v76, 0, 1.0, vcc
	v_cndmask_b32_e64 v77, 0, 1.0, s[0:1]
	v_pk_add_f32 v[76:77], v[76:77], v[100:101]
	v_cvt_pk_bf16_f32 v71, v92, v93
	v_pk_mul_f32 v[92:93], v[102:103], v[76:77]
	v_pk_mul_f32 v[76:77], v[76:77], v[78:79]
	v_cmp_eq_u32_e32 vcc, v180, v117
	v_cmp_eq_u32_e64 s[0:1], v180, v116
	v_cvt_pk_bf16_f32 v91, v76, v77
	v_cndmask_b32_e64 v76, 0, 1.0, vcc
	v_cndmask_b32_e64 v77, 0, 1.0, s[0:1]
	v_pk_add_f32 v[76:77], v[76:77], v[96:97]
	v_cvt_pk_bf16_f32 v75, v92, v93
	v_pk_mul_f32 v[92:93], v[102:103], v[76:77]
	v_pk_mul_f32 v[76:77], v[76:77], v[78:79]
	v_add_u32_e32 v117, 32, v148
	v_cvt_pk_bf16_f32 v67, v104, v105
	v_cvt_pk_bf16_f32 v104, v106, v107
	v_cvt_pk_bf16_f32 v107, v76, v77
	v_cvt_pk_bf16_f32 v77, v108, v109
	v_and_or_b32 v108, v117, 56, v169
	v_cvt_pk_bf16_f32 v76, v112, v113
	v_lshlrev_b32_e32 v112, 2, v108
	ds_bpermute_b32 v108, v112, v157
	ds_bpermute_b32 v109, v112, v157 offset:4
	v_cvt_pk_bf16_f32 v106, v98, v99
	v_cvt_pk_bf16_f32 v78, v94, v95
	v_cvt_pk_bf16_f32 v79, v92, v93
	ds_read_b128 v[100:103], v118 offset:128
	ds_read_b128 v[132:135], v118 offset:144
	ds_read_b128 v[96:99], v111 offset:128
	ds_read_b128 v[128:131], v111 offset:144
	ds_read_b128 v[92:95], v119 offset:128
	ds_read_b128 v[124:127], v119 offset:144
	ds_bpermute_b32 v118, v112, v153
	s_waitcnt lgkmcnt(8)
	v_mul_f32_e32 v108, 0x3fb8aa3b, v108
	ds_bpermute_b32 v119, v112, v153 offset:4
	s_waitcnt lgkmcnt(8)
	v_mul_f32_e32 v109, 0x3fb8aa3b, v109
	v_exp_f32_e32 v108, v108
	v_exp_f32_e32 v109, v109
	v_cvt_pk_bf16_f32 v105, v114, v115
	v_add_u32_e32 v113, 33, v148
	v_cmp_eq_u32_e32 vcc, v177, v117
	s_waitcnt lgkmcnt(0)
	v_pk_mul_f32 v[158:159], v[108:109], v[118:119]
	ds_bpermute_b32 v108, v112, v157 offset:8
	v_cmp_eq_u32_e64 s[0:1], v177, v113
	ds_read_b128 v[136:139], v120 offset:128
	ds_read_b128 v[120:123], v120 offset:144
	v_cndmask_b32_e64 v109, 0, 1.0, s[0:1]
	v_cmp_eq_u32_e64 s[0:1], v178, v113
	s_waitcnt lgkmcnt(2)
	v_mul_f32_e32 v108, 0x3fb8aa3b, v108
	v_exp_f32_e32 v160, v108
	ds_bpermute_b32 v108, v112, v157 offset:12
	v_add_f32_e32 v92, v110, v92
	ds_bpermute_b32 v110, v112, v153 offset:8
	ds_bpermute_b32 v111, v112, v153 offset:12
	ds_bpermute_b32 v154, v112, v153 offset:16
	s_waitcnt lgkmcnt(3)
	v_mul_f32_e32 v108, 0x3fb8aa3b, v108
	v_exp_f32_e32 v161, v108
	ds_bpermute_b32 v108, v112, v157 offset:16
	ds_bpermute_b32 v155, v112, v153 offset:20
	ds_bpermute_b32 v152, v112, v153 offset:24
	ds_bpermute_b32 v153, v112, v153 offset:28
	s_waitcnt lgkmcnt(0)
	s_waitcnt lgkmcnt(3)
	v_mul_f32_e32 v108, 0x3fb8aa3b, v108
	v_exp_f32_e32 v114, v108
	ds_bpermute_b32 v108, v112, v157 offset:20
	s_waitcnt lgkmcnt(0)
	v_mul_f32_e32 v108, 0x3fb8aa3b, v108
	v_exp_f32_e32 v115, v108
	ds_bpermute_b32 v108, v112, v157 offset:24
	s_waitcnt lgkmcnt(0)
	v_mul_f32_e32 v108, 0x3fb8aa3b, v108
	v_exp_f32_e32 v156, v108
	ds_bpermute_b32 v108, v112, v157 offset:28
	s_waitcnt lgkmcnt(0)
	v_mul_f32_e32 v108, 0x3fb8aa3b, v108
	v_exp_f32_e32 v157, v108
	v_cndmask_b32_e64 v108, 0, 1.0, vcc
	v_pk_add_f32 v[100:101], v[108:109], v[100:101]
	v_cmp_eq_u32_e32 vcc, v178, v117
	v_pk_mul_f32 v[108:109], v[158:159], v[100:101]
	v_pk_mul_f32 v[100:101], v[100:101], v[118:119]
	s_nop 0
	v_cvt_pk_bf16_f32 v116, v100, v101
	v_cvt_pk_bf16_f32 v100, v108, v109
	v_cndmask_b32_e64 v108, 0, 1.0, vcc
	v_cmp_eq_u32_e32 vcc, v179, v113
	v_cndmask_b32_e64 v109, 0, 1.0, s[0:1]
	v_cmp_eq_u32_e64 s[0:1], v180, v113
	v_cndmask_b32_e64 v101, 0, 1.0, vcc
	v_cmp_eq_u32_e32 vcc, v180, v117
	v_pk_add_f32 v[96:97], v[108:109], v[96:97]
	v_cndmask_b32_e64 v163, 0, 1.0, s[0:1]
	v_cndmask_b32_e64 v162, 0, 1.0, vcc
	v_pk_mul_f32 v[108:109], v[158:159], v[96:97]
	v_pk_mul_f32 v[96:97], v[96:97], v[118:119]
	v_add_f32_e32 v93, v101, v93
	v_pk_add_f32 v[162:163], v[162:163], v[136:137]
	v_cvt_pk_bf16_f32 v112, v96, v97
	v_mul_f32_e32 v97, v92, v118
	v_mul_f32_e32 v92, v158, v92
	v_mul_f32_e32 v101, v93, v119
	v_mul_f32_e32 v93, v159, v93
	v_pk_mul_f32 v[136:137], v[158:159], v[162:163]
	v_pk_mul_f32 v[158:159], v[162:163], v[118:119]
	v_add_u32_e32 v162, 34, v148
	v_cmp_eq_u32_e32 vcc, v177, v162
	v_cmp_eq_u32_e64 s[0:1], v177, v149
	v_pk_mul_f32 v[118:119], v[160:161], v[110:111]
	v_cndmask_b32_e64 v160, 0, 1.0, vcc
	v_cndmask_b32_e64 v161, 0, 1.0, s[0:1]
	v_pk_add_f32 v[102:103], v[160:161], v[102:103]
	v_cmp_eq_u32_e32 vcc, v178, v162
	v_pk_mul_f32 v[160:161], v[118:119], v[102:103]
	v_pk_mul_f32 v[102:103], v[102:103], v[110:111]
	v_cmp_eq_u32_e64 s[0:1], v178, v149
	v_cvt_pk_bf16_f32 v117, v102, v103
	v_cndmask_b32_e64 v102, 0, 1.0, vcc
	v_cndmask_b32_e64 v103, 0, 1.0, s[0:1]
	v_pk_add_f32 v[98:99], v[102:103], v[98:99]
	v_cmp_eq_u32_e32 vcc, v179, v162
	v_pk_mul_f32 v[102:103], v[118:119], v[98:99]
	v_pk_mul_f32 v[98:99], v[98:99], v[110:111]
	v_cmp_eq_u32_e64 s[0:1], v179, v149
	v_cvt_pk_bf16_f32 v113, v98, v99
	v_cndmask_b32_e64 v98, 0, 1.0, vcc
	v_cndmask_b32_e64 v99, 0, 1.0, s[0:1]
	v_pk_add_f32 v[94:95], v[98:99], v[94:95]
	v_cmp_eq_u32_e32 vcc, v180, v162
	v_pk_mul_f32 v[98:99], v[118:119], v[94:95]
	v_pk_mul_f32 v[94:95], v[94:95], v[110:111]
	v_cmp_eq_u32_e64 s[0:1], v180, v149
	v_cvt_pk_bf16_f32 v96, v108, v109
	v_cvt_pk_bf16_f32 v109, v94, v95
	v_cndmask_b32_e64 v95, 0, 1.0, s[0:1]
	v_cndmask_b32_e64 v94, 0, 1.0, vcc
	v_pk_add_f32 v[94:95], v[94:95], v[138:139]
	v_cvt_pk_bf16_f32 v108, v97, v101
	v_cvt_pk_bf16_f32 v101, v160, v161
	v_cvt_pk_bf16_f32 v97, v102, v103
	v_pk_mul_f32 v[160:161], v[94:95], v[110:111]
	v_add_u32_e32 v103, 37, v148
	v_add_u32_e32 v111, 36, v148
	v_cmp_eq_u32_e32 vcc, v177, v111
	v_cmp_eq_u32_e64 s[0:1], v177, v103
	v_pk_mul_f32 v[138:139], v[118:119], v[94:95]
	v_cndmask_b32_e64 v94, 0, 1.0, vcc
	v_cndmask_b32_e64 v95, 0, 1.0, s[0:1]
	v_pk_mul_f32 v[162:163], v[114:115], v[154:155]
	v_pk_add_f32 v[94:95], v[94:95], v[132:133]
	v_cvt_pk_bf16_f32 v92, v92, v93
	v_cvt_pk_bf16_f32 v93, v98, v99
	v_pk_mul_f32 v[98:99], v[162:163], v[94:95]
	v_pk_mul_f32 v[94:95], v[94:95], v[154:155]
	v_cmp_eq_u32_e32 vcc, v178, v111
	v_cmp_eq_u32_e64 s[0:1], v178, v103
	v_cvt_pk_bf16_f32 v118, v94, v95
	v_cndmask_b32_e64 v94, 0, 1.0, vcc
	v_cndmask_b32_e64 v95, 0, 1.0, s[0:1]
	v_pk_add_f32 v[94:95], v[94:95], v[128:129]
	v_cvt_pk_bf16_f32 v102, v98, v99
	v_pk_mul_f32 v[98:99], v[162:163], v[94:95]
	v_pk_mul_f32 v[94:95], v[94:95], v[154:155]
	v_cmp_eq_u32_e32 vcc, v179, v111
	v_cmp_eq_u32_e64 s[0:1], v179, v103
	v_cvt_pk_bf16_f32 v114, v94, v95
	v_cndmask_b32_e64 v94, 0, 1.0, vcc
	v_cndmask_b32_e64 v95, 0, 1.0, s[0:1]
	v_pk_add_f32 v[94:95], v[94:95], v[124:125]
	v_cmp_eq_u32_e32 vcc, v180, v111
	v_pk_mul_f32 v[124:125], v[162:163], v[94:95]
	v_pk_mul_f32 v[94:95], v[94:95], v[154:155]
	v_cmp_eq_u32_e64 s[0:1], v180, v103
	v_cvt_pk_bf16_f32 v110, v94, v95
	v_cvt_pk_bf16_f32 v94, v124, v125
	v_cndmask_b32_e64 v125, 0, 1.0, s[0:1]
	v_cndmask_b32_e64 v124, 0, 1.0, vcc
	v_pk_add_f32 v[120:121], v[124:125], v[120:121]
	v_add_u32_e32 v149, 39, v148
	v_pk_mul_f32 v[128:129], v[162:163], v[120:121]
	v_pk_mul_f32 v[120:121], v[120:121], v[154:155]
	v_add_u32_e32 v154, 38, v148
	v_cmp_eq_u32_e32 vcc, v177, v154
	v_cmp_eq_u32_e64 s[0:1], v177, v149
	v_pk_mul_f32 v[124:125], v[156:157], v[152:153]
	v_cndmask_b32_e64 v132, 0, 1.0, vcc
	v_cndmask_b32_e64 v133, 0, 1.0, s[0:1]
	v_pk_add_f32 v[132:133], v[132:133], v[134:135]
	v_cmp_eq_u32_e32 vcc, v178, v154
	v_pk_mul_f32 v[134:135], v[124:125], v[132:133]
	v_pk_mul_f32 v[132:133], v[132:133], v[152:153]
	v_cmp_eq_u32_e64 s[0:1], v178, v149
	v_cvt_pk_bf16_f32 v119, v132, v133
	v_cndmask_b32_e64 v132, 0, 1.0, vcc
	v_cndmask_b32_e64 v133, 0, 1.0, s[0:1]
	v_pk_add_f32 v[130:131], v[132:133], v[130:131]
	v_cmp_eq_u32_e32 vcc, v179, v154
	v_pk_mul_f32 v[132:133], v[124:125], v[130:131]
	v_pk_mul_f32 v[130:131], v[130:131], v[152:153]
	v_cmp_eq_u32_e64 s[0:1], v179, v149
	v_cvt_pk_bf16_f32 v115, v130, v131
	v_cndmask_b32_e64 v130, 0, 1.0, vcc
	v_cndmask_b32_e64 v131, 0, 1.0, s[0:1]
	v_pk_add_f32 v[126:127], v[130:131], v[126:127]
	v_cmp_eq_u32_e32 vcc, v180, v154
	v_pk_mul_f32 v[130:131], v[124:125], v[126:127]
	v_pk_mul_f32 v[126:127], v[126:127], v[152:153]
	v_cmp_eq_u32_e64 s[0:1], v180, v149
	v_cvt_pk_bf16_f32 v111, v126, v127
	v_cndmask_b32_e64 v126, 0, 1.0, vcc
	v_cndmask_b32_e64 v127, 0, 1.0, s[0:1]
	v_pk_add_f32 v[122:123], v[126:127], v[122:123]
	v_cvt_pk_bf16_f32 v95, v130, v131
	v_pk_mul_f32 v[130:131], v[124:125], v[122:123]
	v_pk_mul_f32 v[122:123], v[122:123], v[152:153]
	v_cvt_pk_bf16_f32 v98, v98, v99
	v_cvt_pk_bf16_f32 v99, v132, v133
	v_cvt_pk_bf16_f32 v127, v122, v123
	v_cvt_pk_bf16_f32 v123, v130, v131
	s_waitcnt vmcnt(15)
	v_mfma_f32_16x16x32_bf16 v[130:133], v[80:83], v[56:59], 0
	v_cvt_pk_bf16_f32 v103, v134, v135
	v_cvt_pk_bf16_f32 v124, v158, v159
	v_cvt_pk_bf16_f32 v125, v160, v161
	s_waitcnt vmcnt(14)
	v_mfma_f32_16x16x32_bf16 v[130:133], v[116:119], v[60:63], v[130:133]
	v_cvt_pk_bf16_f32 v126, v120, v121
	v_cvt_pk_bf16_f32 v122, v128, v129
	v_add3_u32 v128, v166, v144, v148
	s_mov_b32 s0, 0x2fe80000
	v_cvt_pk_bf16_f32 v120, v136, v137
	s_nop 2
	v_cvt_pk_bf16_f32 v134, v130, v131
	v_cvt_pk_bf16_f32 v135, v132, v133
	v_mfma_f32_16x16x32_bf16 v[130:133], v[84:87], v[56:59], 0
	v_cvt_pk_bf16_f32 v121, v138, v139
	v_mfma_f32_16x16x32_bf16 v[130:133], v[112:115], v[60:63], v[130:133]
	s_nop 7
	v_cvt_pk_bf16_f32 v130, v130, v131
	v_cvt_pk_bf16_f32 v131, v132, v133
	ds_write2_b64 v128, v[134:135], v[130:131] offset1:4
	v_mfma_f32_16x16x32_bf16 v[130:133], v[88:91], v[56:59], 0
	v_mfma_f32_16x16x32_bf16 v[56:59], v[104:107], v[56:59], 0
	v_mfma_f32_16x16x32_bf16 v[130:133], v[108:111], v[60:63], v[130:133]
	v_mfma_f32_16x16x32_bf16 v[56:59], v[124:127], v[60:63], v[56:59]
	v_add_u32_e32 v62, 0x800, v128
	s_nop 5
	v_cvt_pk_bf16_f32 v130, v130, v131
	v_cvt_pk_bf16_f32 v131, v132, v133
	v_cvt_pk_bf16_f32 v56, v56, v57
	v_cvt_pk_bf16_f32 v57, v58, v59
	ds_write2_b64 v128, v[130:131], v[56:57] offset0:8 offset1:12
	s_waitcnt vmcnt(13)
	v_mfma_f32_16x16x32_bf16 v[56:59], v[80:83], v[48:51], 0
	s_waitcnt vmcnt(12)
	v_mfma_f32_16x16x32_bf16 v[56:59], v[116:119], v[52:55], v[56:59]
	s_nop 7
	v_cvt_pk_bf16_f32 v60, v56, v57
	v_cvt_pk_bf16_f32 v61, v58, v59
	v_mfma_f32_16x16x32_bf16 v[56:59], v[84:87], v[48:51], 0
	v_mfma_f32_16x16x32_bf16 v[56:59], v[112:115], v[52:55], v[56:59]
	s_nop 7
	v_cvt_pk_bf16_f32 v56, v56, v57
	v_cvt_pk_bf16_f32 v57, v58, v59
	ds_write2_b64 v62, v[60:61], v[56:57] offset1:4
	v_mfma_f32_16x16x32_bf16 v[56:59], v[88:91], v[48:51], 0
	v_mfma_f32_16x16x32_bf16 v[48:51], v[104:107], v[48:51], 0
	v_mfma_f32_16x16x32_bf16 v[56:59], v[108:111], v[52:55], v[56:59]
	v_mfma_f32_16x16x32_bf16 v[48:51], v[124:127], v[52:55], v[48:51]
	v_add_u32_e32 v54, 0x1000, v128
	s_nop 5
	v_cvt_pk_bf16_f32 v56, v56, v57
	v_cvt_pk_bf16_f32 v57, v58, v59
	v_lshl_add_u32 v58, v176, 4, v166
	v_add3_u32 v59, v166, v175, v148
	v_cvt_pk_bf16_f32 v48, v48, v49
	v_cvt_pk_bf16_f32 v49, v50, v51
	ds_write2_b64 v62, v[56:57], v[48:49] offset0:8 offset1:12
	s_waitcnt vmcnt(11)
	v_mfma_f32_16x16x32_bf16 v[48:51], v[80:83], v[40:43], 0
	v_lshlrev_b32_e32 v56, 3, v176
	v_ashrrev_i32_e32 v57, 31, v56
	v_lshl_add_u64 v[56:57], v[56:57], 1, v[142:143]
	s_waitcnt vmcnt(10)
	v_mfma_f32_16x16x32_bf16 v[48:51], v[116:119], v[44:47], v[48:51]
	v_lshl_add_u64 v[56:57], s[58:59], 0, v[56:57]
	s_nop 6
	v_cvt_pk_bf16_f32 v52, v48, v49
	v_cvt_pk_bf16_f32 v53, v50, v51
	v_mfma_f32_16x16x32_bf16 v[48:51], v[84:87], v[40:43], 0
	v_mfma_f32_16x16x32_bf16 v[48:51], v[112:115], v[44:47], v[48:51]
	s_nop 7
	v_cvt_pk_bf16_f32 v48, v48, v49
	v_cvt_pk_bf16_f32 v49, v50, v51
	ds_write2_b64 v54, v[52:53], v[48:49] offset1:4
	v_mfma_f32_16x16x32_bf16 v[48:51], v[88:91], v[40:43], 0
	v_mfma_f32_16x16x32_bf16 v[40:43], v[104:107], v[40:43], 0
	v_mfma_f32_16x16x32_bf16 v[48:51], v[108:111], v[44:47], v[48:51]
	v_mfma_f32_16x16x32_bf16 v[40:43], v[124:127], v[44:47], v[40:43]
	v_add_u32_e32 v46, 0x1800, v128
	s_nop 5
	v_cvt_pk_bf16_f32 v48, v48, v49
	v_cvt_pk_bf16_f32 v49, v50, v51
	v_cvt_pk_bf16_f32 v40, v40, v41
	v_cvt_pk_bf16_f32 v41, v42, v43
	ds_write2_b64 v54, v[48:49], v[40:41] offset0:8 offset1:12
	s_waitcnt vmcnt(9)
	v_mfma_f32_16x16x32_bf16 v[40:43], v[80:83], v[32:35], 0
	s_waitcnt vmcnt(8)
	v_mfma_f32_16x16x32_bf16 v[40:43], v[116:119], v[36:39], v[40:43]
	s_nop 7
	v_cvt_pk_bf16_f32 v44, v40, v41
	v_cvt_pk_bf16_f32 v45, v42, v43
	v_mfma_f32_16x16x32_bf16 v[40:43], v[84:87], v[32:35], 0
	v_mfma_f32_16x16x32_bf16 v[40:43], v[112:115], v[36:39], v[40:43]
	s_nop 7
	v_cvt_pk_bf16_f32 v40, v40, v41
	v_cvt_pk_bf16_f32 v41, v42, v43
	ds_write2_b64 v46, v[44:45], v[40:41] offset1:4
	v_mfma_f32_16x16x32_bf16 v[40:43], v[88:91], v[32:35], 0
	v_mfma_f32_16x16x32_bf16 v[32:35], v[104:107], v[32:35], 0
	v_mfma_f32_16x16x32_bf16 v[40:43], v[108:111], v[36:39], v[40:43]
	v_mfma_f32_16x16x32_bf16 v[32:35], v[124:127], v[36:39], v[32:35]
	v_add_u32_e32 v38, 0x2000, v128
	s_nop 5
	v_cvt_pk_bf16_f32 v40, v40, v41
	v_cvt_pk_bf16_f32 v41, v42, v43
	v_cvt_pk_bf16_f32 v32, v32, v33
	v_cvt_pk_bf16_f32 v33, v34, v35
	ds_write2_b64 v46, v[40:41], v[32:33] offset0:8 offset1:12
	s_waitcnt vmcnt(7)
	v_mfma_f32_16x16x32_bf16 v[32:35], v[80:83], v[24:27], 0
	s_waitcnt vmcnt(6)
	v_mfma_f32_16x16x32_bf16 v[32:35], v[116:119], v[28:31], v[32:35]
	s_nop 7
	v_cvt_pk_bf16_f32 v36, v32, v33
	v_cvt_pk_bf16_f32 v37, v34, v35
	v_mfma_f32_16x16x32_bf16 v[32:35], v[84:87], v[24:27], 0
	v_mfma_f32_16x16x32_bf16 v[32:35], v[112:115], v[28:31], v[32:35]
	s_nop 7
	v_cvt_pk_bf16_f32 v32, v32, v33
	v_cvt_pk_bf16_f32 v33, v34, v35
	ds_write2_b64 v38, v[36:37], v[32:33] offset1:4
	v_mfma_f32_16x16x32_bf16 v[32:35], v[88:91], v[24:27], 0
	v_mfma_f32_16x16x32_bf16 v[24:27], v[104:107], v[24:27], 0
	v_mfma_f32_16x16x32_bf16 v[32:35], v[108:111], v[28:31], v[32:35]
	v_mfma_f32_16x16x32_bf16 v[24:27], v[124:127], v[28:31], v[24:27]
	v_add_u32_e32 v30, 0x2800, v128
	s_nop 5
	v_cvt_pk_bf16_f32 v32, v32, v33
	v_cvt_pk_bf16_f32 v33, v34, v35
	v_cvt_pk_bf16_f32 v24, v24, v25
	v_cvt_pk_bf16_f32 v25, v26, v27
	ds_write2_b64 v38, v[32:33], v[24:25] offset0:8 offset1:12
	s_waitcnt vmcnt(5)
	v_mfma_f32_16x16x32_bf16 v[24:27], v[80:83], v[16:19], 0
	s_waitcnt vmcnt(4)
	v_mfma_f32_16x16x32_bf16 v[24:27], v[116:119], v[20:23], v[24:27]
	s_nop 7
	v_cvt_pk_bf16_f32 v28, v24, v25
	v_cvt_pk_bf16_f32 v29, v26, v27
	v_mfma_f32_16x16x32_bf16 v[24:27], v[84:87], v[16:19], 0
	v_mfma_f32_16x16x32_bf16 v[24:27], v[112:115], v[20:23], v[24:27]
	s_nop 7
	v_cvt_pk_bf16_f32 v24, v24, v25
	v_cvt_pk_bf16_f32 v25, v26, v27
	ds_write2_b64 v30, v[28:29], v[24:25] offset1:4
	v_mfma_f32_16x16x32_bf16 v[24:27], v[88:91], v[16:19], 0
	v_mfma_f32_16x16x32_bf16 v[16:19], v[104:107], v[16:19], 0
	v_mfma_f32_16x16x32_bf16 v[24:27], v[108:111], v[20:23], v[24:27]
	v_mfma_f32_16x16x32_bf16 v[16:19], v[124:127], v[20:23], v[16:19]
	v_add_u32_e32 v22, 0x3000, v128
	s_nop 5
	v_cvt_pk_bf16_f32 v24, v24, v25
	v_cvt_pk_bf16_f32 v25, v26, v27
	v_cvt_pk_bf16_f32 v16, v16, v17
	v_cvt_pk_bf16_f32 v17, v18, v19
	ds_write2_b64 v30, v[24:25], v[16:17] offset0:8 offset1:12
	s_waitcnt vmcnt(3)
	v_mfma_f32_16x16x32_bf16 v[16:19], v[80:83], v[8:11], 0
	s_waitcnt vmcnt(2)
	v_mfma_f32_16x16x32_bf16 v[16:19], v[116:119], v[12:15], v[16:19]
	s_nop 7
	v_cvt_pk_bf16_f32 v20, v16, v17
	v_cvt_pk_bf16_f32 v21, v18, v19
	v_mfma_f32_16x16x32_bf16 v[16:19], v[84:87], v[8:11], 0
	v_mfma_f32_16x16x32_bf16 v[16:19], v[112:115], v[12:15], v[16:19]
	s_nop 7
	v_cvt_pk_bf16_f32 v16, v16, v17
	v_cvt_pk_bf16_f32 v17, v18, v19
	ds_write2_b64 v22, v[20:21], v[16:17] offset1:4
	v_mfma_f32_16x16x32_bf16 v[16:19], v[88:91], v[8:11], 0
	v_mfma_f32_16x16x32_bf16 v[8:11], v[104:107], v[8:11], 0
	v_mfma_f32_16x16x32_bf16 v[16:19], v[108:111], v[12:15], v[16:19]
	v_mfma_f32_16x16x32_bf16 v[8:11], v[124:127], v[12:15], v[8:11]
	v_add_u32_e32 v14, 0x3800, v128
	s_nop 5
	v_cvt_pk_bf16_f32 v16, v16, v17
	v_cvt_pk_bf16_f32 v17, v18, v19
	v_cvt_pk_bf16_f32 v8, v8, v9
	v_cvt_pk_bf16_f32 v9, v10, v11
	ds_write2_b64 v22, v[16:17], v[8:9] offset0:8 offset1:12
	s_waitcnt vmcnt(1)
	v_mfma_f32_16x16x32_bf16 v[8:11], v[80:83], v[0:3], 0
	s_waitcnt vmcnt(0)
	v_mfma_f32_16x16x32_bf16 v[8:11], v[116:119], v[4:7], v[8:11]
	s_nop 7
	v_cvt_pk_bf16_f32 v12, v8, v9
	v_cvt_pk_bf16_f32 v13, v10, v11
	v_mfma_f32_16x16x32_bf16 v[8:11], v[84:87], v[0:3], 0
	v_add_co_u32_e32 v84, vcc, s0, v56
	s_mov_b32 s0, 0x2fe81000
	v_mfma_f32_16x16x32_bf16 v[8:11], v[112:115], v[4:7], v[8:11]
	v_addc_co_u32_e32 v85, vcc, 0, v57, vcc
	v_add_co_u32_e32 v86, vcc, s0, v56
	s_mov_b32 s0, 0x2fe82000
	s_nop 4
	v_cvt_pk_bf16_f32 v8, v8, v9
	v_cvt_pk_bf16_f32 v9, v10, v11
	ds_write2_b64 v14, v[12:13], v[8:9] offset1:4
	v_mfma_f32_16x16x32_bf16 v[8:11], v[88:91], v[0:3], 0
	v_addc_co_u32_e32 v87, vcc, 0, v57, vcc
	v_mfma_f32_16x16x32_bf16 v[0:3], v[104:107], v[0:3], 0
	v_mfma_f32_16x16x32_bf16 v[8:11], v[108:111], v[4:7], v[8:11]
	v_mfma_f32_16x16x32_bf16 v[0:3], v[124:127], v[4:7], v[0:3]
	s_nop 6
	v_cvt_pk_bf16_f32 v8, v8, v9
	v_cvt_pk_bf16_f32 v9, v10, v11
	v_cvt_pk_bf16_f32 v0, v0, v1
	v_cvt_pk_bf16_f32 v1, v2, v3
	ds_write2_b64 v14, v[8:9], v[0:1] offset0:8 offset1:12
	s_waitcnt lgkmcnt(0)
	ds_read_b128 v[0:3], v58
	ds_read_b128 v[4:7], v58 offset:1024
	ds_read_b128 v[8:11], v58 offset:2048
	ds_read_b128 v[12:15], v58 offset:3072
	ds_read_b128 v[16:19], v58 offset:4096
	ds_read_b128 v[20:23], v58 offset:5120
	ds_read_b128 v[24:27], v58 offset:6144
	ds_read_b128 v[28:31], v58 offset:7168
	ds_read_b128 v[32:35], v58 offset:8192
	ds_read_b128 v[36:39], v58 offset:9216
	ds_read_b128 v[40:43], v58 offset:10240
	ds_read_b128 v[44:47], v58 offset:11264
	ds_read_b128 v[48:51], v58 offset:12288
	ds_read_b128 v[52:55], v58 offset:13312
	ds_read_b128 v[60:63], v58 offset:14336
	ds_read_b128 v[80:83], v58 offset:15360
	s_waitcnt lgkmcnt(14)
	global_store_dwordx4 v[86:87], v[0:3], off offset:-4096
	global_store_dwordx4 v[84:85], v[4:7], off offset:1024
	s_waitcnt lgkmcnt(13)
	global_store_dwordx4 v[84:85], v[8:11], off offset:2048
	s_waitcnt lgkmcnt(12)
	global_store_dwordx4 v[84:85], v[12:15], off offset:3072
	s_waitcnt lgkmcnt(11)
	global_store_dwordx4 v[86:87], v[16:19], off
	s_waitcnt lgkmcnt(10)
	global_store_dwordx4 v[86:87], v[20:23], off offset:1024
	s_waitcnt lgkmcnt(9)
	global_store_dwordx4 v[86:87], v[24:27], off offset:2048
	s_waitcnt lgkmcnt(8)
	global_store_dwordx4 v[86:87], v[28:31], off offset:3072
	v_add_co_u32_e32 v0, vcc, s0, v56
	s_mov_b32 s0, 0x2fe83000
	s_nop 0
	v_addc_co_u32_e32 v1, vcc, 0, v57, vcc
	v_add_co_u32_e32 v2, vcc, s0, v56
	s_movk_i32 s0, 0x2000
	s_nop 0
	v_addc_co_u32_e32 v3, vcc, 0, v57, vcc
	s_waitcnt lgkmcnt(7)
	global_store_dwordx4 v[2:3], v[32:35], off offset:-4096
	s_waitcnt lgkmcnt(6)
	global_store_dwordx4 v[0:1], v[36:39], off offset:1024
	s_waitcnt lgkmcnt(5)
	global_store_dwordx4 v[0:1], v[40:43], off offset:2048
	s_waitcnt lgkmcnt(4)
	global_store_dwordx4 v[0:1], v[44:47], off offset:3072
	s_waitcnt lgkmcnt(3)
	global_store_dwordx4 v[2:3], v[48:51], off
	s_waitcnt lgkmcnt(2)
	global_store_dwordx4 v[2:3], v[52:55], off offset:1024
	s_waitcnt lgkmcnt(1)
	global_store_dwordx4 v[2:3], v[60:63], off offset:2048
	s_waitcnt lgkmcnt(0)
	global_store_dwordx4 v[2:3], v[80:83], off offset:3072
	v_lshlrev_b64 v[0:1], 14, v[146:147]
	v_lshl_add_u64 v[0:1], s[86:87], 0, v[0:1]
	v_lshl_add_u64 v[0:1], v[0:1], 0, v[144:145]
	v_lshl_add_u64 v[0:1], v[0:1], 0, v[150:151]
	s_waitcnt lgkmcnt(0)
	global_load_dwordx4 v[60:63], v[0:1], off
	global_load_dwordx4 v[80:83], v[0:1], off offset:64
	global_load_dwordx4 v[48:51], v[0:1], off offset:2048
	global_load_dwordx4 v[52:55], v[0:1], off offset:2112
	v_add_co_u32_e32 v2, vcc, s2, v0
	s_waitcnt vmcnt(3)
	v_mfma_f32_16x16x32_bf16 v[84:87], v[60:63], v[64:67], 0
	v_addc_co_u32_e32 v3, vcc, 0, v1, vcc
	v_add_co_u32_e32 v4, vcc, s0, v0
	s_waitcnt vmcnt(2)
	v_mfma_f32_16x16x32_bf16 v[84:87], v[80:83], v[100:103], v[84:87]
	v_addc_co_u32_e32 v5, vcc, 0, v1, vcc
	global_load_dwordx4 v[40:43], v[4:5], off offset:-4096
	global_load_dwordx4 v[44:47], v[2:3], off offset:64
	global_load_dwordx4 v[32:35], v[2:3], off offset:2048
	global_load_dwordx4 v[36:39], v[2:3], off offset:2112
	global_load_dwordx4 v[24:27], v[4:5], off
	global_load_dwordx4 v[28:31], v[4:5], off offset:64
	global_load_dwordx4 v[16:19], v[4:5], off offset:2048
	global_load_dwordx4 v[20:23], v[4:5], off offset:2112
	v_cvt_pk_bf16_f32 v88, v84, v85
	v_cvt_pk_bf16_f32 v89, v86, v87
	v_mfma_f32_16x16x32_bf16 v[84:87], v[60:63], v[68:71], 0
	s_movk_i32 s0, 0x3000
	v_add_co_u32_e32 v4, vcc, s0, v0
	v_mfma_f32_16x16x32_bf16 v[84:87], v[80:83], v[96:99], v[84:87]
	s_nop 0
	v_addc_co_u32_e32 v5, vcc, 0, v1, vcc
	global_load_dwordx4 v[8:11], v[4:5], off
	global_load_dwordx4 v[12:15], v[4:5], off offset:64
	global_load_dwordx4 v[0:3], v[4:5], off offset:2048
	s_nop 0
	global_load_dwordx4 v[4:7], v[4:5], off offset:2112
	s_nop 0
	v_cvt_pk_bf16_f32 v90, v84, v85
	v_cvt_pk_bf16_f32 v91, v86, v87
	v_mfma_f32_16x16x32_bf16 v[84:87], v[60:63], v[72:75], 0
	s_mov_b32 s0, 0x33e80000
	v_mfma_f32_16x16x32_bf16 v[60:63], v[60:63], v[76:79], 0
	v_mfma_f32_16x16x32_bf16 v[84:87], v[80:83], v[92:95], v[84:87]
	v_mfma_f32_16x16x32_bf16 v[60:63], v[80:83], v[120:123], v[60:63]
	s_nop 6
	v_cvt_pk_bf16_f32 v84, v84, v85
	v_cvt_pk_bf16_f32 v85, v86, v87
	v_cvt_pk_bf16_f32 v86, v60, v61
	v_cvt_pk_bf16_f32 v87, v62, v63
	s_waitcnt vmcnt(13)
	v_mfma_f32_16x16x32_bf16 v[60:63], v[48:51], v[64:67], 0
	s_waitcnt vmcnt(12)
	v_mfma_f32_16x16x32_bf16 v[60:63], v[52:55], v[100:103], v[60:63]
	s_nop 7
	v_cvt_pk_bf16_f32 v60, v60, v61
	v_cvt_pk_bf16_f32 v61, v62, v63
	ds_write2_b64 v59, v[88:89], v[60:61] offset1:4
	v_mfma_f32_16x16x32_bf16 v[60:63], v[48:51], v[68:71], 0
	v_mfma_f32_16x16x32_bf16 v[60:63], v[52:55], v[96:99], v[60:63]
	s_nop 7
	v_cvt_pk_bf16_f32 v80, v60, v61
	v_cvt_pk_bf16_f32 v81, v62, v63
	v_add_u32_e32 v60, 0x1000, v59
	ds_write2_b64 v60, v[90:91], v[80:81] offset1:4
	v_mfma_f32_16x16x32_bf16 v[80:83], v[48:51], v[72:75], 0
	v_add_u32_e32 v61, 0x2000, v59
	v_mfma_f32_16x16x32_bf16 v[48:51], v[48:51], v[76:79], 0
	v_mfma_f32_16x16x32_bf16 v[48:51], v[52:55], v[120:123], v[48:51]
	v_mfma_f32_16x16x32_bf16 v[80:83], v[52:55], v[92:95], v[80:83]
	s_nop 6
	v_cvt_pk_bf16_f32 v52, v48, v49
	v_cvt_pk_bf16_f32 v53, v50, v51
	v_add_u32_e32 v48, 0x3000, v59
	ds_write2_b64 v48, v[86:87], v[52:53] offset1:4
	s_waitcnt vmcnt(11)
	v_mfma_f32_16x16x32_bf16 v[50:53], v[40:43], v[64:67], 0
	v_cvt_pk_bf16_f32 v62, v80, v81
	v_cvt_pk_bf16_f32 v63, v82, v83
	ds_write2_b64 v61, v[84:85], v[62:63] offset1:4
	s_waitcnt vmcnt(10)
	v_mfma_f32_16x16x32_bf16 v[50:53], v[44:47], v[100:103], v[50:53]
	s_nop 7
	v_cvt_pk_bf16_f32 v54, v50, v51
	v_cvt_pk_bf16_f32 v55, v52, v53
	v_mfma_f32_16x16x32_bf16 v[50:53], v[40:43], v[68:71], 0
	v_mfma_f32_16x16x32_bf16 v[50:53], v[44:47], v[96:99], v[50:53]
	s_nop 7
	v_cvt_pk_bf16_f32 v62, v50, v51
	v_cvt_pk_bf16_f32 v63, v52, v53
	v_mfma_f32_16x16x32_bf16 v[50:53], v[40:43], v[72:75], 0
	v_mfma_f32_16x16x32_bf16 v[40:43], v[40:43], v[76:79], 0
	v_mfma_f32_16x16x32_bf16 v[40:43], v[44:47], v[120:123], v[40:43]
	v_mfma_f32_16x16x32_bf16 v[50:53], v[44:47], v[92:95], v[50:53]
	s_nop 6
	v_cvt_pk_bf16_f32 v44, v40, v41
	v_cvt_pk_bf16_f32 v45, v42, v43
	s_waitcnt vmcnt(9)
	v_mfma_f32_16x16x32_bf16 v[40:43], v[32:35], v[64:67], 0
	v_cvt_pk_bf16_f32 v50, v50, v51
	v_cvt_pk_bf16_f32 v51, v52, v53
	s_waitcnt vmcnt(8)
	v_mfma_f32_16x16x32_bf16 v[40:43], v[36:39], v[100:103], v[40:43]
	s_nop 7
	v_cvt_pk_bf16_f32 v40, v40, v41
	v_cvt_pk_bf16_f32 v41, v42, v43
	ds_write2_b64 v59, v[54:55], v[40:41] offset0:8 offset1:12
	v_mfma_f32_16x16x32_bf16 v[40:43], v[32:35], v[68:71], 0
	v_mfma_f32_16x16x32_bf16 v[40:43], v[36:39], v[96:99], v[40:43]
	s_nop 7
	v_cvt_pk_bf16_f32 v40, v40, v41
	v_cvt_pk_bf16_f32 v41, v42, v43
	ds_write2_b64 v60, v[62:63], v[40:41] offset0:8 offset1:12
	v_mfma_f32_16x16x32_bf16 v[40:43], v[32:35], v[72:75], 0
	v_mfma_f32_16x16x32_bf16 v[32:35], v[32:35], v[76:79], 0
	v_mfma_f32_16x16x32_bf16 v[32:35], v[36:39], v[120:123], v[32:35]
	v_mfma_f32_16x16x32_bf16 v[40:43], v[36:39], v[92:95], v[40:43]
	s_nop 6
	v_cvt_pk_bf16_f32 v32, v32, v33
	v_cvt_pk_bf16_f32 v33, v34, v35
	ds_write2_b64 v48, v[44:45], v[32:33] offset0:8 offset1:12
	s_waitcnt vmcnt(7)
	v_mfma_f32_16x16x32_bf16 v[32:35], v[24:27], v[64:67], 0
	v_cvt_pk_bf16_f32 v40, v40, v41
	v_cvt_pk_bf16_f32 v41, v42, v43
	ds_write2_b64 v61, v[50:51], v[40:41] offset0:8 offset1:12
	s_waitcnt vmcnt(6)
	v_mfma_f32_16x16x32_bf16 v[32:35], v[28:31], v[100:103], v[32:35]
	s_nop 7
	v_cvt_pk_bf16_f32 v36, v32, v33
	v_cvt_pk_bf16_f32 v37, v34, v35
	v_mfma_f32_16x16x32_bf16 v[32:35], v[24:27], v[68:71], 0
	v_mfma_f32_16x16x32_bf16 v[32:35], v[28:31], v[96:99], v[32:35]
	s_nop 7
	v_cvt_pk_bf16_f32 v38, v32, v33
	v_cvt_pk_bf16_f32 v39, v34, v35
	v_mfma_f32_16x16x32_bf16 v[32:35], v[24:27], v[72:75], 0
	v_mfma_f32_16x16x32_bf16 v[24:27], v[24:27], v[76:79], 0
	v_mfma_f32_16x16x32_bf16 v[24:27], v[28:31], v[120:123], v[24:27]
	v_mfma_f32_16x16x32_bf16 v[32:35], v[28:31], v[92:95], v[32:35]
	s_nop 6
	v_cvt_pk_bf16_f32 v28, v24, v25
	v_cvt_pk_bf16_f32 v29, v26, v27
	s_waitcnt vmcnt(5)
	v_mfma_f32_16x16x32_bf16 v[24:27], v[16:19], v[64:67], 0
	v_cvt_pk_bf16_f32 v32, v32, v33
	v_cvt_pk_bf16_f32 v33, v34, v35
	s_waitcnt vmcnt(4)
	v_mfma_f32_16x16x32_bf16 v[24:27], v[20:23], v[100:103], v[24:27]
	s_nop 7
	v_cvt_pk_bf16_f32 v24, v24, v25
	v_cvt_pk_bf16_f32 v25, v26, v27
	ds_write2_b64 v59, v[36:37], v[24:25] offset0:16 offset1:20
	v_mfma_f32_16x16x32_bf16 v[24:27], v[16:19], v[68:71], 0
	v_mfma_f32_16x16x32_bf16 v[24:27], v[20:23], v[96:99], v[24:27]
	s_nop 7
	v_cvt_pk_bf16_f32 v24, v24, v25
	v_cvt_pk_bf16_f32 v25, v26, v27
	ds_write2_b64 v60, v[38:39], v[24:25] offset0:16 offset1:20
	v_mfma_f32_16x16x32_bf16 v[24:27], v[16:19], v[72:75], 0
	v_mfma_f32_16x16x32_bf16 v[16:19], v[16:19], v[76:79], 0
	v_mfma_f32_16x16x32_bf16 v[16:19], v[20:23], v[120:123], v[16:19]
	v_mfma_f32_16x16x32_bf16 v[24:27], v[20:23], v[92:95], v[24:27]
	s_nop 6
	v_cvt_pk_bf16_f32 v16, v16, v17
	v_cvt_pk_bf16_f32 v17, v18, v19
	ds_write2_b64 v48, v[28:29], v[16:17] offset0:16 offset1:20
	s_waitcnt vmcnt(3)
	v_mfma_f32_16x16x32_bf16 v[16:19], v[8:11], v[64:67], 0
	v_cvt_pk_bf16_f32 v24, v24, v25
	v_cvt_pk_bf16_f32 v25, v26, v27
	ds_write2_b64 v61, v[32:33], v[24:25] offset0:16 offset1:20
	s_waitcnt vmcnt(2)
	v_mfma_f32_16x16x32_bf16 v[16:19], v[12:15], v[100:103], v[16:19]
	s_nop 7
	v_cvt_pk_bf16_f32 v20, v16, v17
	v_cvt_pk_bf16_f32 v21, v18, v19
	v_mfma_f32_16x16x32_bf16 v[16:19], v[8:11], v[68:71], 0
	v_mfma_f32_16x16x32_bf16 v[16:19], v[12:15], v[96:99], v[16:19]
	s_nop 7
	v_cvt_pk_bf16_f32 v22, v16, v17
	v_cvt_pk_bf16_f32 v23, v18, v19
	v_mfma_f32_16x16x32_bf16 v[16:19], v[8:11], v[72:75], 0
	v_mfma_f32_16x16x32_bf16 v[8:11], v[8:11], v[76:79], 0
	v_mfma_f32_16x16x32_bf16 v[8:11], v[12:15], v[120:123], v[8:11]
	v_mfma_f32_16x16x32_bf16 v[16:19], v[12:15], v[92:95], v[16:19]
	s_nop 6
	v_cvt_pk_bf16_f32 v12, v8, v9
	v_cvt_pk_bf16_f32 v13, v10, v11
	s_waitcnt vmcnt(1)
	v_mfma_f32_16x16x32_bf16 v[8:11], v[0:3], v[64:67], 0
	v_cvt_pk_bf16_f32 v16, v16, v17
	v_cvt_pk_bf16_f32 v17, v18, v19
	s_waitcnt vmcnt(0)
	v_mfma_f32_16x16x32_bf16 v[8:11], v[4:7], v[100:103], v[8:11]
	s_nop 7
	v_cvt_pk_bf16_f32 v8, v8, v9
	v_cvt_pk_bf16_f32 v9, v10, v11
	ds_write2_b64 v59, v[20:21], v[8:9] offset0:24 offset1:28
	v_mfma_f32_16x16x32_bf16 v[8:11], v[0:3], v[68:71], 0
	v_mfma_f32_16x16x32_bf16 v[8:11], v[4:7], v[96:99], v[8:11]
	s_nop 7
	v_cvt_pk_bf16_f32 v8, v8, v9
	v_cvt_pk_bf16_f32 v9, v10, v11
	ds_write2_b64 v60, v[22:23], v[8:9] offset0:24 offset1:28
	v_mfma_f32_16x16x32_bf16 v[8:11], v[0:3], v[72:75], 0
	v_mfma_f32_16x16x32_bf16 v[0:3], v[0:3], v[76:79], 0
	v_mfma_f32_16x16x32_bf16 v[8:11], v[4:7], v[92:95], v[8:11]
	v_mfma_f32_16x16x32_bf16 v[0:3], v[4:7], v[120:123], v[0:3]
	s_nop 6
	v_cvt_pk_bf16_f32 v8, v8, v9
	v_cvt_pk_bf16_f32 v9, v10, v11
	v_cvt_pk_bf16_f32 v0, v0, v1
	v_cvt_pk_bf16_f32 v1, v2, v3
	ds_write2_b64 v61, v[16:17], v[8:9] offset0:24 offset1:28
	ds_write2_b64 v48, v[12:13], v[0:1] offset0:24 offset1:28
	s_waitcnt lgkmcnt(0)
	ds_read_b128 v[0:3], v58
	ds_read_b128 v[4:7], v58 offset:1024
	ds_read_b128 v[8:11], v58 offset:2048
	ds_read_b128 v[12:15], v58 offset:3072
	ds_read_b128 v[16:19], v58 offset:4096
	ds_read_b128 v[20:23], v58 offset:5120
	ds_read_b128 v[24:27], v58 offset:6144
	ds_read_b128 v[28:31], v58 offset:7168
	ds_read_b128 v[32:35], v58 offset:8192
	ds_read_b128 v[36:39], v58 offset:9216
	ds_read_b128 v[40:43], v58 offset:10240
	ds_read_b128 v[44:47], v58 offset:11264
	ds_read_b128 v[48:51], v58 offset:12288
	ds_read_b128 v[52:55], v58 offset:13312
	ds_read_b128 v[60:63], v58 offset:14336
	ds_read_b128 v[64:67], v58 offset:15360
	v_add_co_u32_e32 v58, vcc, s0, v56
	s_mov_b32 s0, 0x33e81000
	s_nop 0
	v_addc_co_u32_e32 v59, vcc, 0, v57, vcc
	v_add_co_u32_e32 v68, vcc, s0, v56
	s_mov_b32 s0, 0x33e82000
	s_nop 0
	v_addc_co_u32_e32 v69, vcc, 0, v57, vcc
	s_waitcnt lgkmcnt(14)
	global_store_dwordx4 v[68:69], v[0:3], off offset:-4096
	global_store_dwordx4 v[58:59], v[4:7], off offset:1024
	s_waitcnt lgkmcnt(13)
	global_store_dwordx4 v[58:59], v[8:11], off offset:2048
	s_waitcnt lgkmcnt(12)
	global_store_dwordx4 v[58:59], v[12:15], off offset:3072
	s_waitcnt lgkmcnt(11)
	global_store_dwordx4 v[68:69], v[16:19], off
	s_waitcnt lgkmcnt(10)
	global_store_dwordx4 v[68:69], v[20:23], off offset:1024
	s_waitcnt lgkmcnt(9)
	global_store_dwordx4 v[68:69], v[24:27], off offset:2048
	s_waitcnt lgkmcnt(8)
	global_store_dwordx4 v[68:69], v[28:31], off offset:3072
	v_add_co_u32_e32 v0, vcc, s0, v56
	v_readlane_b32 s0, v246, 7
	s_nop 0
	v_addc_co_u32_e32 v1, vcc, 0, v57, vcc
	v_readlane_b32 s1, v246, 8
	s_waitcnt lgkmcnt(7)
	global_store_dwordx4 v[0:1], v[32:35], off
	s_waitcnt lgkmcnt(6)
	global_store_dwordx4 v[0:1], v[36:39], off offset:1024
	s_waitcnt lgkmcnt(5)
	global_store_dwordx4 v[0:1], v[40:43], off offset:2048
	s_waitcnt lgkmcnt(4)
	global_store_dwordx4 v[0:1], v[44:47], off offset:3072
	v_add_co_u32_e32 v0, vcc, 0x33e83000, v56
	v_lshl_add_u64 v[140:141], v[140:141], 0, s[0:1]
	v_readlane_b32 s0, v246, 9
	v_addc_co_u32_e32 v1, vcc, 0, v57, vcc
	v_readlane_b32 s1, v246, 10
	s_waitcnt lgkmcnt(3)
	global_store_dwordx4 v[0:1], v[48:51], off
	s_waitcnt lgkmcnt(2)
	global_store_dwordx4 v[0:1], v[52:55], off offset:1024
	s_waitcnt lgkmcnt(1)
	global_store_dwordx4 v[0:1], v[60:63], off offset:2048
	s_waitcnt lgkmcnt(0)
	global_store_dwordx4 v[0:1], v[64:67], off offset:3072
	v_lshl_add_u64 v[142:143], v[142:143], 0, s[0:1]
	s_movk_i32 s0, 0xfff
	s_waitcnt lgkmcnt(0)
	v_cmp_lt_i32_e32 vcc, s0, v164
	v_readlane_b32 s0, v247, 21
	v_readlane_b32 s1, v247, 22
	s_or_b64 s[0:1], vcc, s[0:1]
	s_andn2_b64 exec, exec, s[0:1]
	s_cbranch_execnz .LBB0_955
	s_or_b64 exec, exec, s[0:1]
	v_readlane_b32 s61, v246, 11
